# GEMM operand staging re-laid out: each LDS-DMA piece covers 8 full 128B rows (XOR-swizzled chunks) instead of 16 half rows; k=1 fragment reads via xor-64 base registers; plus trimmed redundant waitcnt
# speedup vs baseline: 1.0088x; 1.0088x over previous
.LBB0_296:
	s_add_u32 s60, s74, 0x13b00000
	s_addc_u32 s61, s75, 0
	s_add_u32 s50, s74, 0xfb00000
	s_addc_u32 s51, s75, 0
	s_andn2_b64 vcc, exec, s[4:5]
	s_cbranch_vccnz .LBB0_381
	v_bfe_i32 v2, v12, 27, 1
	v_lshlrev_b32_e32 v0, 4, v12
	v_lshrrev_b32_e32 v2, 22, v2
	v_add_u32_e32 v2, v0, v2
	v_and_b32_e32 v2, 0xfffffc00, v2
	v_sub_u32_e32 v2, v0, v2
	v_ashrrev_i32_e32 v1, 31, v12
	v_lshrrev_b32_e32 v3, 4, v2
	v_lshrrev_b32_e32 v1, 26, v1
	v_bitop3_b32 v2, v3, v2, 32 bitop3:0x6c
	v_add_u32_e32 v1, v12, v1
	v_ashrrev_i32_e32 v4, 31, v2
	v_ashrrev_i32_e32 v1, 6, v1
	v_lshrrev_b32_e32 v4, 26, v4
	v_lshlrev_b32_e32 v3, 3, v1
	v_add_u32_e32 v4, v2, v4
	v_and_b32_e32 v3, -16, v3
	v_ashrrev_i32_e32 v5, 6, v4
	v_lshlrev_b32_e32 v1, 5, v1
	v_add_u32_e32 v3, v5, v3
	v_and_b32_e32 v13, 32, v1
	v_and_b32_e32 v1, 0xc0, v4
	v_sub_u32_e32 v1, v2, v1
	v_mov_b32_e32 v2, 1
	v_lshlrev_b32_e32 v4, 1, v3
	v_lshrrev_b32_e32 v6, 2, v3
	v_and_b32_e32 v5, 3, v5
	s_mov_b32 s1, 0x7fffffe0
	v_ashrrev_i16_sdwa v1, v2, sext(v1) dst_sel:DWORD dst_unused:UNUSED_PAD src0_sel:DWORD src1_sel:BYTE_0
	v_and_b32_e32 v4, 24, v4
	v_and_b32_e32 v6, 4, v6
	v_and_or_b32 v5, v3, s1, v5
	v_bfe_i32 v14, v1, 0, 16
	v_or3_b32 v4, v5, v6, v4
	v_add_u32_e32 v1, v13, v14
	v_mul_lo_u32 v15, v3, s0
	v_mul_lo_u32 v3, v4, s0
	v_add_u32_e32 v0, 0x2000, v0
	v_lshrrev_b32_e32 v252, 3, v220
	v_bfe_u32 v253, v220, 4, 2
	v_bfe_u32 v254, v220, 6, 1
	v_lshl_or_b32 v253, v254, 2, v253
	v_and_b32_e32 v254, 7, v220
	v_xor_b32_e32 v253, v254, v253
	v_lshlrev_b32_e32 v253, 4, v253
	v_and_b32_e32 v254, 32, v252
	v_bfe_u32 v255, v252, 2, 2
	v_lshl_or_b32 v254, v255, 3, v254
	v_bfe_u32 v255, v252, 4, 1
	v_lshl_or_b32 v254, v255, 2, v254
	v_and_b32_e32 v255, 3, v252
	v_or_b32_e32 v254, v254, v255
	v_mul_u32_u24_e32 v254, 0x1000, v254
	v_add_u32_e32 v254, v254, v253
	v_add_u32_e32 v255, 0x40000, v254
	v_mul_u32_u24_e32 v252, 0x1000, v252
	v_add_u32_e32 v252, v252, v253
	v_add_u32_e32 v253, 0x40000, v252
	v_mov_b32_e32 v128, v252
	v_mov_b32_e32 v130, v254
	v_ashrrev_i32_e32 v1, 31, v0
	v_lshrrev_b32_e32 v1, 22, v1
	v_add_u32_e32 v1, v0, v1
	v_ashrrev_i32_e32 v1, 10, v1
	v_mul_i32_i24_e32 v3, 0x400, v1
	v_sub_u32_e32 v0, v0, v3
	v_lshrrev_b32_e32 v3, 4, v0
	v_bitop3_b32 v0, v3, v0, 32 bitop3:0x6c
	v_ashrrev_i32_e32 v4, 31, v0
	v_lshrrev_b32_e32 v4, 26, v4
	v_lshlrev_b32_e32 v3, 3, v1
	v_add_u32_e32 v4, v0, v4
	v_and_b32_e32 v3, -16, v3
	v_ashrrev_i32_e32 v5, 6, v4
	v_lshlrev_b32_e32 v1, 5, v1
	s_add_u32 s30, s74, 0x700000
	v_add_u32_e32 v3, v5, v3
	v_and_b32_e32 v16, 32, v1
	v_and_b32_e32 v1, 0xc0, v4
	v_and_b32_e32 v4, 3, v5
	s_addc_u32 s31, s75, 0
	v_and_or_b32 v4, v3, s1, v4
	s_ashr_i32 s1, s0, 31
	s_lshl_b64 s[12:13], s[0:1], 9
	s_ashr_i32 s7, s29, 31
	s_mul_i32 s7, s12, s7
	s_mul_hi_u32 s8, s12, s29
	s_ashr_i32 s14, s28, 31
	s_add_i32 s7, s8, s7
	s_lshr_b64 s[8:9], s[0:1], 23
	s_mul_i32 s14, s12, s14
	s_mul_hi_u32 s15, s12, s28
	s_ashr_i32 s4, s6, 6
	s_mul_i32 s9, s8, s29
	s_add_i32 s14, s15, s14
	s_mul_i32 s8, s8, s28
	v_sub_u32_e32 v0, v0, v1
	s_ashr_i32 s5, s6, 8
	s_lshl_b64 s[10:11], s[0:1], 8
	s_lshl_b32 s34, s4, 10
	s_add_i32 s7, s7, s9
	s_add_i32 s14, s14, s8
	s_mul_i32 s8, s12, s28
	v_ashrrev_i16_sdwa v0, v2, sext(v0) dst_sel:DWORD dst_unused:UNUSED_PAD src0_sel:DWORD src1_sel:BYTE_0
	v_lshlrev_b32_e32 v1, 1, v3
	v_lshrrev_b32_e32 v2, 2, v3
	s_add_u32 s22, s30, s8
	v_and_b32_e32 v1, 24, v1
	v_and_b32_e32 v2, 4, v2
	s_addc_u32 s23, s31, s14
	s_add_i32 s35, s34, 0
	v_bfe_i32 v17, v0, 0, 16
	v_or3_b32 v1, v4, v2, v1
	s_add_i32 m0, s35, 0x10000
	v_add_u32_e32 v0, v16, v17
	v_mul_lo_u32 v1, v1, s0
	global_load_lds_dwordx4 v130, s[22:23]
	s_add_i32 m0, s35, 0x12000
	v_mov_b32_e32 v134, v255
	s_add_u32 s14, s22, s10
	global_load_lds_dwordx4 v134, s[22:23]
	s_addc_u32 s15, s23, s11
	s_add_i32 m0, s35, 0x14000
	s_mul_i32 s9, s12, s29
	global_load_lds_dwordx4 v130, s[14:15]
	s_add_i32 m0, s35, 0x16000
	s_add_u32 s8, s50, s9
	s_addc_u32 s9, s51, s7
	s_add_i32 s36, s35, 0x2000
	v_mul_lo_u32 v18, v3, s0
	global_load_lds_dwordx4 v134, s[14:15]
	s_mov_b32 m0, s35
	s_add_u32 s16, s8, s10
	v_mov_b32_e32 v132, v253
	global_load_lds_dwordx4 v128, s[8:9]
	s_mov_b32 m0, s36
	s_addc_u32 s17, s9, s11
	s_add_i32 s37, s35, 0x4000
	global_load_lds_dwordx4 v132, s[8:9]
	s_mov_b32 m0, s37
	s_add_i32 s38, s35, 0x6000
	global_load_lds_dwordx4 v128, s[16:17]
	s_mov_b32 m0, s38
	v_mov_b32_e32 v137, 0
	global_load_lds_dwordx4 v132, s[16:17]
	v_mov_b32_e32 v131, v137
	v_mov_b32_e32 v135, v137
	v_mov_b32_e32 v129, v137
	v_mov_b32_e32 v133, v137
	s_cmp_eq_u32 s5, 1
	s_mov_b32 s39, 0
	v_lshl_add_u64 v[8:9], s[22:23], 0, v[130:131]
	v_lshl_add_u64 v[4:5], s[22:23], 0, v[134:135]
	v_lshl_add_u64 v[2:3], s[14:15], 0, v[130:131]
	v_lshl_add_u64 v[0:1], s[14:15], 0, v[134:135]
	v_lshl_add_u64 v[6:7], s[8:9], 0, v[128:129]
	s_cselect_b64 s[14:15], -1, 0
	s_cmp_lg_u32 s5, 1
	v_lshl_add_u64 v[10:11], s[8:9], 0, v[132:133]
	s_cbranch_scc1 .LBB0_299
	s_barrier
.LBB0_299:
	s_mov_b64 s[16:17], 0x80
	s_add_i32 m0, s35, 0x18000
	v_lshl_add_u64 v[8:9], v[8:9], 0, s[16:17]
	s_waitcnt vmcnt(2)
	s_barrier
	global_load_lds_dwordx4 v[8:9], off
	v_lshl_add_u64 v[4:5], v[4:5], 0, s[16:17]
	s_add_i32 m0, s35, 0x1a000
	s_add_i32 s40, s35, 0x8000
	global_load_lds_dwordx4 v[4:5], off
	v_lshl_add_u64 v[4:5], v[6:7], 0, s[16:17]
	s_mov_b32 m0, s40
	s_add_i32 s41, s35, 0xa000
	global_load_lds_dwordx4 v[4:5], off
	v_lshl_add_u64 v[4:5], v[10:11], 0, s[16:17]
	s_mov_b32 m0, s41
	v_lshl_add_u64 v[2:3], v[2:3], 0, s[16:17]
	global_load_lds_dwordx4 v[4:5], off
	s_add_i32 m0, s35, 0x1c000
	v_lshl_add_u64 v[0:1], v[0:1], 0, s[16:17]
	global_load_lds_dwordx4 v[2:3], off
	s_add_i32 m0, s35, 0x1e000
	s_lshr_b32 s1, s1, 26
	global_load_lds_dwordx4 v[0:1], off
	v_lshrrev_b32_e32 v0, 1, v12
	v_and_b32_e32 v138, 24, v0
	v_and_b32_e32 v155, 15, v12
	s_add_i32 s1, s0, s1
	v_lshlrev_b32_e32 v0, 1, v138
	v_lshlrev_b32_e32 v1, 2, v12
	s_ashr_i32 s42, s1, 6
	v_lshl_or_b32 v0, v155, 6, v0
	s_lshl_b32 s1, s5, 13
	v_and_b32_e32 v1, 32, v1
	v_bitop3_b32 v2, v0, s1, v1 bitop3:0xde
	s_lshl_b32 s1, s4, 5
	s_and_b32 s44, s1, 0x60
	s_lshl_b32 s43, s5, 6
	s_lshl_b32 s1, s44, 7
	s_cmp_gt_i32 s0, 63
	v_and_b32_e32 v252, 15, v220
	v_bfe_u32 v253, v220, 4, 2
	v_bfe_u32 v254, v252, 1, 2
	v_xor_b32_e32 v253, v253, v254
	v_bfe_u32 v254, v252, 3, 1
	v_lshl_or_b32 v253, v254, 2, v253
	v_lshlrev_b32_e32 v253, 4, v253
	v_lshl_or_b32 v253, v252, 7, v253
	v_lshrrev_b32_e32 v254, 6, v220
	v_lshrrev_b32_e32 v255, 2, v254
	v_lshl_or_b32 v252, v255, 13, v253
	v_and_b32_e32 v254, 3, v254
	v_lshl_or_b32 v253, v254, 12, v253
	v_mov_b32_e32 v156, v253
	s_cselect_b64 s[0:1], -1, 0
	s_add_i32 s45, s42, -2
	v_add_u32_e32 v0, v15, v13
	s_waitcnt vmcnt(6)
	s_cmpk_lt_u32 s6, 0x100
	v_readlane_b32 s4, v251, 1
	v_mov_b32_e32 v136, v128
	v_add_u32_e32 v0, v18, v16
	s_cselect_b64 s[18:19], -1, 0
	v_readlane_b32 s5, v251, 2
	v_lshl_add_u64 v[140:141], s[10:11], 0, v[136:137]
	v_mov_b32_e32 v136, v132
	v_cndmask_b32_e64 v0, 0, 1, s[0:1]
	s_add_i32 s77, 0, 0x10000
	s_add_i32 s78, 0, 0x14000
	v_or_b32_e32 v157, 16, v155
	v_or_b32_e32 v158, 32, v155
	v_or_b32_e32 v159, 48, v155
	s_ashr_i32 s47, s4, 31
	s_mov_b32 s62, s4
	s_ashr_i32 s63, s2, 31
	v_mov_b32_e32 v139, v137
	v_lshl_add_u64 v[142:143], s[10:11], 0, v[136:137]
	v_mov_b64_e32 v[144:145], 0x600
	v_mov_b64_e32 v[146:147], 0x5ff
	s_movk_i32 s76, 0xc1
	v_add_u32_e32 v160, s77, v156
	v_add_u32_e32 v161, s78, v156
	v_mov_b32_e32 v162, v252
	v_xor_b32_e32 v252, 64, v162
	v_xor_b32_e32 v253, 64, v160
	v_xor_b32_e32 v254, 64, v161
	v_cmp_ne_u32_e64 s[4:5], 1, v0
	s_barrier
	s_branch .LBB0_302

.LBB0_310:
	ds_read_b128 v[148:151], v160
	ds_read_b128 v[164:167], v253
	ds_read_b128 v[168:171], v160 offset:2048
	ds_read_b128 v[172:175], v253 offset:2048
	ds_read_b128 v[176:179], v161
	ds_read_b128 v[180:183], v254
	ds_read_b128 v[184:187], v161 offset:2048
	ds_read_b128 v[188:191], v254 offset:2048
	s_add_i32 s26, s22, 2
	s_add_u32 s27, s8, 0x80
	s_addc_u32 s23, s9, 0
	s_cmp_eq_u32 s45, s22
	s_cselect_b32 s22, s0, s27
	s_cselect_b32 s23, s1, s23
	s_cselect_b32 s85, s21, s25
	s_cselect_b32 s84, s20, s24
	v_lshl_add_u64 v[152:153], s[8:9], 0, v[140:141]
	s_add_i32 m0, s35, 0xc000
	ds_read_b128 v[192:195], v162
	ds_read_b128 v[196:199], v252
	ds_read_b128 v[200:203], v162 offset:2048
	ds_read_b128 v[204:207], v252 offset:2048
	ds_read_b128 v[208:211], v162 offset:4096
	ds_read_b128 v[212:215], v252 offset:4096
	ds_read_b128 v[216:219], v162 offset:6144
	ds_read_b128 v[222:225], v252 offset:6144
	global_load_lds_dwordx4 v[152:153], off
	v_lshl_add_u64 v[152:153], s[8:9], 0, v[142:143]
	s_add_i32 m0, s35, 0xe000
	s_nop 0
	global_load_lds_dwordx4 v[152:153], off
	s_waitcnt vmcnt(8)
	s_waitcnt lgkmcnt(0)
	s_setprio 1
	s_barrier
	v_mfma_f32_16x16x32_bf16 v[124:127], v[148:151], v[192:195], v[124:127]
	v_mfma_f32_16x16x32_bf16 v[120:123], v[168:171], v[192:195], v[120:123]
	v_mfma_f32_16x16x32_bf16 v[108:111], v[148:151], v[200:203], v[108:111]
	v_mfma_f32_16x16x32_bf16 v[104:107], v[168:171], v[200:203], v[104:107]
	v_mfma_f32_16x16x32_bf16 v[92:95], v[148:151], v[208:211], v[92:95]
	v_mfma_f32_16x16x32_bf16 v[88:91], v[168:171], v[208:211], v[88:91]
	v_mfma_f32_16x16x32_bf16 v[76:79], v[148:151], v[216:219], v[76:79]
	v_mfma_f32_16x16x32_bf16 v[72:75], v[168:171], v[216:219], v[72:75]
	v_mfma_f32_16x16x32_bf16 v[124:127], v[164:167], v[196:199], v[124:127]
	v_mfma_f32_16x16x32_bf16 v[120:123], v[172:175], v[196:199], v[120:123]
	v_mfma_f32_16x16x32_bf16 v[108:111], v[164:167], v[204:207], v[108:111]
	v_mfma_f32_16x16x32_bf16 v[104:107], v[172:175], v[204:207], v[104:107]
	v_mfma_f32_16x16x32_bf16 v[92:95], v[164:167], v[212:215], v[92:95]
	v_mfma_f32_16x16x32_bf16 v[88:91], v[172:175], v[212:215], v[88:91]
	v_mfma_f32_16x16x32_bf16 v[76:79], v[164:167], v[222:225], v[76:79]
	v_mfma_f32_16x16x32_bf16 v[72:75], v[172:175], v[222:225], v[72:75]
	v_mfma_f32_16x16x32_bf16 v[116:119], v[176:179], v[192:195], v[116:119]
	v_mfma_f32_16x16x32_bf16 v[112:115], v[184:187], v[192:195], v[112:115]
	v_mfma_f32_16x16x32_bf16 v[100:103], v[176:179], v[200:203], v[100:103]
	v_mfma_f32_16x16x32_bf16 v[96:99], v[184:187], v[200:203], v[96:99]
	v_mfma_f32_16x16x32_bf16 v[84:87], v[176:179], v[208:211], v[84:87]
	v_mfma_f32_16x16x32_bf16 v[80:83], v[184:187], v[208:211], v[80:83]
	v_mfma_f32_16x16x32_bf16 v[68:71], v[176:179], v[216:219], v[68:71]
	v_mfma_f32_16x16x32_bf16 v[64:67], v[184:187], v[216:219], v[64:67]
	v_mfma_f32_16x16x32_bf16 v[116:119], v[180:183], v[196:199], v[116:119]
	v_mfma_f32_16x16x32_bf16 v[112:115], v[188:191], v[196:199], v[112:115]
	v_mfma_f32_16x16x32_bf16 v[100:103], v[180:183], v[204:207], v[100:103]
	v_mfma_f32_16x16x32_bf16 v[96:99], v[188:191], v[204:207], v[96:99]
	v_mfma_f32_16x16x32_bf16 v[84:87], v[180:183], v[212:215], v[84:87]
	v_mfma_f32_16x16x32_bf16 v[80:83], v[188:191], v[212:215], v[80:83]
	v_mfma_f32_16x16x32_bf16 v[68:71], v[180:183], v[222:225], v[68:71]
	v_mfma_f32_16x16x32_bf16 v[64:67], v[188:191], v[222:225], v[64:67]
	s_barrier
	s_setprio 0
	s_add_i32 s27, s77, s34
	v_lshl_add_u64 v[152:153], s[84:85], 0, v[130:131]
	s_mov_b32 m0, s27
	ds_read_b128 v[192:195], v162 offset:16384
	ds_read_b128 v[196:199], v252 offset:16384
	ds_read_b128 v[200:203], v162 offset:18432
	ds_read_b128 v[204:207], v252 offset:18432
	ds_read_b128 v[208:211], v162 offset:20480
	ds_read_b128 v[212:215], v252 offset:20480
	ds_read_b128 v[216:219], v162 offset:22528
	ds_read_b128 v[222:225], v252 offset:22528
	global_load_lds_dwordx4 v[152:153], off
	s_add_i32 m0, s27, 0x2000
	v_lshl_add_u64 v[226:227], s[84:85], 0, v[134:135]
	s_add_u32 s84, s84, s10
	s_addc_u32 s85, s85, s11
	s_add_i32 s27, s78, s34
	global_load_lds_dwordx4 v[226:227], off
	v_lshl_add_u64 v[228:229], s[84:85], 0, v[130:131]
	s_mov_b32 m0, s27
	v_lshl_add_u64 v[230:231], s[84:85], 0, v[134:135]
	global_load_lds_dwordx4 v[228:229], off
	s_add_i32 m0, s27, 0x2000
	v_lshl_add_u64 v[232:233], s[22:23], 0, v[128:129]
	global_load_lds_dwordx4 v[230:231], off
	s_mov_b32 m0, s35
	v_lshl_add_u64 v[234:235], s[22:23], 0, v[132:133]
	global_load_lds_dwordx4 v[232:233], off
	s_mov_b32 m0, s36
	s_nop 0
	global_load_lds_dwordx4 v[234:235], off
	s_waitcnt vmcnt(8)
	s_waitcnt lgkmcnt(0)
	s_setprio 1
	s_barrier
	v_mfma_f32_16x16x32_bf16 v[60:63], v[148:151], v[192:195], v[60:63]
	v_mfma_f32_16x16x32_bf16 v[56:59], v[168:171], v[192:195], v[56:59]
	v_mfma_f32_16x16x32_bf16 v[44:47], v[148:151], v[200:203], v[44:47]
	v_mfma_f32_16x16x32_bf16 v[40:43], v[168:171], v[200:203], v[40:43]
	v_mfma_f32_16x16x32_bf16 v[28:31], v[148:151], v[208:211], v[28:31]
	v_mfma_f32_16x16x32_bf16 v[24:27], v[168:171], v[208:211], v[24:27]
	v_mfma_f32_16x16x32_bf16 v[12:15], v[148:151], v[216:219], v[12:15]
	v_mfma_f32_16x16x32_bf16 v[8:11], v[168:171], v[216:219], v[8:11]
	v_mfma_f32_16x16x32_bf16 v[60:63], v[164:167], v[196:199], v[60:63]
	v_mfma_f32_16x16x32_bf16 v[56:59], v[172:175], v[196:199], v[56:59]
	v_mfma_f32_16x16x32_bf16 v[44:47], v[164:167], v[204:207], v[44:47]
	v_mfma_f32_16x16x32_bf16 v[40:43], v[172:175], v[204:207], v[40:43]
	v_mfma_f32_16x16x32_bf16 v[28:31], v[164:167], v[212:215], v[28:31]
	v_mfma_f32_16x16x32_bf16 v[24:27], v[172:175], v[212:215], v[24:27]
	v_mfma_f32_16x16x32_bf16 v[12:15], v[164:167], v[222:225], v[12:15]
	v_mfma_f32_16x16x32_bf16 v[8:11], v[172:175], v[222:225], v[8:11]
	v_mfma_f32_16x16x32_bf16 v[52:55], v[176:179], v[192:195], v[52:55]
	v_mfma_f32_16x16x32_bf16 v[48:51], v[184:187], v[192:195], v[48:51]
	v_mfma_f32_16x16x32_bf16 v[36:39], v[176:179], v[200:203], v[36:39]
	v_mfma_f32_16x16x32_bf16 v[32:35], v[184:187], v[200:203], v[32:35]
	v_mfma_f32_16x16x32_bf16 v[20:23], v[176:179], v[208:211], v[20:23]
	v_mfma_f32_16x16x32_bf16 v[16:19], v[184:187], v[208:211], v[16:19]
	v_mfma_f32_16x16x32_bf16 v[4:7], v[176:179], v[216:219], v[4:7]
	v_mfma_f32_16x16x32_bf16 v[0:3], v[184:187], v[216:219], v[0:3]
	v_mfma_f32_16x16x32_bf16 v[52:55], v[180:183], v[196:199], v[52:55]
	v_mfma_f32_16x16x32_bf16 v[48:51], v[188:191], v[196:199], v[48:51]
	v_mfma_f32_16x16x32_bf16 v[36:39], v[180:183], v[204:207], v[36:39]
	v_mfma_f32_16x16x32_bf16 v[32:35], v[188:191], v[204:207], v[32:35]
	v_mfma_f32_16x16x32_bf16 v[20:23], v[180:183], v[212:215], v[20:23]
	v_mfma_f32_16x16x32_bf16 v[16:19], v[188:191], v[212:215], v[16:19]
	v_mfma_f32_16x16x32_bf16 v[4:7], v[180:183], v[222:225], v[4:7]
	v_mfma_f32_16x16x32_bf16 v[0:3], v[188:191], v[222:225], v[0:3]
	s_barrier
	s_setprio 0
	s_add_i32 s27, 0, 0x18000
	v_add_u32_e32 v136, s27, v156
	s_add_i32 s81, 0, 0x1c000
	v_xor_b32_e32 v255, 64, v136
	ds_read_b128 v[148:151], v136
	ds_read_b128 v[164:167], v255
	ds_read_b128 v[168:171], v136 offset:2048
	ds_read_b128 v[172:175], v255 offset:2048
	v_add_u32_e32 v136, s81, v156
	v_xor_b32_e32 v255, 64, v136
	ds_read_b128 v[176:179], v136
	ds_read_b128 v[180:183], v255
	ds_read_b128 v[184:187], v136 offset:2048
	ds_read_b128 v[188:191], v255 offset:2048
	s_add_u32 s22, s22, s10
	s_addc_u32 s23, s23, s11
	s_mov_b32 m0, s37
	v_lshl_add_u64 v[236:237], s[22:23], 0, v[128:129]
	ds_read_b128 v[192:195], v162 offset:32768
	ds_read_b128 v[196:199], v252 offset:32768
	ds_read_b128 v[200:203], v162 offset:34816
	ds_read_b128 v[204:207], v252 offset:34816
	ds_read_b128 v[208:211], v162 offset:36864
	ds_read_b128 v[212:215], v252 offset:36864
	ds_read_b128 v[216:219], v162 offset:38912
	ds_read_b128 v[222:225], v252 offset:38912
	global_load_lds_dwordx4 v[236:237], off
	v_lshl_add_u64 v[236:237], s[22:23], 0, v[132:133]
	s_mov_b32 m0, s38
	s_nop 0
	global_load_lds_dwordx4 v[236:237], off
	s_waitcnt vmcnt(8)
	s_waitcnt lgkmcnt(0)
	s_setprio 1
	s_barrier
	v_mfma_f32_16x16x32_bf16 v[124:127], v[148:151], v[192:195], v[124:127]
	v_mfma_f32_16x16x32_bf16 v[120:123], v[168:171], v[192:195], v[120:123]
	v_mfma_f32_16x16x32_bf16 v[108:111], v[148:151], v[200:203], v[108:111]
	v_mfma_f32_16x16x32_bf16 v[104:107], v[168:171], v[200:203], v[104:107]
	v_mfma_f32_16x16x32_bf16 v[92:95], v[148:151], v[208:211], v[92:95]
	v_mfma_f32_16x16x32_bf16 v[88:91], v[168:171], v[208:211], v[88:91]
	v_mfma_f32_16x16x32_bf16 v[76:79], v[148:151], v[216:219], v[76:79]
	v_mfma_f32_16x16x32_bf16 v[72:75], v[168:171], v[216:219], v[72:75]
	v_mfma_f32_16x16x32_bf16 v[124:127], v[164:167], v[196:199], v[124:127]
	v_mfma_f32_16x16x32_bf16 v[120:123], v[172:175], v[196:199], v[120:123]
	v_mfma_f32_16x16x32_bf16 v[108:111], v[164:167], v[204:207], v[108:111]
	v_mfma_f32_16x16x32_bf16 v[104:107], v[172:175], v[204:207], v[104:107]
	v_mfma_f32_16x16x32_bf16 v[92:95], v[164:167], v[212:215], v[92:95]
	v_mfma_f32_16x16x32_bf16 v[88:91], v[172:175], v[212:215], v[88:91]
	v_mfma_f32_16x16x32_bf16 v[76:79], v[164:167], v[222:225], v[76:79]
	v_mfma_f32_16x16x32_bf16 v[72:75], v[172:175], v[222:225], v[72:75]
	v_mfma_f32_16x16x32_bf16 v[116:119], v[176:179], v[192:195], v[116:119]
	v_mfma_f32_16x16x32_bf16 v[112:115], v[184:187], v[192:195], v[112:115]
	v_mfma_f32_16x16x32_bf16 v[100:103], v[176:179], v[200:203], v[100:103]
	v_mfma_f32_16x16x32_bf16 v[96:99], v[184:187], v[200:203], v[96:99]
	v_mfma_f32_16x16x32_bf16 v[84:87], v[176:179], v[208:211], v[84:87]
	v_mfma_f32_16x16x32_bf16 v[80:83], v[184:187], v[208:211], v[80:83]
	v_mfma_f32_16x16x32_bf16 v[68:71], v[176:179], v[216:219], v[68:71]
	v_mfma_f32_16x16x32_bf16 v[64:67], v[184:187], v[216:219], v[64:67]
	v_mfma_f32_16x16x32_bf16 v[116:119], v[180:183], v[196:199], v[116:119]
	v_mfma_f32_16x16x32_bf16 v[112:115], v[188:191], v[196:199], v[112:115]
	v_mfma_f32_16x16x32_bf16 v[100:103], v[180:183], v[204:207], v[100:103]
	v_mfma_f32_16x16x32_bf16 v[96:99], v[188:191], v[204:207], v[96:99]
	v_mfma_f32_16x16x32_bf16 v[84:87], v[180:183], v[212:215], v[84:87]
	v_mfma_f32_16x16x32_bf16 v[80:83], v[188:191], v[212:215], v[80:83]
	v_mfma_f32_16x16x32_bf16 v[68:71], v[180:183], v[222:225], v[68:71]
	v_mfma_f32_16x16x32_bf16 v[64:67], v[188:191], v[222:225], v[64:67]
	s_barrier
	s_setprio 0
	s_add_i32 s22, s27, s34
	v_lshl_add_u64 v[152:153], v[152:153], 0, s[16:17]
	s_mov_b32 m0, s22
	ds_read_b128 v[192:195], v162 offset:49152
	ds_read_b128 v[196:199], v252 offset:49152
	ds_read_b128 v[200:203], v162 offset:51200
	ds_read_b128 v[204:207], v252 offset:51200
	ds_read_b128 v[208:211], v162 offset:53248
	ds_read_b128 v[212:215], v252 offset:53248
	ds_read_b128 v[216:219], v162 offset:55296
	ds_read_b128 v[222:225], v252 offset:55296
	global_load_lds_dwordx4 v[152:153], off
	v_lshl_add_u64 v[152:153], v[226:227], 0, s[16:17]
	s_add_i32 m0, s22, 0x2000
	s_add_i32 s22, s81, s34
	global_load_lds_dwordx4 v[152:153], off
	v_lshl_add_u64 v[152:153], v[228:229], 0, s[16:17]
	s_mov_b32 m0, s22
	s_nop 0
	global_load_lds_dwordx4 v[152:153], off
	v_lshl_add_u64 v[152:153], v[230:231], 0, s[16:17]
	s_add_i32 m0, s22, 0x2000
	s_nop 0
	global_load_lds_dwordx4 v[152:153], off
	v_lshl_add_u64 v[152:153], v[232:233], 0, s[16:17]
	s_mov_b32 m0, s40
	s_nop 0
	global_load_lds_dwordx4 v[152:153], off
	v_lshl_add_u64 v[152:153], v[234:235], 0, s[16:17]
	s_mov_b32 m0, s41
	s_nop 0
	global_load_lds_dwordx4 v[152:153], off
	s_waitcnt vmcnt(8)
	s_waitcnt lgkmcnt(0)
	s_setprio 1
	s_barrier
	v_mfma_f32_16x16x32_bf16 v[60:63], v[148:151], v[192:195], v[60:63]
	v_mfma_f32_16x16x32_bf16 v[56:59], v[168:171], v[192:195], v[56:59]
	v_mfma_f32_16x16x32_bf16 v[44:47], v[148:151], v[200:203], v[44:47]
	v_mfma_f32_16x16x32_bf16 v[40:43], v[168:171], v[200:203], v[40:43]
	v_mfma_f32_16x16x32_bf16 v[28:31], v[148:151], v[208:211], v[28:31]
	v_mfma_f32_16x16x32_bf16 v[24:27], v[168:171], v[208:211], v[24:27]
	v_mfma_f32_16x16x32_bf16 v[12:15], v[148:151], v[216:219], v[12:15]
	v_mfma_f32_16x16x32_bf16 v[8:11], v[168:171], v[216:219], v[8:11]
	v_mfma_f32_16x16x32_bf16 v[60:63], v[164:167], v[196:199], v[60:63]
	v_mfma_f32_16x16x32_bf16 v[56:59], v[172:175], v[196:199], v[56:59]
	v_mfma_f32_16x16x32_bf16 v[44:47], v[164:167], v[204:207], v[44:47]
	v_mfma_f32_16x16x32_bf16 v[40:43], v[172:175], v[204:207], v[40:43]
	v_mfma_f32_16x16x32_bf16 v[28:31], v[164:167], v[212:215], v[28:31]
	v_mfma_f32_16x16x32_bf16 v[24:27], v[172:175], v[212:215], v[24:27]
	v_mfma_f32_16x16x32_bf16 v[12:15], v[164:167], v[222:225], v[12:15]
	v_mfma_f32_16x16x32_bf16 v[8:11], v[172:175], v[222:225], v[8:11]
	v_mfma_f32_16x16x32_bf16 v[52:55], v[176:179], v[192:195], v[52:55]
	v_mfma_f32_16x16x32_bf16 v[48:51], v[184:187], v[192:195], v[48:51]
	v_mfma_f32_16x16x32_bf16 v[36:39], v[176:179], v[200:203], v[36:39]
	v_mfma_f32_16x16x32_bf16 v[32:35], v[184:187], v[200:203], v[32:35]
	v_mfma_f32_16x16x32_bf16 v[20:23], v[176:179], v[208:211], v[20:23]
	v_mfma_f32_16x16x32_bf16 v[16:19], v[184:187], v[208:211], v[16:19]
	v_mfma_f32_16x16x32_bf16 v[4:7], v[176:179], v[216:219], v[4:7]
	v_mfma_f32_16x16x32_bf16 v[0:3], v[184:187], v[216:219], v[0:3]
	v_mfma_f32_16x16x32_bf16 v[52:55], v[180:183], v[196:199], v[52:55]
	v_mfma_f32_16x16x32_bf16 v[48:51], v[188:191], v[196:199], v[48:51]
	v_mfma_f32_16x16x32_bf16 v[36:39], v[180:183], v[204:207], v[36:39]
	v_mfma_f32_16x16x32_bf16 v[32:35], v[188:191], v[204:207], v[32:35]
	v_mfma_f32_16x16x32_bf16 v[20:23], v[180:183], v[212:215], v[20:23]
	v_mfma_f32_16x16x32_bf16 v[16:19], v[188:191], v[212:215], v[16:19]
	v_mfma_f32_16x16x32_bf16 v[4:7], v[180:183], v[222:225], v[4:7]
	v_mfma_f32_16x16x32_bf16 v[0:3], v[188:191], v[222:225], v[0:3]
	s_barrier
	s_setprio 0
	s_add_u32 s8, s8, 0x100
	s_addc_u32 s9, s9, 0
	s_add_u32 s24, s24, 0x100
	s_addc_u32 s25, s25, 0
	s_cmp_ge_i32 s26, s42
	s_mov_b32 s22, s26
	s_cbranch_scc0 .LBB0_310

.LBB0_657:
	s_add_u32 s20, s74, 0x1fb40000
	v_cndmask_b32_e64 v0, 0, 1, s[6:7]
	s_addc_u32 s21, s75, 0
	v_cmp_ne_u32_e64 s[4:5], 1, v0
	s_andn2_b64 vcc, exec, s[6:7]
	s_cbranch_vccnz .LBB0_698
	v_bfe_i32 v2, v12, 27, 1
	v_lshlrev_b32_e32 v0, 4, v12
	v_lshrrev_b32_e32 v2, 22, v2
	v_add_u32_e32 v2, v0, v2
	v_and_b32_e32 v2, 0xfffffc00, v2
	v_sub_u32_e32 v2, v0, v2
	v_ashrrev_i32_e32 v1, 31, v12
	v_lshrrev_b32_e32 v3, 4, v2
	v_lshrrev_b32_e32 v1, 26, v1
	v_bitop3_b32 v2, v3, v2, 32 bitop3:0x6c
	v_add_u32_e32 v1, v12, v1
	v_ashrrev_i32_e32 v4, 31, v2
	v_ashrrev_i32_e32 v1, 6, v1
	v_lshrrev_b32_e32 v4, 26, v4
	v_lshlrev_b32_e32 v3, 3, v1
	v_add_u32_e32 v4, v2, v4
	v_and_b32_e32 v3, -16, v3
	v_ashrrev_i32_e32 v5, 6, v4
	v_lshlrev_b32_e32 v1, 5, v1
	v_add_u32_e32 v3, v5, v3
	v_and_b32_e32 v13, 32, v1
	v_and_b32_e32 v1, 0xc0, v4
	v_sub_u32_e32 v1, v2, v1
	v_mov_b32_e32 v2, 1
	v_lshlrev_b32_e32 v4, 1, v3
	v_lshrrev_b32_e32 v6, 2, v3
	v_and_b32_e32 v5, 3, v5
	s_mov_b32 s1, 0x7fffffe0
	v_ashrrev_i16_sdwa v1, v2, sext(v1) dst_sel:DWORD dst_unused:UNUSED_PAD src0_sel:DWORD src1_sel:BYTE_0
	v_and_b32_e32 v4, 24, v4
	v_and_b32_e32 v6, 4, v6
	v_and_or_b32 v5, v3, s1, v5
	v_bfe_i32 v14, v1, 0, 16
	v_or3_b32 v4, v5, v6, v4
	v_add_u32_e32 v1, v13, v14
	v_mul_lo_u32 v15, v3, s0
	v_mul_lo_u32 v3, v4, s0
	v_add_u32_e32 v0, 0x2000, v0
	v_lshrrev_b32_e32 v252, 3, v220
	v_bfe_u32 v253, v220, 4, 2
	v_bfe_u32 v254, v220, 6, 1
	v_lshl_or_b32 v253, v254, 2, v253
	v_and_b32_e32 v254, 7, v220
	v_xor_b32_e32 v253, v254, v253
	v_lshlrev_b32_e32 v253, 4, v253
	v_and_b32_e32 v254, 32, v252
	v_bfe_u32 v255, v252, 2, 2
	v_lshl_or_b32 v254, v255, 3, v254
	v_bfe_u32 v255, v252, 4, 1
	v_lshl_or_b32 v254, v255, 2, v254
	v_and_b32_e32 v255, 3, v252
	v_or_b32_e32 v254, v254, v255
	v_mul_u32_u24_e32 v254, 0x1000, v254
	v_add_u32_e32 v254, v254, v253
	v_add_u32_e32 v255, 0x40000, v254
	v_mul_u32_u24_e32 v252, 0x1000, v252
	v_add_u32_e32 v252, v252, v253
	v_add_u32_e32 v253, 0x40000, v252
	v_mov_b32_e32 v128, v252
	v_mov_b32_e32 v130, v254
	v_ashrrev_i32_e32 v1, 31, v0
	v_lshrrev_b32_e32 v1, 22, v1
	v_add_u32_e32 v1, v0, v1
	v_ashrrev_i32_e32 v1, 10, v1
	v_mul_i32_i24_e32 v3, 0x400, v1
	v_sub_u32_e32 v0, v0, v3
	v_lshrrev_b32_e32 v3, 4, v0
	v_bitop3_b32 v0, v3, v0, 32 bitop3:0x6c
	v_ashrrev_i32_e32 v4, 31, v0
	v_lshrrev_b32_e32 v4, 26, v4
	v_lshlrev_b32_e32 v3, 3, v1
	v_add_u32_e32 v4, v0, v4
	v_and_b32_e32 v3, -16, v3
	v_ashrrev_i32_e32 v5, 6, v4
	v_lshlrev_b32_e32 v1, 5, v1
	s_add_u32 s29, s74, 0x1f00000
	v_add_u32_e32 v3, v5, v3
	v_and_b32_e32 v16, 32, v1
	v_and_b32_e32 v1, 0xc0, v4
	v_and_b32_e32 v4, 3, v5
	s_addc_u32 s38, s75, 0
	v_and_or_b32 v4, v3, s1, v4
	s_ashr_i32 s1, s0, 31
	s_lshl_b64 s[12:13], s[0:1], 9
	s_ashr_i32 s9, s77, 31
	s_mul_i32 s9, s12, s9
	s_mul_hi_u32 s14, s12, s77
	s_add_i32 s9, s14, s9
	s_lshr_b64 s[14:15], s[0:1], 23
	s_mul_i32 s15, s14, s77
	s_add_i32 s9, s9, s15
	s_ashr_i32 s15, s78, 31
	s_mul_i32 s15, s12, s15
	s_mul_hi_u32 s23, s12, s78
	s_ashr_i32 s7, s8, 6
	s_add_i32 s15, s23, s15
	s_mul_i32 s14, s14, s78
	s_ashr_i32 s6, s8, 8
	v_sub_u32_e32 v0, v0, v1
	s_lshl_b64 s[10:11], s[0:1], 8
	s_lshl_b32 s39, s7, 10
	s_add_i32 s15, s15, s14
	s_mul_i32 s14, s12, s78
	v_ashrrev_i16_sdwa v0, v2, sext(v0) dst_sel:DWORD dst_unused:UNUSED_PAD src0_sel:DWORD src1_sel:BYTE_0
	v_lshlrev_b32_e32 v1, 1, v3
	v_lshrrev_b32_e32 v2, 2, v3
	s_add_u32 s36, s29, s14
	v_and_b32_e32 v1, 24, v1
	v_and_b32_e32 v2, 4, v2
	s_addc_u32 s37, s38, s15
	s_add_i32 s40, s39, 0
	v_bfe_i32 v17, v0, 0, 16
	v_or3_b32 v1, v4, v2, v1
	s_add_i32 m0, s40, 0x10000
	v_add_u32_e32 v0, v16, v17
	v_mul_lo_u32 v1, v1, s0
	global_load_lds_dwordx4 v130, s[36:37]
	s_add_i32 m0, s40, 0x12000
	v_mov_b32_e32 v134, v255
	s_add_u32 s14, s36, s10
	global_load_lds_dwordx4 v134, s[36:37]
	s_addc_u32 s15, s37, s11
	s_add_i32 m0, s40, 0x14000
	s_mul_i32 s22, s12, s77
	global_load_lds_dwordx4 v130, s[14:15]
	s_add_i32 m0, s40, 0x16000
	s_add_u32 s34, s60, s22
	s_addc_u32 s35, s61, s9
	s_add_i32 s41, s40, 0x2000
	v_mul_lo_u32 v18, v3, s0
	global_load_lds_dwordx4 v134, s[14:15]
	s_mov_b32 m0, s40
	s_add_u32 s22, s34, s10
	v_mov_b32_e32 v132, v253
	global_load_lds_dwordx4 v128, s[34:35]
	s_mov_b32 m0, s41
	s_addc_u32 s23, s35, s11
	s_add_i32 s42, s40, 0x4000
	global_load_lds_dwordx4 v132, s[34:35]
	s_mov_b32 m0, s42
	s_add_i32 s43, s40, 0x6000
	global_load_lds_dwordx4 v128, s[22:23]
	s_mov_b32 m0, s43
	v_mov_b32_e32 v131, 0
	global_load_lds_dwordx4 v132, s[22:23]
	v_mov_b32_e32 v135, v131
	v_mov_b32_e32 v129, v131
	v_mov_b32_e32 v133, v131
	s_cmp_eq_u32 s6, 1
	s_mov_b32 s44, 0
	v_lshl_add_u64 v[8:9], s[36:37], 0, v[130:131]
	v_lshl_add_u64 v[4:5], s[36:37], 0, v[134:135]
	v_lshl_add_u64 v[2:3], s[14:15], 0, v[130:131]
	v_lshl_add_u64 v[0:1], s[14:15], 0, v[134:135]
	v_lshl_add_u64 v[6:7], s[34:35], 0, v[128:129]
	s_cselect_b64 s[14:15], -1, 0
	s_cmp_lg_u32 s6, 1
	v_lshl_add_u64 v[10:11], s[34:35], 0, v[132:133]
	s_cbranch_scc1 .LBB0_660
	s_barrier
.LBB0_660:
	s_mov_b64 s[22:23], 0x80
	s_add_i32 m0, s40, 0x18000
	v_lshl_add_u64 v[8:9], v[8:9], 0, s[22:23]
	s_waitcnt vmcnt(2)
	s_barrier
	global_load_lds_dwordx4 v[8:9], off
	v_lshl_add_u64 v[4:5], v[4:5], 0, s[22:23]
	s_add_i32 m0, s40, 0x1a000
	s_add_i32 s45, s40, 0x8000
	global_load_lds_dwordx4 v[4:5], off
	v_lshl_add_u64 v[4:5], v[6:7], 0, s[22:23]
	s_mov_b32 m0, s45
	s_add_i32 s47, s40, 0xa000
	global_load_lds_dwordx4 v[4:5], off
	v_lshl_add_u64 v[4:5], v[10:11], 0, s[22:23]
	s_mov_b32 m0, s47
	v_lshl_add_u64 v[2:3], v[2:3], 0, s[22:23]
	global_load_lds_dwordx4 v[4:5], off
	s_add_i32 m0, s40, 0x1c000
	v_lshl_add_u64 v[0:1], v[0:1], 0, s[22:23]
	global_load_lds_dwordx4 v[2:3], off
	s_add_i32 m0, s40, 0x1e000
	s_lshr_b32 s1, s1, 26
	global_load_lds_dwordx4 v[0:1], off
	v_bfe_u32 v0, v12, 4, 2
	v_and_b32_e32 v1, 15, v12
	v_lshlrev_b32_e32 v2, 4, v0
	s_add_i32 s1, s0, s1
	v_lshl_or_b32 v188, s6, 6, v1
	v_lshl_or_b32 v1, v1, 6, v2
	v_lshlrev_b32_e32 v2, 2, v12
	s_ashr_i32 s54, s1, 6
	s_lshl_b32 s1, s6, 13
	v_and_b32_e32 v2, 32, v2
	v_bitop3_b32 v3, v1, s1, v2 bitop3:0xde
	s_lshl_b32 s1, s7, 5
	s_and_b32 s1, s1, 0x60
	s_lshl_b32 s6, s1, 7
	v_and_b32_e32 v252, 15, v220
	v_bfe_u32 v253, v220, 4, 2
	v_bfe_u32 v254, v252, 1, 2
	v_xor_b32_e32 v253, v253, v254
	v_bfe_u32 v254, v252, 3, 1
	v_lshl_or_b32 v253, v254, 2, v253
	v_lshlrev_b32_e32 v253, 4, v253
	v_lshl_or_b32 v253, v252, 7, v253
	v_lshrrev_b32_e32 v254, 6, v220
	v_lshrrev_b32_e32 v255, 2, v254
	v_lshl_or_b32 v252, v255, 13, v253
	v_and_b32_e32 v254, 3, v254
	v_lshl_or_b32 v253, v254, 12, v253
	v_mov_b32_e32 v189, v253
	v_xor_b32_e32 v1, 16, v221
	v_add_u32_e32 v2, 64, v223
	v_cmp_lt_i32_e32 vcc, v1, v2
	s_cmp_gt_i32 s0, 63
	v_cmp_eq_u32_e64 s[6:7], 0, v0
	v_cndmask_b32_e32 v1, v221, v1, vcc
	v_lshlrev_b32_e32 v190, 2, v1
	v_xor_b32_e32 v1, 32, v221
	v_cmp_lt_i32_e32 vcc, v1, v2
	v_lshl_or_b32 v192, v0, 3, s1
	v_add_u32_e32 v0, v15, v13
	v_cndmask_b32_e32 v1, v221, v1, vcc
	s_cselect_b64 s[24:25], -1, 0
	s_add_i32 s55, s54, -2
	v_lshlrev_b32_e32 v191, 2, v1
	v_mov_b32_e32 v0, v128
	v_mov_b32_e32 v1, v131
	s_waitcnt vmcnt(6)
	s_cmpk_lt_u32 s8, 0x100
	v_lshl_add_u64 v[136:137], s[10:11], 0, v[0:1]
	v_add_u32_e32 v0, v18, v16
	s_cselect_b64 s[26:27], -1, 0
	v_readlane_b32 s8, v251, 1
	v_mov_b32_e32 v0, v132
	s_add_i32 s58, 0, 0x10000
	s_add_i32 s59, 0, 0x14000
	s_ashr_i32 s56, s8, 31
	s_mov_b32 s57, s8
	v_lshl_add_u64 v[138:139], s[10:11], 0, v[0:1]
	v_mov_b64_e32 v[140:141], 0x200
	v_mov_b64_e32 v[142:143], 0x1ff
	v_add_u32_e32 v193, s58, v189
	v_add_u32_e32 v194, s59, v189
	v_mov_b32_e32 v195, v252
	v_xor_b32_e32 v252, 64, v195
	v_xor_b32_e32 v253, 64, v193
	v_xor_b32_e32 v254, 64, v194
	s_mov_b32 s28, 0x3fb504f3
	s_barrier
	v_readlane_b32 s9, v251, 2
	s_branch .LBB0_663

.LBB0_675:
	ds_read_b128 v[144:147], v193
	ds_read_b128 v[148:151], v253
	ds_read_b128 v[152:155], v193 offset:2048
	ds_read_b128 v[156:159], v253 offset:2048
	ds_read_b128 v[160:163], v194
	ds_read_b128 v[164:167], v254
	ds_read_b128 v[168:171], v194 offset:2048
	ds_read_b128 v[172:175], v254 offset:2048
	s_add_i32 s81, s36, 2
	s_add_u32 s84, s34, 0x80
	s_addc_u32 s37, s35, 0
	s_cmp_eq_u32 s55, s36
	s_cselect_b32 s36, s0, s84
	s_cselect_b32 s37, s1, s37
	s_cselect_b32 s85, s31, s80
	s_cselect_b32 s84, s30, s79
	v_lshl_add_u64 v[216:217], s[34:35], 0, v[136:137]
	s_add_i32 m0, s40, 0xc000
	ds_read_b128 v[176:179], v195
	ds_read_b128 v[180:183], v252
	ds_read_b128 v[184:187], v195 offset:2048
	ds_read_b128 v[196:199], v252 offset:2048
	ds_read_b128 v[200:203], v195 offset:4096
	ds_read_b128 v[204:207], v252 offset:4096
	ds_read_b128 v[208:211], v195 offset:6144
	ds_read_b128 v[212:215], v252 offset:6144
	global_load_lds_dwordx4 v[216:217], off
	v_lshl_add_u64 v[216:217], s[34:35], 0, v[138:139]
	s_add_i32 m0, s40, 0xe000
	s_nop 0
	global_load_lds_dwordx4 v[216:217], off
	s_waitcnt vmcnt(8)
	s_waitcnt lgkmcnt(0)
	s_setprio 1
	s_barrier
	v_mfma_f32_16x16x32_bf16 v[120:123], v[144:147], v[176:179], v[120:123]
	v_mfma_f32_16x16x32_bf16 v[124:127], v[152:155], v[176:179], v[124:127]
	v_mfma_f32_16x16x32_bf16 v[116:119], v[144:147], v[184:187], v[116:119]
	v_mfma_f32_16x16x32_bf16 v[112:115], v[152:155], v[184:187], v[112:115]
	v_mfma_f32_16x16x32_bf16 v[108:111], v[144:147], v[200:203], v[108:111]
	v_mfma_f32_16x16x32_bf16 v[104:107], v[152:155], v[200:203], v[104:107]
	v_mfma_f32_16x16x32_bf16 v[100:103], v[144:147], v[208:211], v[100:103]
	v_mfma_f32_16x16x32_bf16 v[96:99], v[152:155], v[208:211], v[96:99]
	v_mfma_f32_16x16x32_bf16 v[120:123], v[148:151], v[180:183], v[120:123]
	v_mfma_f32_16x16x32_bf16 v[124:127], v[156:159], v[180:183], v[124:127]
	v_mfma_f32_16x16x32_bf16 v[116:119], v[148:151], v[196:199], v[116:119]
	v_mfma_f32_16x16x32_bf16 v[112:115], v[156:159], v[196:199], v[112:115]
	v_mfma_f32_16x16x32_bf16 v[108:111], v[148:151], v[204:207], v[108:111]
	v_mfma_f32_16x16x32_bf16 v[104:107], v[156:159], v[204:207], v[104:107]
	v_mfma_f32_16x16x32_bf16 v[100:103], v[148:151], v[212:215], v[100:103]
	v_mfma_f32_16x16x32_bf16 v[96:99], v[156:159], v[212:215], v[96:99]
	v_mfma_f32_16x16x32_bf16 v[60:63], v[160:163], v[176:179], v[60:63]
	v_mfma_f32_16x16x32_bf16 v[56:59], v[168:171], v[176:179], v[56:59]
	v_mfma_f32_16x16x32_bf16 v[52:55], v[160:163], v[184:187], v[52:55]
	v_mfma_f32_16x16x32_bf16 v[48:51], v[168:171], v[184:187], v[48:51]
	v_mfma_f32_16x16x32_bf16 v[44:47], v[160:163], v[200:203], v[44:47]
	v_mfma_f32_16x16x32_bf16 v[40:43], v[168:171], v[200:203], v[40:43]
	v_mfma_f32_16x16x32_bf16 v[36:39], v[160:163], v[208:211], v[36:39]
	v_mfma_f32_16x16x32_bf16 v[32:35], v[168:171], v[208:211], v[32:35]
	v_mfma_f32_16x16x32_bf16 v[60:63], v[164:167], v[180:183], v[60:63]
	v_mfma_f32_16x16x32_bf16 v[56:59], v[172:175], v[180:183], v[56:59]
	v_mfma_f32_16x16x32_bf16 v[52:55], v[164:167], v[196:199], v[52:55]
	v_mfma_f32_16x16x32_bf16 v[48:51], v[172:175], v[196:199], v[48:51]
	v_mfma_f32_16x16x32_bf16 v[44:47], v[164:167], v[204:207], v[44:47]
	v_mfma_f32_16x16x32_bf16 v[40:43], v[172:175], v[204:207], v[40:43]
	v_mfma_f32_16x16x32_bf16 v[36:39], v[164:167], v[212:215], v[36:39]
	v_mfma_f32_16x16x32_bf16 v[32:35], v[172:175], v[212:215], v[32:35]
	s_barrier
	s_setprio 0
	s_add_i32 s86, s58, s39
	v_lshl_add_u64 v[216:217], s[84:85], 0, v[130:131]
	s_mov_b32 m0, s86
	ds_read_b128 v[176:179], v195 offset:16384
	ds_read_b128 v[180:183], v252 offset:16384
	ds_read_b128 v[184:187], v195 offset:18432
	ds_read_b128 v[196:199], v252 offset:18432
	ds_read_b128 v[200:203], v195 offset:20480
	ds_read_b128 v[204:207], v252 offset:20480
	ds_read_b128 v[208:211], v195 offset:22528
	ds_read_b128 v[212:215], v252 offset:22528
	global_load_lds_dwordx4 v[216:217], off
	s_add_i32 m0, s86, 0x2000
	v_lshl_add_u64 v[218:219], s[84:85], 0, v[134:135]
	s_add_u32 s84, s84, s10
	s_addc_u32 s85, s85, s11
	s_add_i32 s86, s59, s39
	global_load_lds_dwordx4 v[218:219], off
	v_lshl_add_u64 v[224:225], s[84:85], 0, v[130:131]
	s_mov_b32 m0, s86
	v_lshl_add_u64 v[226:227], s[84:85], 0, v[134:135]
	global_load_lds_dwordx4 v[224:225], off
	s_add_i32 m0, s86, 0x2000
	v_lshl_add_u64 v[228:229], s[36:37], 0, v[128:129]
	global_load_lds_dwordx4 v[226:227], off
	s_mov_b32 m0, s40
	v_lshl_add_u64 v[230:231], s[36:37], 0, v[132:133]
	global_load_lds_dwordx4 v[228:229], off
	s_mov_b32 m0, s41
	s_nop 0
	global_load_lds_dwordx4 v[230:231], off
	s_waitcnt vmcnt(8)
	s_waitcnt lgkmcnt(0)
	s_setprio 1
	s_barrier
	v_mfma_f32_16x16x32_bf16 v[92:95], v[144:147], v[176:179], v[92:95]
	v_mfma_f32_16x16x32_bf16 v[88:91], v[152:155], v[176:179], v[88:91]
	v_mfma_f32_16x16x32_bf16 v[84:87], v[144:147], v[184:187], v[84:87]
	v_mfma_f32_16x16x32_bf16 v[80:83], v[152:155], v[184:187], v[80:83]
	v_mfma_f32_16x16x32_bf16 v[76:79], v[144:147], v[200:203], v[76:79]
	v_mfma_f32_16x16x32_bf16 v[72:75], v[152:155], v[200:203], v[72:75]
	v_mfma_f32_16x16x32_bf16 v[68:71], v[144:147], v[208:211], v[68:71]
	v_mfma_f32_16x16x32_bf16 v[64:67], v[152:155], v[208:211], v[64:67]
	v_mfma_f32_16x16x32_bf16 v[92:95], v[148:151], v[180:183], v[92:95]
	v_mfma_f32_16x16x32_bf16 v[88:91], v[156:159], v[180:183], v[88:91]
	v_mfma_f32_16x16x32_bf16 v[84:87], v[148:151], v[196:199], v[84:87]
	v_mfma_f32_16x16x32_bf16 v[80:83], v[156:159], v[196:199], v[80:83]
	v_mfma_f32_16x16x32_bf16 v[76:79], v[148:151], v[204:207], v[76:79]
	v_mfma_f32_16x16x32_bf16 v[72:75], v[156:159], v[204:207], v[72:75]
	v_mfma_f32_16x16x32_bf16 v[68:71], v[148:151], v[212:215], v[68:71]
	v_mfma_f32_16x16x32_bf16 v[64:67], v[156:159], v[212:215], v[64:67]
	v_mfma_f32_16x16x32_bf16 v[28:31], v[160:163], v[176:179], v[28:31]
	v_mfma_f32_16x16x32_bf16 v[24:27], v[168:171], v[176:179], v[24:27]
	v_mfma_f32_16x16x32_bf16 v[20:23], v[160:163], v[184:187], v[20:23]
	v_mfma_f32_16x16x32_bf16 v[16:19], v[168:171], v[184:187], v[16:19]
	v_mfma_f32_16x16x32_bf16 v[12:15], v[160:163], v[200:203], v[12:15]
	v_mfma_f32_16x16x32_bf16 v[8:11], v[168:171], v[200:203], v[8:11]
	v_mfma_f32_16x16x32_bf16 v[4:7], v[160:163], v[208:211], v[4:7]
	v_mfma_f32_16x16x32_bf16 v[0:3], v[168:171], v[208:211], v[0:3]
	v_mfma_f32_16x16x32_bf16 v[28:31], v[164:167], v[180:183], v[28:31]
	v_mfma_f32_16x16x32_bf16 v[24:27], v[172:175], v[180:183], v[24:27]
	v_mfma_f32_16x16x32_bf16 v[20:23], v[164:167], v[196:199], v[20:23]
	v_mfma_f32_16x16x32_bf16 v[16:19], v[172:175], v[196:199], v[16:19]
	v_mfma_f32_16x16x32_bf16 v[12:15], v[164:167], v[204:207], v[12:15]
	v_mfma_f32_16x16x32_bf16 v[8:11], v[172:175], v[204:207], v[8:11]
	v_mfma_f32_16x16x32_bf16 v[4:7], v[164:167], v[212:215], v[4:7]
	v_mfma_f32_16x16x32_bf16 v[0:3], v[172:175], v[212:215], v[0:3]
	s_barrier
	s_setprio 0
	s_add_i32 s84, 0, 0x18000
	s_add_i32 s85, 0, 0x1c000
	v_add_u32_e32 v156, s84, v189
	v_add_u32_e32 v172, s85, v189
	v_xor_b32_e32 v255, 64, v156
	ds_read_b128 v[144:147], v156
	ds_read_b128 v[148:151], v255
	ds_read_b128 v[152:155], v156 offset:2048
	ds_read_b128 v[156:159], v255 offset:2048
	v_xor_b32_e32 v255, 64, v172
	ds_read_b128 v[160:163], v172
	ds_read_b128 v[164:167], v255
	ds_read_b128 v[168:171], v172 offset:2048
	ds_read_b128 v[172:175], v255 offset:2048
	s_add_u32 s36, s36, s10
	s_addc_u32 s37, s37, s11
	s_mov_b32 m0, s42
	v_lshl_add_u64 v[232:233], s[36:37], 0, v[128:129]
	ds_read_b128 v[176:179], v195 offset:32768
	ds_read_b128 v[180:183], v252 offset:32768
	ds_read_b128 v[184:187], v195 offset:34816
	ds_read_b128 v[196:199], v252 offset:34816
	ds_read_b128 v[200:203], v195 offset:36864
	ds_read_b128 v[204:207], v252 offset:36864
	ds_read_b128 v[208:211], v195 offset:38912
	ds_read_b128 v[212:215], v252 offset:38912
	global_load_lds_dwordx4 v[232:233], off
	v_lshl_add_u64 v[232:233], s[36:37], 0, v[132:133]
	s_mov_b32 m0, s43
	s_nop 0
	global_load_lds_dwordx4 v[232:233], off
	s_waitcnt vmcnt(8)
	s_waitcnt lgkmcnt(0)
	s_setprio 1
	s_barrier
	v_mfma_f32_16x16x32_bf16 v[120:123], v[144:147], v[176:179], v[120:123]
	v_mfma_f32_16x16x32_bf16 v[124:127], v[152:155], v[176:179], v[124:127]
	v_mfma_f32_16x16x32_bf16 v[116:119], v[144:147], v[184:187], v[116:119]
	v_mfma_f32_16x16x32_bf16 v[112:115], v[152:155], v[184:187], v[112:115]
	v_mfma_f32_16x16x32_bf16 v[108:111], v[144:147], v[200:203], v[108:111]
	v_mfma_f32_16x16x32_bf16 v[104:107], v[152:155], v[200:203], v[104:107]
	v_mfma_f32_16x16x32_bf16 v[100:103], v[144:147], v[208:211], v[100:103]
	v_mfma_f32_16x16x32_bf16 v[96:99], v[152:155], v[208:211], v[96:99]
	v_mfma_f32_16x16x32_bf16 v[120:123], v[148:151], v[180:183], v[120:123]
	v_mfma_f32_16x16x32_bf16 v[124:127], v[156:159], v[180:183], v[124:127]
	v_mfma_f32_16x16x32_bf16 v[116:119], v[148:151], v[196:199], v[116:119]
	v_mfma_f32_16x16x32_bf16 v[112:115], v[156:159], v[196:199], v[112:115]
	v_mfma_f32_16x16x32_bf16 v[108:111], v[148:151], v[204:207], v[108:111]
	v_mfma_f32_16x16x32_bf16 v[104:107], v[156:159], v[204:207], v[104:107]
	v_mfma_f32_16x16x32_bf16 v[100:103], v[148:151], v[212:215], v[100:103]
	v_mfma_f32_16x16x32_bf16 v[96:99], v[156:159], v[212:215], v[96:99]
	v_mfma_f32_16x16x32_bf16 v[60:63], v[160:163], v[176:179], v[60:63]
	v_mfma_f32_16x16x32_bf16 v[56:59], v[168:171], v[176:179], v[56:59]
	v_mfma_f32_16x16x32_bf16 v[52:55], v[160:163], v[184:187], v[52:55]
	v_mfma_f32_16x16x32_bf16 v[48:51], v[168:171], v[184:187], v[48:51]
	v_mfma_f32_16x16x32_bf16 v[44:47], v[160:163], v[200:203], v[44:47]
	v_mfma_f32_16x16x32_bf16 v[40:43], v[168:171], v[200:203], v[40:43]
	v_mfma_f32_16x16x32_bf16 v[36:39], v[160:163], v[208:211], v[36:39]
	v_mfma_f32_16x16x32_bf16 v[32:35], v[168:171], v[208:211], v[32:35]
	v_mfma_f32_16x16x32_bf16 v[60:63], v[164:167], v[180:183], v[60:63]
	v_mfma_f32_16x16x32_bf16 v[56:59], v[172:175], v[180:183], v[56:59]
	v_mfma_f32_16x16x32_bf16 v[52:55], v[164:167], v[196:199], v[52:55]
	v_mfma_f32_16x16x32_bf16 v[48:51], v[172:175], v[196:199], v[48:51]
	v_mfma_f32_16x16x32_bf16 v[44:47], v[164:167], v[204:207], v[44:47]
	v_mfma_f32_16x16x32_bf16 v[40:43], v[172:175], v[204:207], v[40:43]
	v_mfma_f32_16x16x32_bf16 v[36:39], v[164:167], v[212:215], v[36:39]
	v_mfma_f32_16x16x32_bf16 v[32:35], v[172:175], v[212:215], v[32:35]
	s_barrier
	s_setprio 0
	s_add_i32 s36, s84, s39
	v_lshl_add_u64 v[216:217], v[216:217], 0, s[22:23]
	s_mov_b32 m0, s36
	ds_read_b128 v[176:179], v195 offset:49152
	ds_read_b128 v[180:183], v252 offset:49152
	ds_read_b128 v[184:187], v195 offset:51200
	ds_read_b128 v[196:199], v252 offset:51200
	ds_read_b128 v[200:203], v195 offset:53248
	ds_read_b128 v[204:207], v252 offset:53248
	ds_read_b128 v[208:211], v195 offset:55296
	ds_read_b128 v[212:215], v252 offset:55296
	global_load_lds_dwordx4 v[216:217], off
	v_lshl_add_u64 v[216:217], v[218:219], 0, s[22:23]
	s_add_i32 m0, s36, 0x2000
	s_add_i32 s36, s85, s39
	global_load_lds_dwordx4 v[216:217], off
	v_lshl_add_u64 v[216:217], v[224:225], 0, s[22:23]
	s_mov_b32 m0, s36
	s_nop 0
	global_load_lds_dwordx4 v[216:217], off
	v_lshl_add_u64 v[216:217], v[226:227], 0, s[22:23]
	s_add_i32 m0, s36, 0x2000
	s_nop 0
	global_load_lds_dwordx4 v[216:217], off
	v_lshl_add_u64 v[216:217], v[228:229], 0, s[22:23]
	s_mov_b32 m0, s45
	s_nop 0
	global_load_lds_dwordx4 v[216:217], off
	v_lshl_add_u64 v[216:217], v[230:231], 0, s[22:23]
	s_mov_b32 m0, s47
	s_nop 0
	global_load_lds_dwordx4 v[216:217], off
	s_waitcnt vmcnt(8)
	s_waitcnt lgkmcnt(0)
	s_setprio 1
	s_barrier
	v_mfma_f32_16x16x32_bf16 v[92:95], v[144:147], v[176:179], v[92:95]
	v_mfma_f32_16x16x32_bf16 v[88:91], v[152:155], v[176:179], v[88:91]
	v_mfma_f32_16x16x32_bf16 v[84:87], v[144:147], v[184:187], v[84:87]
	v_mfma_f32_16x16x32_bf16 v[80:83], v[152:155], v[184:187], v[80:83]
	v_mfma_f32_16x16x32_bf16 v[76:79], v[144:147], v[200:203], v[76:79]
	v_mfma_f32_16x16x32_bf16 v[72:75], v[152:155], v[200:203], v[72:75]
	v_mfma_f32_16x16x32_bf16 v[68:71], v[144:147], v[208:211], v[68:71]
	v_mfma_f32_16x16x32_bf16 v[64:67], v[152:155], v[208:211], v[64:67]
	v_mfma_f32_16x16x32_bf16 v[92:95], v[148:151], v[180:183], v[92:95]
	v_mfma_f32_16x16x32_bf16 v[88:91], v[156:159], v[180:183], v[88:91]
	v_mfma_f32_16x16x32_bf16 v[84:87], v[148:151], v[196:199], v[84:87]
	v_mfma_f32_16x16x32_bf16 v[80:83], v[156:159], v[196:199], v[80:83]
	v_mfma_f32_16x16x32_bf16 v[76:79], v[148:151], v[204:207], v[76:79]
	v_mfma_f32_16x16x32_bf16 v[72:75], v[156:159], v[204:207], v[72:75]
	v_mfma_f32_16x16x32_bf16 v[68:71], v[148:151], v[212:215], v[68:71]
	v_mfma_f32_16x16x32_bf16 v[64:67], v[156:159], v[212:215], v[64:67]
	v_mfma_f32_16x16x32_bf16 v[28:31], v[160:163], v[176:179], v[28:31]
	v_mfma_f32_16x16x32_bf16 v[24:27], v[168:171], v[176:179], v[24:27]
	v_mfma_f32_16x16x32_bf16 v[20:23], v[160:163], v[184:187], v[20:23]
	v_mfma_f32_16x16x32_bf16 v[16:19], v[168:171], v[184:187], v[16:19]
	v_mfma_f32_16x16x32_bf16 v[12:15], v[160:163], v[200:203], v[12:15]
	v_mfma_f32_16x16x32_bf16 v[8:11], v[168:171], v[200:203], v[8:11]
	v_mfma_f32_16x16x32_bf16 v[4:7], v[160:163], v[208:211], v[4:7]
	v_mfma_f32_16x16x32_bf16 v[0:3], v[168:171], v[208:211], v[0:3]
	v_mfma_f32_16x16x32_bf16 v[28:31], v[164:167], v[180:183], v[28:31]
	v_mfma_f32_16x16x32_bf16 v[24:27], v[172:175], v[180:183], v[24:27]
	v_mfma_f32_16x16x32_bf16 v[20:23], v[164:167], v[196:199], v[20:23]
	v_mfma_f32_16x16x32_bf16 v[16:19], v[172:175], v[196:199], v[16:19]
	v_mfma_f32_16x16x32_bf16 v[12:15], v[164:167], v[204:207], v[12:15]
	v_mfma_f32_16x16x32_bf16 v[8:11], v[172:175], v[204:207], v[8:11]
	v_mfma_f32_16x16x32_bf16 v[4:7], v[164:167], v[212:215], v[4:7]
	v_mfma_f32_16x16x32_bf16 v[0:3], v[172:175], v[212:215], v[0:3]
	s_barrier
	s_setprio 0
	s_add_u32 s34, s34, 0x100
	s_addc_u32 s35, s35, 0
	s_add_u32 s79, s79, 0x100
	s_addc_u32 s80, s80, 0
	s_cmp_ge_i32 s81, s54
	s_mov_b32 s36, s81
	s_cbranch_scc0 .LBB0_675

.LBB0_755:
	v_bfe_i32 v2, v12, 27, 1
	v_lshlrev_b32_e32 v0, 4, v12
	v_lshrrev_b32_e32 v2, 22, v2
	v_add_u32_e32 v2, v0, v2
	v_and_b32_e32 v2, 0xfffffc00, v2
	v_sub_u32_e32 v2, v0, v2
	v_ashrrev_i32_e32 v1, 31, v12
	v_lshrrev_b32_e32 v3, 4, v2
	v_lshrrev_b32_e32 v1, 26, v1
	v_bitop3_b32 v2, v3, v2, 32 bitop3:0x6c
	v_add_u32_e32 v1, v12, v1
	v_ashrrev_i32_e32 v4, 31, v2
	v_ashrrev_i32_e32 v1, 6, v1
	v_lshrrev_b32_e32 v4, 26, v4
	v_lshlrev_b32_e32 v3, 3, v1
	v_add_u32_e32 v4, v2, v4
	v_and_b32_e32 v3, -16, v3
	v_ashrrev_i32_e32 v5, 6, v4
	v_lshlrev_b32_e32 v1, 5, v1
	v_add_u32_e32 v3, v5, v3
	v_and_b32_e32 v13, 32, v1
	v_and_b32_e32 v1, 0xc0, v4
	s_ashr_i32 s6, s1, 3
	v_sub_u32_e32 v1, v2, v1
	v_mov_b32_e32 v2, 1
	v_lshlrev_b32_e32 v4, 1, v3
	v_lshrrev_b32_e32 v6, 2, v3
	v_and_b32_e32 v5, 3, v5
	s_mov_b32 s1, 0x7fffffe0
	v_ashrrev_i16_sdwa v1, v2, sext(v1) dst_sel:DWORD dst_unused:UNUSED_PAD src0_sel:DWORD src1_sel:BYTE_0
	v_and_b32_e32 v4, 24, v4
	v_and_b32_e32 v6, 4, v6
	v_and_or_b32 v5, v3, s1, v5
	v_bfe_i32 v14, v1, 0, 16
	v_or3_b32 v4, v5, v6, v4
	v_add_u32_e32 v1, v13, v14
	v_mul_lo_u32 v15, v3, s0
	v_mul_lo_u32 v3, v4, s0
	v_add_u32_e32 v0, 0x2000, v0
	s_add_u32 s37, s74, 0x2700000
	v_lshrrev_b32_e32 v252, 3, v220
	v_bfe_u32 v253, v220, 4, 2
	v_bfe_u32 v254, v220, 6, 1
	v_lshl_or_b32 v253, v254, 2, v253
	v_and_b32_e32 v254, 7, v220
	v_xor_b32_e32 v253, v254, v253
	v_lshlrev_b32_e32 v253, 4, v253
	v_and_b32_e32 v254, 32, v252
	v_bfe_u32 v255, v252, 2, 2
	v_lshl_or_b32 v254, v255, 3, v254
	v_bfe_u32 v255, v252, 4, 1
	v_lshl_or_b32 v254, v255, 2, v254
	v_and_b32_e32 v255, 3, v252
	v_or_b32_e32 v254, v254, v255
	v_mul_u32_u24_e32 v254, 0x1000, v254
	v_add_u32_e32 v254, v254, v253
	v_add_u32_e32 v255, 0x40000, v254
	v_mul_u32_u24_e32 v252, 0x1000, v252
	v_add_u32_e32 v252, v252, v253
	v_add_u32_e32 v253, 0x40000, v252
	v_mov_b32_e32 v144, v252
	v_mov_b32_e32 v146, v254
	v_ashrrev_i32_e32 v1, 31, v0
	s_addc_u32 s42, s75, 0
	v_lshrrev_b32_e32 v1, 22, v1
	s_add_i32 s6, s8, s6
	v_add_u32_e32 v1, v0, v1
	s_ashr_i32 s8, s6, 31
	v_ashrrev_i32_e32 v1, 10, v1
	s_lshr_b32 s8, s8, 25
	v_mul_i32_i24_e32 v3, 0x400, v1
	s_add_i32 s8, s6, s8
	v_sub_u32_e32 v0, v0, v3
	s_ashr_i32 s9, s8, 7
	s_and_b32 s8, s8, 0xffffff80
	v_lshrrev_b32_e32 v3, 4, v0
	s_sub_i32 s8, s6, s8
	v_bitop3_b32 v0, v3, v0, 32 bitop3:0x6c
	s_bfe_i32 s6, s8, 0x80000
	v_ashrrev_i32_e32 v4, 31, v0
	s_bfe_u32 s6, s6, 0x2000d
	v_lshrrev_b32_e32 v4, 26, v4
	s_add_i32 s10, s8, s6
	v_lshlrev_b32_e32 v3, 3, v1
	v_add_u32_e32 v4, v0, v4
	s_bfe_i32 s6, s10, 0x80000
	s_and_b32 s10, s10, 0xfc
	v_and_b32_e32 v3, -16, v3
	v_ashrrev_i32_e32 v5, 6, v4
	v_lshlrev_b32_e32 v1, 5, v1
	s_sub_i32 s8, s8, s10
	v_add_u32_e32 v3, v5, v3
	v_and_b32_e32 v16, 32, v1
	v_and_b32_e32 v1, 0xc0, v4
	v_and_b32_e32 v4, 3, v5
	s_lshl_b32 s9, s9, 2
	s_sext_i32_i8 s8, s8
	v_and_or_b32 v4, v3, s1, v4
	s_ashr_i32 s1, s0, 31
	s_add_i32 s79, s9, s8
	s_lshl_b64 s[22:23], s[0:1], 9
	s_ashr_i32 s8, s79, 31
	s_mul_i32 s8, s22, s8
	s_mul_hi_u32 s9, s22, s79
	s_sext_i32_i16 s24, s6
	s_add_i32 s10, s9, s8
	s_lshr_b64 s[8:9], s[0:1], 23
	s_ashr_i32 s7, s34, 6
	s_lshr_b32 s6, s24, 2
	s_mul_i32 s9, s8, s79
	s_add_i32 s26, s10, s9
	s_bfe_i64 s[10:11], s[6:7], 0x100000
	s_ashr_i32 s9, s24, 2
	s_mul_hi_u32 s10, s22, s9
	s_mul_i32 s11, s22, s11
	s_add_i32 s10, s10, s11
	s_mul_i32 s8, s8, s9
	v_sub_u32_e32 v0, v0, v1
	s_ashr_i32 s30, s34, 8
	s_lshl_b64 s[14:15], s[0:1], 8
	s_lshl_b32 s43, s7, 10
	s_add_i32 s10, s10, s8
	s_mul_i32 s8, s22, s9
	v_ashrrev_i16_sdwa v0, v2, sext(v0) dst_sel:DWORD dst_unused:UNUSED_PAD src0_sel:DWORD src1_sel:BYTE_0
	v_lshlrev_b32_e32 v1, 1, v3
	v_lshrrev_b32_e32 v2, 2, v3
	s_add_u32 s8, s37, s8
	v_and_b32_e32 v1, 24, v1
	v_and_b32_e32 v2, 4, v2
	s_addc_u32 s9, s42, s10
	s_add_i32 s44, s43, 0
	v_bfe_i32 v17, v0, 0, 16
	v_or3_b32 v1, v4, v2, v1
	s_add_i32 m0, s44, 0x10000
	v_add_u32_e32 v0, v16, v17
	v_mul_lo_u32 v1, v1, s0
	global_load_lds_dwordx4 v146, s[8:9]
	s_add_i32 m0, s44, 0x12000
	v_mov_b32_e32 v150, v255
	s_add_u32 s24, s8, s14
	global_load_lds_dwordx4 v150, s[8:9]
	s_addc_u32 s25, s9, s15
	s_add_i32 m0, s44, 0x14000
	s_mul_i32 s27, s22, s79
	global_load_lds_dwordx4 v146, s[24:25]
	s_add_i32 m0, s44, 0x16000
	s_add_u32 s10, s16, s27
	s_addc_u32 s11, s17, s26
	s_add_i32 s45, s44, 0x2000
	v_mul_lo_u32 v18, v3, s0
	global_load_lds_dwordx4 v150, s[24:25]
	s_mov_b32 m0, s44
	s_add_u32 s26, s10, s14
	v_mov_b32_e32 v148, v253
	global_load_lds_dwordx4 v144, s[10:11]
	s_mov_b32 m0, s45
	s_addc_u32 s27, s11, s15
	s_add_i32 s47, s44, 0x4000
	global_load_lds_dwordx4 v148, s[10:11]
	s_mov_b32 m0, s47
	s_add_i32 s48, s44, 0x6000
	global_load_lds_dwordx4 v144, s[26:27]
	s_mov_b32 m0, s48
	v_mov_b32_e32 v147, 0
	global_load_lds_dwordx4 v148, s[26:27]
	v_mov_b32_e32 v151, v147
	v_mov_b32_e32 v145, v147
	v_mov_b32_e32 v149, v147
	s_cmp_eq_u32 s30, 1
	s_mov_b32 s49, 0
	v_lshl_add_u64 v[8:9], s[8:9], 0, v[146:147]
	v_lshl_add_u64 v[4:5], s[8:9], 0, v[150:151]
	v_lshl_add_u64 v[2:3], s[24:25], 0, v[146:147]
	v_lshl_add_u64 v[0:1], s[24:25], 0, v[150:151]
	v_lshl_add_u64 v[6:7], s[10:11], 0, v[144:145]
	s_cselect_b64 s[24:25], -1, 0
	s_cmp_lg_u32 s30, 1
	v_lshl_add_u64 v[10:11], s[10:11], 0, v[148:149]
	s_cbranch_scc1 .LBB0_757
	s_barrier
.LBB0_757:
	s_add_u32 s26, s74, 0x1fb0c000
	s_mov_b64 s[28:29], 0x80
	s_addc_u32 s27, s75, 0
	s_add_i32 m0, s44, 0x18000
	v_lshl_add_u64 v[8:9], v[8:9], 0, s[28:29]
	s_waitcnt vmcnt(2)
	s_barrier
	global_load_lds_dwordx4 v[8:9], off
	v_lshl_add_u64 v[4:5], v[4:5], 0, s[28:29]
	s_add_i32 m0, s44, 0x1a000
	s_add_i32 s54, s44, 0x8000
	global_load_lds_dwordx4 v[4:5], off
	v_lshl_add_u64 v[4:5], v[6:7], 0, s[28:29]
	s_mov_b32 m0, s54
	s_add_i32 s55, s44, 0xa000
	global_load_lds_dwordx4 v[4:5], off
	v_lshl_add_u64 v[4:5], v[10:11], 0, s[28:29]
	s_mov_b32 m0, s55
	v_lshl_add_u64 v[2:3], v[2:3], 0, s[28:29]
	global_load_lds_dwordx4 v[4:5], off
	s_add_i32 m0, s44, 0x1c000
	v_lshl_add_u64 v[0:1], v[0:1], 0, s[28:29]
	global_load_lds_dwordx4 v[2:3], off
	s_add_i32 m0, s44, 0x1e000
	s_lshr_b32 s1, s1, 26
	global_load_lds_dwordx4 v[0:1], off
	v_lshrrev_b32_e32 v1, 1, v12
	v_and_b32_e32 v1, 24, v1
	v_and_b32_e32 v0, 15, v12
	v_lshlrev_b32_e32 v2, 1, v1
	s_add_i32 s1, s0, s1
	v_lshl_or_b32 v175, s30, 6, v0
	v_lshl_or_b32 v0, v0, 6, v2
	v_lshlrev_b32_e32 v2, 2, v12
	s_ashr_i32 s56, s1, 6
	s_lshl_b32 s1, s30, 13
	v_and_b32_e32 v2, 32, v2
	v_bitop3_b32 v3, v0, s1, v2 bitop3:0xde
	s_lshl_b32 s1, s7, 5
	s_and_b32 s1, s1, 0x60
	s_sext_i32_i8 s78, s6
	s_lshl_b32 s6, s1, 7
	v_and_b32_e32 v252, 15, v220
	v_bfe_u32 v253, v220, 4, 2
	v_bfe_u32 v254, v252, 1, 2
	v_xor_b32_e32 v253, v253, v254
	v_bfe_u32 v254, v252, 3, 1
	v_lshl_or_b32 v253, v254, 2, v253
	v_lshlrev_b32_e32 v253, 4, v253
	v_lshl_or_b32 v253, v252, 7, v253
	v_lshrrev_b32_e32 v254, 6, v220
	v_lshrrev_b32_e32 v255, 2, v254
	v_lshl_or_b32 v252, v255, 13, v253
	v_and_b32_e32 v254, 3, v254
	v_lshl_or_b32 v253, v254, 12, v253
	v_mov_b32_e32 v177, v253
	s_cmp_gt_i32 s0, 63
	v_add_u32_e32 v0, v15, v13
	s_cselect_b64 s[30:31], -1, 0
	s_add_i32 s57, s56, -2
	v_or_b32_e32 v181, s1, v1
	v_mov_b32_e32 v0, v144
	v_mov_b32_e32 v1, v147
	s_waitcnt vmcnt(6)
	s_cmpk_lt_u32 s34, 0x100
	v_lshl_add_u64 v[152:153], s[14:15], 0, v[0:1]
	v_add_u32_e32 v0, v18, v16
	s_cselect_b64 s[34:35], -1, 0
	v_readlane_b32 s6, v251, 1
	v_mov_b32_e32 v0, v148
	s_add_i32 s60, 0, 0x10000
	s_add_i32 s61, 0, 0x14000
	s_ashr_i32 s58, s6, 31
	s_mov_b32 s59, s6
	v_lshl_add_u64 v[154:155], s[14:15], 0, v[0:1]
	v_mov_b64_e32 v[156:157], 0x800
	v_mov_b64_e32 v[158:159], 0x7ff
	v_add_u32_e32 v183, s60, v177
	v_add_u32_e32 v185, s61, v177
	v_mov_b32_e32 v187, v252
	v_xor_b32_e32 v252, 64, v187
	v_xor_b32_e32 v253, 64, v183
	v_xor_b32_e32 v254, 64, v185
	s_mov_b32 s36, 0x3a000000
	s_mov_b32 s63, 0xf800000
	v_mov_b32_e32 v189, 0x260
	s_barrier
	v_readlane_b32 s7, v251, 2
	s_branch .LBB0_760

.LBB0_772:
	ds_read_b128 v[128:131], v183
	ds_read_b128 v[132:135], v253
	ds_read_b128 v[136:139], v183 offset:2048
	ds_read_b128 v[140:143], v253 offset:2048
	ds_read_b128 v[160:163], v185
	ds_read_b128 v[164:167], v254
	ds_read_b128 v[168:171], v185 offset:2048
	ds_read_b128 v[190:193], v254 offset:2048
	s_add_i32 s80, s8, 2
	s_add_u32 s81, s0, 0x80
	s_addc_u32 s9, s1, 0
	s_cmp_eq_u32 s57, s8
	s_cselect_b32 s8, s38, s81
	s_cselect_b32 s9, s39, s9
	s_cselect_b32 s85, s41, s11
	s_cselect_b32 s84, s40, s10
	v_lshl_add_u64 v[172:173], s[0:1], 0, v[152:153]
	s_add_i32 m0, s44, 0xc000
	ds_read_b128 v[194:197], v187
	ds_read_b128 v[198:201], v252
	ds_read_b128 v[202:205], v187 offset:2048
	ds_read_b128 v[206:209], v252 offset:2048
	ds_read_b128 v[210:213], v187 offset:4096
	ds_read_b128 v[214:217], v252 offset:4096
	ds_read_b128 v[224:227], v187 offset:6144
	ds_read_b128 v[228:231], v252 offset:6144
	global_load_lds_dwordx4 v[172:173], off
	v_lshl_add_u64 v[172:173], s[0:1], 0, v[154:155]
	s_add_i32 m0, s44, 0xe000
	s_nop 0
	global_load_lds_dwordx4 v[172:173], off
	s_waitcnt vmcnt(8)
	s_waitcnt lgkmcnt(0)
	s_setprio 1
	s_barrier
	v_mfma_f32_16x16x32_bf16 v[124:127], v[128:131], v[194:197], v[124:127]
	v_mfma_f32_16x16x32_bf16 v[120:123], v[136:139], v[194:197], v[120:123]
	v_mfma_f32_16x16x32_bf16 v[116:119], v[128:131], v[202:205], v[116:119]
	v_mfma_f32_16x16x32_bf16 v[112:115], v[136:139], v[202:205], v[112:115]
	v_mfma_f32_16x16x32_bf16 v[108:111], v[128:131], v[210:213], v[108:111]
	v_mfma_f32_16x16x32_bf16 v[104:107], v[136:139], v[210:213], v[104:107]
	v_mfma_f32_16x16x32_bf16 v[100:103], v[128:131], v[224:227], v[100:103]
	v_mfma_f32_16x16x32_bf16 v[96:99], v[136:139], v[224:227], v[96:99]
	v_mfma_f32_16x16x32_bf16 v[124:127], v[132:135], v[198:201], v[124:127]
	v_mfma_f32_16x16x32_bf16 v[120:123], v[140:143], v[198:201], v[120:123]
	v_mfma_f32_16x16x32_bf16 v[116:119], v[132:135], v[206:209], v[116:119]
	v_mfma_f32_16x16x32_bf16 v[112:115], v[140:143], v[206:209], v[112:115]
	v_mfma_f32_16x16x32_bf16 v[108:111], v[132:135], v[214:217], v[108:111]
	v_mfma_f32_16x16x32_bf16 v[104:107], v[140:143], v[214:217], v[104:107]
	v_mfma_f32_16x16x32_bf16 v[100:103], v[132:135], v[228:231], v[100:103]
	v_mfma_f32_16x16x32_bf16 v[96:99], v[140:143], v[228:231], v[96:99]
	v_mfma_f32_16x16x32_bf16 v[60:63], v[160:163], v[194:197], v[60:63]
	v_mfma_f32_16x16x32_bf16 v[56:59], v[168:171], v[194:197], v[56:59]
	v_mfma_f32_16x16x32_bf16 v[52:55], v[160:163], v[202:205], v[52:55]
	v_mfma_f32_16x16x32_bf16 v[48:51], v[168:171], v[202:205], v[48:51]
	v_mfma_f32_16x16x32_bf16 v[44:47], v[160:163], v[210:213], v[44:47]
	v_mfma_f32_16x16x32_bf16 v[40:43], v[168:171], v[210:213], v[40:43]
	v_mfma_f32_16x16x32_bf16 v[36:39], v[160:163], v[224:227], v[36:39]
	v_mfma_f32_16x16x32_bf16 v[32:35], v[168:171], v[224:227], v[32:35]
	v_mfma_f32_16x16x32_bf16 v[60:63], v[164:167], v[198:201], v[60:63]
	v_mfma_f32_16x16x32_bf16 v[56:59], v[190:193], v[198:201], v[56:59]
	v_mfma_f32_16x16x32_bf16 v[52:55], v[164:167], v[206:209], v[52:55]
	v_mfma_f32_16x16x32_bf16 v[48:51], v[190:193], v[206:209], v[48:51]
	v_mfma_f32_16x16x32_bf16 v[44:47], v[164:167], v[214:217], v[44:47]
	v_mfma_f32_16x16x32_bf16 v[40:43], v[190:193], v[214:217], v[40:43]
	v_mfma_f32_16x16x32_bf16 v[36:39], v[164:167], v[228:231], v[36:39]
	v_mfma_f32_16x16x32_bf16 v[32:35], v[190:193], v[228:231], v[32:35]
	s_barrier
	s_setprio 0
	s_add_i32 s81, s60, s43
	v_lshl_add_u64 v[172:173], s[84:85], 0, v[146:147]
	s_mov_b32 m0, s81
	ds_read_b128 v[194:197], v187 offset:16384
	ds_read_b128 v[198:201], v252 offset:16384
	ds_read_b128 v[202:205], v187 offset:18432
	ds_read_b128 v[206:209], v252 offset:18432
	ds_read_b128 v[210:213], v187 offset:20480
	ds_read_b128 v[214:217], v252 offset:20480
	ds_read_b128 v[224:227], v187 offset:22528
	ds_read_b128 v[228:231], v252 offset:22528
	global_load_lds_dwordx4 v[172:173], off
	s_add_i32 m0, s81, 0x2000
	v_lshl_add_u64 v[178:179], s[84:85], 0, v[150:151]
	s_add_u32 s84, s84, s14
	s_addc_u32 s85, s85, s15
	s_add_i32 s81, s61, s43
	global_load_lds_dwordx4 v[178:179], off
	v_lshl_add_u64 v[218:219], s[84:85], 0, v[146:147]
	s_mov_b32 m0, s81
	v_lshl_add_u64 v[232:233], s[84:85], 0, v[150:151]
	global_load_lds_dwordx4 v[218:219], off
	s_add_i32 m0, s81, 0x2000
	v_lshl_add_u64 v[234:235], s[8:9], 0, v[144:145]
	global_load_lds_dwordx4 v[232:233], off
	s_mov_b32 m0, s44
	v_lshl_add_u64 v[236:237], s[8:9], 0, v[148:149]
	global_load_lds_dwordx4 v[234:235], off
	s_mov_b32 m0, s45
	s_nop 0
	global_load_lds_dwordx4 v[236:237], off
	s_waitcnt vmcnt(8)
	s_waitcnt lgkmcnt(0)
	s_setprio 1
	s_barrier
	v_mfma_f32_16x16x32_bf16 v[92:95], v[128:131], v[194:197], v[92:95]
	v_mfma_f32_16x16x32_bf16 v[88:91], v[136:139], v[194:197], v[88:91]
	v_mfma_f32_16x16x32_bf16 v[84:87], v[128:131], v[202:205], v[84:87]
	v_mfma_f32_16x16x32_bf16 v[80:83], v[136:139], v[202:205], v[80:83]
	v_mfma_f32_16x16x32_bf16 v[76:79], v[128:131], v[210:213], v[76:79]
	v_mfma_f32_16x16x32_bf16 v[72:75], v[136:139], v[210:213], v[72:75]
	v_mfma_f32_16x16x32_bf16 v[68:71], v[128:131], v[224:227], v[68:71]
	v_mfma_f32_16x16x32_bf16 v[64:67], v[136:139], v[224:227], v[64:67]
	v_mfma_f32_16x16x32_bf16 v[92:95], v[132:135], v[198:201], v[92:95]
	v_mfma_f32_16x16x32_bf16 v[88:91], v[140:143], v[198:201], v[88:91]
	v_mfma_f32_16x16x32_bf16 v[84:87], v[132:135], v[206:209], v[84:87]
	v_mfma_f32_16x16x32_bf16 v[80:83], v[140:143], v[206:209], v[80:83]
	v_mfma_f32_16x16x32_bf16 v[76:79], v[132:135], v[214:217], v[76:79]
	v_mfma_f32_16x16x32_bf16 v[72:75], v[140:143], v[214:217], v[72:75]
	v_mfma_f32_16x16x32_bf16 v[68:71], v[132:135], v[228:231], v[68:71]
	v_mfma_f32_16x16x32_bf16 v[64:67], v[140:143], v[228:231], v[64:67]
	v_mfma_f32_16x16x32_bf16 v[28:31], v[160:163], v[194:197], v[28:31]
	v_mfma_f32_16x16x32_bf16 v[24:27], v[168:171], v[194:197], v[24:27]
	v_mfma_f32_16x16x32_bf16 v[20:23], v[160:163], v[202:205], v[20:23]
	v_mfma_f32_16x16x32_bf16 v[16:19], v[168:171], v[202:205], v[16:19]
	v_mfma_f32_16x16x32_bf16 v[12:15], v[160:163], v[210:213], v[12:15]
	v_mfma_f32_16x16x32_bf16 v[8:11], v[168:171], v[210:213], v[8:11]
	v_mfma_f32_16x16x32_bf16 v[4:7], v[160:163], v[224:227], v[4:7]
	v_mfma_f32_16x16x32_bf16 v[0:3], v[168:171], v[224:227], v[0:3]
	v_mfma_f32_16x16x32_bf16 v[28:31], v[164:167], v[198:201], v[28:31]
	v_mfma_f32_16x16x32_bf16 v[24:27], v[190:193], v[198:201], v[24:27]
	v_mfma_f32_16x16x32_bf16 v[20:23], v[164:167], v[206:209], v[20:23]
	v_mfma_f32_16x16x32_bf16 v[16:19], v[190:193], v[206:209], v[16:19]
	v_mfma_f32_16x16x32_bf16 v[12:15], v[164:167], v[214:217], v[12:15]
	v_mfma_f32_16x16x32_bf16 v[8:11], v[190:193], v[214:217], v[8:11]
	v_mfma_f32_16x16x32_bf16 v[4:7], v[164:167], v[228:231], v[4:7]
	v_mfma_f32_16x16x32_bf16 v[0:3], v[190:193], v[228:231], v[0:3]
	s_barrier
	s_setprio 0
	s_add_i32 s81, 0, 0x18000
	s_add_i32 s84, 0, 0x1c000
	v_add_u32_e32 v140, s81, v177
	v_add_u32_e32 v174, s84, v177
	v_xor_b32_e32 v255, 64, v140
	ds_read_b128 v[128:131], v140
	ds_read_b128 v[132:135], v255
	ds_read_b128 v[136:139], v140 offset:2048
	ds_read_b128 v[140:143], v255 offset:2048
	v_xor_b32_e32 v255, 64, v174
	ds_read_b128 v[160:163], v174
	ds_read_b128 v[164:167], v255
	ds_read_b128 v[168:171], v174 offset:2048
	ds_read_b128 v[190:193], v255 offset:2048
	s_add_u32 s8, s8, s14
	s_addc_u32 s9, s9, s15
	s_mov_b32 m0, s47
	v_lshl_add_u64 v[238:239], s[8:9], 0, v[144:145]
	ds_read_b128 v[194:197], v187 offset:32768
	ds_read_b128 v[198:201], v252 offset:32768
	ds_read_b128 v[202:205], v187 offset:34816
	ds_read_b128 v[206:209], v252 offset:34816
	ds_read_b128 v[210:213], v187 offset:36864
	ds_read_b128 v[214:217], v252 offset:36864
	ds_read_b128 v[224:227], v187 offset:38912
	ds_read_b128 v[228:231], v252 offset:38912
	global_load_lds_dwordx4 v[238:239], off
	v_lshl_add_u64 v[238:239], s[8:9], 0, v[148:149]
	s_mov_b32 m0, s48
	s_nop 0
	global_load_lds_dwordx4 v[238:239], off
	s_waitcnt vmcnt(8)
	s_waitcnt lgkmcnt(0)
	s_setprio 1
	s_barrier
	v_mfma_f32_16x16x32_bf16 v[124:127], v[128:131], v[194:197], v[124:127]
	v_mfma_f32_16x16x32_bf16 v[120:123], v[136:139], v[194:197], v[120:123]
	v_mfma_f32_16x16x32_bf16 v[116:119], v[128:131], v[202:205], v[116:119]
	v_mfma_f32_16x16x32_bf16 v[112:115], v[136:139], v[202:205], v[112:115]
	v_mfma_f32_16x16x32_bf16 v[108:111], v[128:131], v[210:213], v[108:111]
	v_mfma_f32_16x16x32_bf16 v[104:107], v[136:139], v[210:213], v[104:107]
	v_mfma_f32_16x16x32_bf16 v[100:103], v[128:131], v[224:227], v[100:103]
	v_mfma_f32_16x16x32_bf16 v[96:99], v[136:139], v[224:227], v[96:99]
	v_mfma_f32_16x16x32_bf16 v[124:127], v[132:135], v[198:201], v[124:127]
	v_mfma_f32_16x16x32_bf16 v[120:123], v[140:143], v[198:201], v[120:123]
	v_mfma_f32_16x16x32_bf16 v[116:119], v[132:135], v[206:209], v[116:119]
	v_mfma_f32_16x16x32_bf16 v[112:115], v[140:143], v[206:209], v[112:115]
	v_mfma_f32_16x16x32_bf16 v[108:111], v[132:135], v[214:217], v[108:111]
	v_mfma_f32_16x16x32_bf16 v[104:107], v[140:143], v[214:217], v[104:107]
	v_mfma_f32_16x16x32_bf16 v[100:103], v[132:135], v[228:231], v[100:103]
	v_mfma_f32_16x16x32_bf16 v[96:99], v[140:143], v[228:231], v[96:99]
	v_mfma_f32_16x16x32_bf16 v[60:63], v[160:163], v[194:197], v[60:63]
	v_mfma_f32_16x16x32_bf16 v[56:59], v[168:171], v[194:197], v[56:59]
	v_mfma_f32_16x16x32_bf16 v[52:55], v[160:163], v[202:205], v[52:55]
	v_mfma_f32_16x16x32_bf16 v[48:51], v[168:171], v[202:205], v[48:51]
	v_mfma_f32_16x16x32_bf16 v[44:47], v[160:163], v[210:213], v[44:47]
	v_mfma_f32_16x16x32_bf16 v[40:43], v[168:171], v[210:213], v[40:43]
	v_mfma_f32_16x16x32_bf16 v[36:39], v[160:163], v[224:227], v[36:39]
	v_mfma_f32_16x16x32_bf16 v[32:35], v[168:171], v[224:227], v[32:35]
	v_mfma_f32_16x16x32_bf16 v[60:63], v[164:167], v[198:201], v[60:63]
	v_mfma_f32_16x16x32_bf16 v[56:59], v[190:193], v[198:201], v[56:59]
	v_mfma_f32_16x16x32_bf16 v[52:55], v[164:167], v[206:209], v[52:55]
	v_mfma_f32_16x16x32_bf16 v[48:51], v[190:193], v[206:209], v[48:51]
	v_mfma_f32_16x16x32_bf16 v[44:47], v[164:167], v[214:217], v[44:47]
	v_mfma_f32_16x16x32_bf16 v[40:43], v[190:193], v[214:217], v[40:43]
	v_mfma_f32_16x16x32_bf16 v[36:39], v[164:167], v[228:231], v[36:39]
	v_mfma_f32_16x16x32_bf16 v[32:35], v[190:193], v[228:231], v[32:35]
	s_barrier
	s_setprio 0
	s_add_i32 s8, s81, s43
	v_lshl_add_u64 v[172:173], v[172:173], 0, s[28:29]
	s_mov_b32 m0, s8
	ds_read_b128 v[194:197], v187 offset:49152
	ds_read_b128 v[198:201], v252 offset:49152
	ds_read_b128 v[202:205], v187 offset:51200
	ds_read_b128 v[206:209], v252 offset:51200
	ds_read_b128 v[210:213], v187 offset:53248
	ds_read_b128 v[214:217], v252 offset:53248
	ds_read_b128 v[224:227], v187 offset:55296
	ds_read_b128 v[228:231], v252 offset:55296
	global_load_lds_dwordx4 v[172:173], off
	v_lshl_add_u64 v[172:173], v[178:179], 0, s[28:29]
	s_add_i32 m0, s8, 0x2000
	s_add_i32 s8, s84, s43
	global_load_lds_dwordx4 v[172:173], off
	v_lshl_add_u64 v[172:173], v[218:219], 0, s[28:29]
	s_mov_b32 m0, s8
	s_nop 0
	global_load_lds_dwordx4 v[172:173], off
	v_lshl_add_u64 v[172:173], v[232:233], 0, s[28:29]
	s_add_i32 m0, s8, 0x2000
	s_nop 0
	global_load_lds_dwordx4 v[172:173], off
	v_lshl_add_u64 v[172:173], v[234:235], 0, s[28:29]
	s_mov_b32 m0, s54
	s_nop 0
	global_load_lds_dwordx4 v[172:173], off
	v_lshl_add_u64 v[172:173], v[236:237], 0, s[28:29]
	s_mov_b32 m0, s55
	s_nop 0
	global_load_lds_dwordx4 v[172:173], off
	s_waitcnt vmcnt(8)
	s_waitcnt lgkmcnt(0)
	s_setprio 1
	s_barrier
	v_mfma_f32_16x16x32_bf16 v[92:95], v[128:131], v[194:197], v[92:95]
	v_mfma_f32_16x16x32_bf16 v[88:91], v[136:139], v[194:197], v[88:91]
	v_mfma_f32_16x16x32_bf16 v[84:87], v[128:131], v[202:205], v[84:87]
	v_mfma_f32_16x16x32_bf16 v[80:83], v[136:139], v[202:205], v[80:83]
	v_mfma_f32_16x16x32_bf16 v[76:79], v[128:131], v[210:213], v[76:79]
	v_mfma_f32_16x16x32_bf16 v[72:75], v[136:139], v[210:213], v[72:75]
	v_mfma_f32_16x16x32_bf16 v[68:71], v[128:131], v[224:227], v[68:71]
	v_mfma_f32_16x16x32_bf16 v[64:67], v[136:139], v[224:227], v[64:67]
	v_mfma_f32_16x16x32_bf16 v[92:95], v[132:135], v[198:201], v[92:95]
	v_mfma_f32_16x16x32_bf16 v[88:91], v[140:143], v[198:201], v[88:91]
	v_mfma_f32_16x16x32_bf16 v[84:87], v[132:135], v[206:209], v[84:87]
	v_mfma_f32_16x16x32_bf16 v[80:83], v[140:143], v[206:209], v[80:83]
	v_mfma_f32_16x16x32_bf16 v[76:79], v[132:135], v[214:217], v[76:79]
	v_mfma_f32_16x16x32_bf16 v[72:75], v[140:143], v[214:217], v[72:75]
	v_mfma_f32_16x16x32_bf16 v[68:71], v[132:135], v[228:231], v[68:71]
	v_mfma_f32_16x16x32_bf16 v[64:67], v[140:143], v[228:231], v[64:67]
	v_mfma_f32_16x16x32_bf16 v[28:31], v[160:163], v[194:197], v[28:31]
	v_mfma_f32_16x16x32_bf16 v[24:27], v[168:171], v[194:197], v[24:27]
	v_mfma_f32_16x16x32_bf16 v[20:23], v[160:163], v[202:205], v[20:23]
	v_mfma_f32_16x16x32_bf16 v[16:19], v[168:171], v[202:205], v[16:19]
	v_mfma_f32_16x16x32_bf16 v[12:15], v[160:163], v[210:213], v[12:15]
	v_mfma_f32_16x16x32_bf16 v[8:11], v[168:171], v[210:213], v[8:11]
	v_mfma_f32_16x16x32_bf16 v[4:7], v[160:163], v[224:227], v[4:7]
	v_mfma_f32_16x16x32_bf16 v[0:3], v[168:171], v[224:227], v[0:3]
	v_mfma_f32_16x16x32_bf16 v[28:31], v[164:167], v[198:201], v[28:31]
	v_mfma_f32_16x16x32_bf16 v[24:27], v[190:193], v[198:201], v[24:27]
	v_mfma_f32_16x16x32_bf16 v[20:23], v[164:167], v[206:209], v[20:23]
	v_mfma_f32_16x16x32_bf16 v[16:19], v[190:193], v[206:209], v[16:19]
	v_mfma_f32_16x16x32_bf16 v[12:15], v[164:167], v[214:217], v[12:15]
	v_mfma_f32_16x16x32_bf16 v[8:11], v[190:193], v[214:217], v[8:11]
	v_mfma_f32_16x16x32_bf16 v[4:7], v[164:167], v[228:231], v[4:7]
	v_mfma_f32_16x16x32_bf16 v[0:3], v[190:193], v[228:231], v[0:3]
	s_barrier
	s_setprio 0
	s_add_u32 s0, s0, 0x100
	s_addc_u32 s1, s1, 0
	s_add_u32 s10, s10, 0x100
	s_addc_u32 s11, s11, 0
	s_cmp_ge_i32 s80, s56
	s_mov_b32 s8, s80
	s_cbranch_scc0 .LBB0_772

.LBB0_837:
	s_add_u32 s14, s74, 0x1fb60000
	s_addc_u32 s15, s75, 0
	s_and_b64 vcc, exec, s[4:5]
	s_cbranch_vccnz .LBB0_878
	v_bfe_i32 v2, v12, 27, 1
	v_lshlrev_b32_e32 v0, 4, v12
	v_lshrrev_b32_e32 v2, 22, v2
	v_add_u32_e32 v2, v0, v2
	v_and_b32_e32 v2, 0xfffffc00, v2
	v_sub_u32_e32 v2, v0, v2
	v_ashrrev_i32_e32 v1, 31, v12
	v_lshrrev_b32_e32 v3, 4, v2
	v_lshrrev_b32_e32 v1, 26, v1
	v_bitop3_b32 v2, v3, v2, 32 bitop3:0x6c
	v_add_u32_e32 v1, v12, v1
	v_ashrrev_i32_e32 v4, 31, v2
	v_ashrrev_i32_e32 v1, 6, v1
	v_lshrrev_b32_e32 v4, 26, v4
	v_lshlrev_b32_e32 v3, 3, v1
	v_add_u32_e32 v4, v2, v4
	v_and_b32_e32 v3, -16, v3
	v_ashrrev_i32_e32 v5, 6, v4
	v_lshlrev_b32_e32 v1, 5, v1
	v_add_u32_e32 v3, v5, v3
	v_and_b32_e32 v13, 32, v1
	v_and_b32_e32 v1, 0xc0, v4
	v_sub_u32_e32 v1, v2, v1
	v_mov_b32_e32 v2, 1
	v_lshlrev_b32_e32 v4, 1, v3
	v_lshrrev_b32_e32 v6, 2, v3
	v_and_b32_e32 v5, 3, v5
	s_mov_b32 s1, 0x7fffffe0
	v_ashrrev_i16_sdwa v1, v2, sext(v1) dst_sel:DWORD dst_unused:UNUSED_PAD src0_sel:DWORD src1_sel:BYTE_0
	v_and_b32_e32 v4, 24, v4
	v_and_b32_e32 v6, 4, v6
	v_and_or_b32 v5, v3, s1, v5
	v_bfe_i32 v14, v1, 0, 16
	v_or3_b32 v4, v5, v6, v4
	v_add_u32_e32 v1, v13, v14
	v_mul_lo_u32 v15, v3, s0
	v_mul_lo_u32 v3, v4, s0
	v_add_u32_e32 v0, 0x2000, v0
	v_lshrrev_b32_e32 v252, 3, v220
	v_bfe_u32 v253, v220, 4, 2
	v_bfe_u32 v254, v220, 6, 1
	v_lshl_or_b32 v253, v254, 2, v253
	v_and_b32_e32 v254, 7, v220
	v_xor_b32_e32 v253, v254, v253
	v_lshlrev_b32_e32 v253, 4, v253
	v_and_b32_e32 v254, 32, v252
	v_bfe_u32 v255, v252, 2, 2
	v_lshl_or_b32 v254, v255, 3, v254
	v_bfe_u32 v255, v252, 4, 1
	v_lshl_or_b32 v254, v255, 2, v254
	v_and_b32_e32 v255, 3, v252
	v_or_b32_e32 v254, v254, v255
	v_mul_u32_u24_e32 v254, 0x4000, v254
	v_add_u32_e32 v254, v254, v253
	v_add_u32_e32 v255, 0x100000, v254
	v_mul_u32_u24_e32 v252, 0x4000, v252
	v_add_u32_e32 v252, v252, v253
	v_add_u32_e32 v253, 0x100000, v252
	v_mov_b32_e32 v144, v252
	v_mov_b32_e32 v146, v254
	v_ashrrev_i32_e32 v1, 31, v0
	v_lshrrev_b32_e32 v1, 22, v1
	v_add_u32_e32 v1, v0, v1
	v_ashrrev_i32_e32 v1, 10, v1
	v_mul_i32_i24_e32 v3, 0x400, v1
	v_sub_u32_e32 v0, v0, v3
	v_lshrrev_b32_e32 v3, 4, v0
	v_bitop3_b32 v0, v3, v0, 32 bitop3:0x6c
	v_ashrrev_i32_e32 v4, 31, v0
	v_lshrrev_b32_e32 v4, 26, v4
	v_lshlrev_b32_e32 v3, 3, v1
	v_add_u32_e32 v4, v0, v4
	v_and_b32_e32 v3, -16, v3
	v_ashrrev_i32_e32 v5, 6, v4
	v_lshlrev_b32_e32 v1, 5, v1
	s_add_u32 s35, s74, 0x4700000
	v_add_u32_e32 v3, v5, v3
	v_and_b32_e32 v16, 32, v1
	v_and_b32_e32 v1, 0xc0, v4
	v_and_b32_e32 v4, 3, v5
	s_addc_u32 s37, s75, 0
	v_and_or_b32 v4, v3, s1, v4
	s_ashr_i32 s1, s0, 31
	s_lshl_b64 s[22:23], s[0:1], 9
	s_ashr_i32 s9, s84, 31
	s_mul_i32 s9, s22, s9
	s_mul_hi_u32 s24, s22, s84
	s_add_i32 s9, s24, s9
	s_lshr_b64 s[24:25], s[0:1], 23
	s_mul_i32 s25, s24, s84
	s_add_i32 s9, s9, s25
	s_ashr_i32 s25, s81, 31
	s_mul_i32 s25, s22, s25
	s_mul_hi_u32 s27, s22, s81
	s_ashr_i32 s7, s8, 6
	s_add_i32 s25, s27, s25
	s_mul_i32 s24, s24, s81
	s_ashr_i32 s6, s8, 8
	v_sub_u32_e32 v0, v0, v1
	s_lshl_b64 s[10:11], s[0:1], 8
	s_lshl_b32 s47, s7, 10
	s_add_i32 s25, s25, s24
	s_mul_i32 s24, s22, s81
	v_ashrrev_i16_sdwa v0, v2, sext(v0) dst_sel:DWORD dst_unused:UNUSED_PAD src0_sel:DWORD src1_sel:BYTE_0
	v_lshlrev_b32_e32 v1, 1, v3
	v_lshrrev_b32_e32 v2, 2, v3
	s_add_u32 s42, s35, s24
	v_and_b32_e32 v1, 24, v1
	v_and_b32_e32 v2, 4, v2
	s_addc_u32 s43, s37, s25
	s_add_i32 s48, s47, 0
	v_bfe_i32 v17, v0, 0, 16
	v_or3_b32 v1, v4, v2, v1
	s_add_i32 m0, s48, 0x10000
	v_add_u32_e32 v0, v16, v17
	v_mul_lo_u32 v1, v1, s0
	global_load_lds_dwordx4 v146, s[42:43]
	s_add_i32 m0, s48, 0x12000
	v_mov_b32_e32 v150, v255
	s_add_u32 s24, s42, s10
	global_load_lds_dwordx4 v150, s[42:43]
	s_addc_u32 s25, s43, s11
	s_add_i32 m0, s48, 0x14000
	s_mul_i32 s26, s22, s84
	global_load_lds_dwordx4 v146, s[24:25]
	s_add_i32 m0, s48, 0x16000
	s_add_u32 s44, s50, s26
	s_addc_u32 s45, s51, s9
	s_add_i32 s49, s48, 0x2000
	v_mul_lo_u32 v18, v3, s0
	global_load_lds_dwordx4 v150, s[24:25]
	s_mov_b32 m0, s48
	s_add_u32 s26, s44, s10
	v_mov_b32_e32 v148, v253
	global_load_lds_dwordx4 v144, s[44:45]
	s_mov_b32 m0, s49
	s_addc_u32 s27, s45, s11
	s_add_i32 s54, s48, 0x4000
	global_load_lds_dwordx4 v148, s[44:45]
	s_mov_b32 m0, s54
	s_add_i32 s55, s48, 0x6000
	global_load_lds_dwordx4 v144, s[26:27]
	s_mov_b32 m0, s55
	v_mov_b32_e32 v147, 0
	global_load_lds_dwordx4 v148, s[26:27]
	v_mov_b32_e32 v151, v147
	v_mov_b32_e32 v145, v147
	v_mov_b32_e32 v149, v147
	s_cmp_eq_u32 s6, 1
	s_mov_b32 s56, 0
	v_lshl_add_u64 v[8:9], s[42:43], 0, v[146:147]
	v_lshl_add_u64 v[4:5], s[42:43], 0, v[150:151]
	v_lshl_add_u64 v[2:3], s[24:25], 0, v[146:147]
	v_lshl_add_u64 v[0:1], s[24:25], 0, v[150:151]
	v_lshl_add_u64 v[6:7], s[44:45], 0, v[144:145]
	s_cselect_b64 s[24:25], -1, 0
	s_cmp_lg_u32 s6, 1
	v_lshl_add_u64 v[10:11], s[44:45], 0, v[148:149]
	s_cbranch_scc1 .LBB0_840
	s_barrier
.LBB0_840:
	s_mov_b64 s[26:27], 0x80
	s_add_i32 m0, s48, 0x18000
	v_lshl_add_u64 v[8:9], v[8:9], 0, s[26:27]
	s_waitcnt vmcnt(2)
	s_barrier
	global_load_lds_dwordx4 v[8:9], off
	v_lshl_add_u64 v[4:5], v[4:5], 0, s[26:27]
	s_add_i32 m0, s48, 0x1a000
	s_add_i32 s57, s48, 0x8000
	global_load_lds_dwordx4 v[4:5], off
	v_lshl_add_u64 v[4:5], v[6:7], 0, s[26:27]
	s_mov_b32 m0, s57
	s_add_i32 s58, s48, 0xa000
	global_load_lds_dwordx4 v[4:5], off
	v_lshl_add_u64 v[4:5], v[10:11], 0, s[26:27]
	s_mov_b32 m0, s58
	v_lshl_add_u64 v[2:3], v[2:3], 0, s[26:27]
	global_load_lds_dwordx4 v[4:5], off
	s_add_i32 m0, s48, 0x1c000
	v_lshl_add_u64 v[0:1], v[0:1], 0, s[26:27]
	global_load_lds_dwordx4 v[2:3], off
	s_add_i32 m0, s48, 0x1e000
	s_lshr_b32 s1, s1, 26
	global_load_lds_dwordx4 v[0:1], off
	v_bfe_u32 v0, v12, 4, 2
	v_and_b32_e32 v1, 15, v12
	v_lshlrev_b32_e32 v2, 4, v0
	s_add_i32 s1, s0, s1
	v_lshl_or_b32 v224, s6, 6, v1
	v_lshl_or_b32 v1, v1, 6, v2
	v_lshlrev_b32_e32 v2, 2, v12
	s_ashr_i32 s59, s1, 6
	s_lshl_b32 s1, s6, 13
	v_and_b32_e32 v2, 32, v2
	v_bitop3_b32 v3, v1, s1, v2 bitop3:0xde
	s_lshl_b32 s1, s7, 5
	s_and_b32 s1, s1, 0x60
	s_lshl_b32 s6, s1, 7
	v_and_b32_e32 v252, 15, v220
	v_bfe_u32 v253, v220, 4, 2
	v_bfe_u32 v254, v252, 1, 2
	v_xor_b32_e32 v253, v253, v254
	v_bfe_u32 v254, v252, 3, 1
	v_lshl_or_b32 v253, v254, 2, v253
	v_lshlrev_b32_e32 v253, 4, v253
	v_lshl_or_b32 v253, v252, 7, v253
	v_lshrrev_b32_e32 v254, 6, v220
	v_lshrrev_b32_e32 v255, 2, v254
	v_lshl_or_b32 v252, v255, 13, v253
	v_and_b32_e32 v254, 3, v254
	v_lshl_or_b32 v253, v254, 12, v253
	v_mov_b32_e32 v225, v253
	v_xor_b32_e32 v1, 16, v221
	v_add_u32_e32 v2, 64, v223
	v_cmp_lt_i32_e32 vcc, v1, v2
	s_cmp_gt_i32 s0, 63
	v_cmp_eq_u32_e64 s[6:7], 0, v0
	v_cndmask_b32_e32 v1, v221, v1, vcc
	v_lshlrev_b32_e32 v226, 2, v1
	v_xor_b32_e32 v1, 32, v221
	v_cmp_lt_i32_e32 vcc, v1, v2
	v_lshl_or_b32 v228, v0, 3, s1
	v_add_u32_e32 v0, v15, v13
	v_cndmask_b32_e32 v1, v221, v1, vcc
	s_cselect_b64 s[28:29], -1, 0
	s_add_i32 s60, s59, -2
	v_lshlrev_b32_e32 v227, 2, v1
	v_mov_b32_e32 v0, v144
	v_mov_b32_e32 v1, v147
	s_waitcnt vmcnt(6)
	s_cmpk_lt_u32 s8, 0x100
	v_lshl_add_u64 v[152:153], s[10:11], 0, v[0:1]
	v_add_u32_e32 v0, v18, v16
	s_cselect_b64 s[30:31], -1, 0
	v_readlane_b32 s8, v251, 1
	v_mov_b32_e32 v0, v148
	s_add_i32 s76, 0, 0x10000
	s_add_i32 s77, 0, 0x14000
	s_ashr_i32 s61, s8, 31
	s_mov_b32 s63, s8
	v_lshl_add_u64 v[154:155], s[10:11], 0, v[0:1]
	v_mov_b64_e32 v[156:157], 0x200
	v_mov_b64_e32 v[158:159], 0x1ff
	v_add_u32_e32 v229, s76, v225
	v_add_u32_e32 v230, s77, v225
	v_mov_b32_e32 v231, v252
	v_xor_b32_e32 v252, 64, v231
	v_xor_b32_e32 v253, 64, v229
	v_xor_b32_e32 v254, 64, v230
	s_mov_b32 s34, 0x3a000000
	s_mov_b32 s78, 0xf800000
	v_mov_b32_e32 v232, 0x260
	s_mov_b32 s36, 0x3fb504f3
	s_barrier
	v_readlane_b32 s9, v251, 2
	s_branch .LBB0_843

.LBB0_855:
	ds_read_b128 v[128:131], v229
	ds_read_b128 v[132:135], v253
	ds_read_b128 v[136:139], v229 offset:2048
	ds_read_b128 v[140:143], v253 offset:2048
	ds_read_b128 v[160:163], v230
	ds_read_b128 v[164:167], v254
	ds_read_b128 v[168:171], v230 offset:2048
	ds_read_b128 v[172:175], v254 offset:2048
	s_add_i32 s85, s42, 2
	s_add_u32 s86, s0, 0x80
	s_addc_u32 s43, s1, 0
	s_cmp_eq_u32 s60, s42
	s_cselect_b32 s42, s38, s86
	s_cselect_b32 s43, s39, s43
	s_cselect_b32 s87, s41, s45
	s_cselect_b32 s86, s40, s44
	v_lshl_add_u64 v[208:209], s[0:1], 0, v[152:153]
	s_add_i32 m0, s48, 0xc000
	ds_read_b128 v[176:179], v231
	ds_read_b128 v[180:183], v252
	ds_read_b128 v[184:187], v231 offset:2048
	ds_read_b128 v[188:191], v252 offset:2048
	ds_read_b128 v[192:195], v231 offset:4096
	ds_read_b128 v[196:199], v252 offset:4096
	ds_read_b128 v[200:203], v231 offset:6144
	ds_read_b128 v[204:207], v252 offset:6144
	global_load_lds_dwordx4 v[208:209], off
	v_lshl_add_u64 v[208:209], s[0:1], 0, v[154:155]
	s_add_i32 m0, s48, 0xe000
	s_nop 0
	global_load_lds_dwordx4 v[208:209], off
	s_waitcnt vmcnt(8)
	s_waitcnt lgkmcnt(0)
	s_setprio 1
	s_barrier
	v_mfma_f32_16x16x32_bf16 v[124:127], v[128:131], v[176:179], v[124:127]
	v_mfma_f32_16x16x32_bf16 v[120:123], v[136:139], v[176:179], v[120:123]
	v_mfma_f32_16x16x32_bf16 v[116:119], v[128:131], v[184:187], v[116:119]
	v_mfma_f32_16x16x32_bf16 v[112:115], v[136:139], v[184:187], v[112:115]
	v_mfma_f32_16x16x32_bf16 v[108:111], v[128:131], v[192:195], v[108:111]
	v_mfma_f32_16x16x32_bf16 v[104:107], v[136:139], v[192:195], v[104:107]
	v_mfma_f32_16x16x32_bf16 v[100:103], v[128:131], v[200:203], v[100:103]
	v_mfma_f32_16x16x32_bf16 v[96:99], v[136:139], v[200:203], v[96:99]
	v_mfma_f32_16x16x32_bf16 v[124:127], v[132:135], v[180:183], v[124:127]
	v_mfma_f32_16x16x32_bf16 v[120:123], v[140:143], v[180:183], v[120:123]
	v_mfma_f32_16x16x32_bf16 v[116:119], v[132:135], v[188:191], v[116:119]
	v_mfma_f32_16x16x32_bf16 v[112:115], v[140:143], v[188:191], v[112:115]
	v_mfma_f32_16x16x32_bf16 v[108:111], v[132:135], v[196:199], v[108:111]
	v_mfma_f32_16x16x32_bf16 v[104:107], v[140:143], v[196:199], v[104:107]
	v_mfma_f32_16x16x32_bf16 v[100:103], v[132:135], v[204:207], v[100:103]
	v_mfma_f32_16x16x32_bf16 v[96:99], v[140:143], v[204:207], v[96:99]
	v_mfma_f32_16x16x32_bf16 v[60:63], v[160:163], v[176:179], v[60:63]
	v_mfma_f32_16x16x32_bf16 v[56:59], v[168:171], v[176:179], v[56:59]
	v_mfma_f32_16x16x32_bf16 v[52:55], v[160:163], v[184:187], v[52:55]
	v_mfma_f32_16x16x32_bf16 v[48:51], v[168:171], v[184:187], v[48:51]
	v_mfma_f32_16x16x32_bf16 v[44:47], v[160:163], v[192:195], v[44:47]
	v_mfma_f32_16x16x32_bf16 v[40:43], v[168:171], v[192:195], v[40:43]
	v_mfma_f32_16x16x32_bf16 v[36:39], v[160:163], v[200:203], v[36:39]
	v_mfma_f32_16x16x32_bf16 v[32:35], v[168:171], v[200:203], v[32:35]
	v_mfma_f32_16x16x32_bf16 v[60:63], v[164:167], v[180:183], v[60:63]
	v_mfma_f32_16x16x32_bf16 v[56:59], v[172:175], v[180:183], v[56:59]
	v_mfma_f32_16x16x32_bf16 v[52:55], v[164:167], v[188:191], v[52:55]
	v_mfma_f32_16x16x32_bf16 v[48:51], v[172:175], v[188:191], v[48:51]
	v_mfma_f32_16x16x32_bf16 v[44:47], v[164:167], v[196:199], v[44:47]
	v_mfma_f32_16x16x32_bf16 v[40:43], v[172:175], v[196:199], v[40:43]
	v_mfma_f32_16x16x32_bf16 v[36:39], v[164:167], v[204:207], v[36:39]
	v_mfma_f32_16x16x32_bf16 v[32:35], v[172:175], v[204:207], v[32:35]
	s_barrier
	s_setprio 0
	s_add_i32 s88, s76, s47
	v_lshl_add_u64 v[208:209], s[86:87], 0, v[146:147]
	s_mov_b32 m0, s88
	ds_read_b128 v[176:179], v231 offset:16384
	ds_read_b128 v[180:183], v252 offset:16384
	ds_read_b128 v[184:187], v231 offset:18432
	ds_read_b128 v[188:191], v252 offset:18432
	ds_read_b128 v[192:195], v231 offset:20480
	ds_read_b128 v[196:199], v252 offset:20480
	ds_read_b128 v[200:203], v231 offset:22528
	ds_read_b128 v[204:207], v252 offset:22528
	global_load_lds_dwordx4 v[208:209], off
	s_add_i32 m0, s88, 0x2000
	v_lshl_add_u64 v[210:211], s[86:87], 0, v[150:151]
	s_add_u32 s86, s86, s10
	s_addc_u32 s87, s87, s11
	s_add_i32 s88, s77, s47
	global_load_lds_dwordx4 v[210:211], off
	v_lshl_add_u64 v[212:213], s[86:87], 0, v[146:147]
	s_mov_b32 m0, s88
	v_lshl_add_u64 v[214:215], s[86:87], 0, v[150:151]
	global_load_lds_dwordx4 v[212:213], off
	s_add_i32 m0, s88, 0x2000
	v_lshl_add_u64 v[216:217], s[42:43], 0, v[144:145]
	global_load_lds_dwordx4 v[214:215], off
	s_mov_b32 m0, s48
	v_lshl_add_u64 v[218:219], s[42:43], 0, v[148:149]
	global_load_lds_dwordx4 v[216:217], off
	s_mov_b32 m0, s49
	s_nop 0
	global_load_lds_dwordx4 v[218:219], off
	s_waitcnt vmcnt(8)
	s_waitcnt lgkmcnt(0)
	s_setprio 1
	s_barrier
	v_mfma_f32_16x16x32_bf16 v[92:95], v[128:131], v[176:179], v[92:95]
	v_mfma_f32_16x16x32_bf16 v[88:91], v[136:139], v[176:179], v[88:91]
	v_mfma_f32_16x16x32_bf16 v[84:87], v[128:131], v[184:187], v[84:87]
	v_mfma_f32_16x16x32_bf16 v[80:83], v[136:139], v[184:187], v[80:83]
	v_mfma_f32_16x16x32_bf16 v[76:79], v[128:131], v[192:195], v[76:79]
	v_mfma_f32_16x16x32_bf16 v[72:75], v[136:139], v[192:195], v[72:75]
	v_mfma_f32_16x16x32_bf16 v[68:71], v[128:131], v[200:203], v[68:71]
	v_mfma_f32_16x16x32_bf16 v[64:67], v[136:139], v[200:203], v[64:67]
	v_mfma_f32_16x16x32_bf16 v[92:95], v[132:135], v[180:183], v[92:95]
	v_mfma_f32_16x16x32_bf16 v[88:91], v[140:143], v[180:183], v[88:91]
	v_mfma_f32_16x16x32_bf16 v[84:87], v[132:135], v[188:191], v[84:87]
	v_mfma_f32_16x16x32_bf16 v[80:83], v[140:143], v[188:191], v[80:83]
	v_mfma_f32_16x16x32_bf16 v[76:79], v[132:135], v[196:199], v[76:79]
	v_mfma_f32_16x16x32_bf16 v[72:75], v[140:143], v[196:199], v[72:75]
	v_mfma_f32_16x16x32_bf16 v[68:71], v[132:135], v[204:207], v[68:71]
	v_mfma_f32_16x16x32_bf16 v[64:67], v[140:143], v[204:207], v[64:67]
	v_mfma_f32_16x16x32_bf16 v[28:31], v[160:163], v[176:179], v[28:31]
	v_mfma_f32_16x16x32_bf16 v[24:27], v[168:171], v[176:179], v[24:27]
	v_mfma_f32_16x16x32_bf16 v[20:23], v[160:163], v[184:187], v[20:23]
	v_mfma_f32_16x16x32_bf16 v[16:19], v[168:171], v[184:187], v[16:19]
	v_mfma_f32_16x16x32_bf16 v[12:15], v[160:163], v[192:195], v[12:15]
	v_mfma_f32_16x16x32_bf16 v[8:11], v[168:171], v[192:195], v[8:11]
	v_mfma_f32_16x16x32_bf16 v[4:7], v[160:163], v[200:203], v[4:7]
	v_mfma_f32_16x16x32_bf16 v[0:3], v[168:171], v[200:203], v[0:3]
	v_mfma_f32_16x16x32_bf16 v[28:31], v[164:167], v[180:183], v[28:31]
	v_mfma_f32_16x16x32_bf16 v[24:27], v[172:175], v[180:183], v[24:27]
	v_mfma_f32_16x16x32_bf16 v[20:23], v[164:167], v[188:191], v[20:23]
	v_mfma_f32_16x16x32_bf16 v[16:19], v[172:175], v[188:191], v[16:19]
	v_mfma_f32_16x16x32_bf16 v[12:15], v[164:167], v[196:199], v[12:15]
	v_mfma_f32_16x16x32_bf16 v[8:11], v[172:175], v[196:199], v[8:11]
	v_mfma_f32_16x16x32_bf16 v[4:7], v[164:167], v[204:207], v[4:7]
	v_mfma_f32_16x16x32_bf16 v[0:3], v[172:175], v[204:207], v[0:3]
	s_barrier
	s_setprio 0
	s_add_i32 s86, 0, 0x18000
	s_add_i32 s87, 0, 0x1c000
	v_add_u32_e32 v140, s86, v225
	v_add_u32_e32 v172, s87, v225
	v_xor_b32_e32 v255, 64, v140
	ds_read_b128 v[128:131], v140
	ds_read_b128 v[132:135], v255
	ds_read_b128 v[136:139], v140 offset:2048
	ds_read_b128 v[140:143], v255 offset:2048
	v_xor_b32_e32 v255, 64, v172
	ds_read_b128 v[160:163], v172
	ds_read_b128 v[164:167], v255
	ds_read_b128 v[168:171], v172 offset:2048
	ds_read_b128 v[172:175], v255 offset:2048
	s_add_u32 s42, s42, s10
	s_addc_u32 s43, s43, s11
	s_mov_b32 m0, s54
	v_lshl_add_u64 v[234:235], s[42:43], 0, v[144:145]
	ds_read_b128 v[176:179], v231 offset:32768
	ds_read_b128 v[180:183], v252 offset:32768
	ds_read_b128 v[184:187], v231 offset:34816
	ds_read_b128 v[188:191], v252 offset:34816
	ds_read_b128 v[192:195], v231 offset:36864
	ds_read_b128 v[196:199], v252 offset:36864
	ds_read_b128 v[200:203], v231 offset:38912
	ds_read_b128 v[204:207], v252 offset:38912
	global_load_lds_dwordx4 v[234:235], off
	v_lshl_add_u64 v[234:235], s[42:43], 0, v[148:149]
	s_mov_b32 m0, s55
	s_nop 0
	global_load_lds_dwordx4 v[234:235], off
	s_waitcnt vmcnt(8)
	s_waitcnt lgkmcnt(0)
	s_setprio 1
	s_barrier
	v_mfma_f32_16x16x32_bf16 v[124:127], v[128:131], v[176:179], v[124:127]
	v_mfma_f32_16x16x32_bf16 v[120:123], v[136:139], v[176:179], v[120:123]
	v_mfma_f32_16x16x32_bf16 v[116:119], v[128:131], v[184:187], v[116:119]
	v_mfma_f32_16x16x32_bf16 v[112:115], v[136:139], v[184:187], v[112:115]
	v_mfma_f32_16x16x32_bf16 v[108:111], v[128:131], v[192:195], v[108:111]
	v_mfma_f32_16x16x32_bf16 v[104:107], v[136:139], v[192:195], v[104:107]
	v_mfma_f32_16x16x32_bf16 v[100:103], v[128:131], v[200:203], v[100:103]
	v_mfma_f32_16x16x32_bf16 v[96:99], v[136:139], v[200:203], v[96:99]
	v_mfma_f32_16x16x32_bf16 v[124:127], v[132:135], v[180:183], v[124:127]
	v_mfma_f32_16x16x32_bf16 v[120:123], v[140:143], v[180:183], v[120:123]
	v_mfma_f32_16x16x32_bf16 v[116:119], v[132:135], v[188:191], v[116:119]
	v_mfma_f32_16x16x32_bf16 v[112:115], v[140:143], v[188:191], v[112:115]
	v_mfma_f32_16x16x32_bf16 v[108:111], v[132:135], v[196:199], v[108:111]
	v_mfma_f32_16x16x32_bf16 v[104:107], v[140:143], v[196:199], v[104:107]
	v_mfma_f32_16x16x32_bf16 v[100:103], v[132:135], v[204:207], v[100:103]
	v_mfma_f32_16x16x32_bf16 v[96:99], v[140:143], v[204:207], v[96:99]
	v_mfma_f32_16x16x32_bf16 v[60:63], v[160:163], v[176:179], v[60:63]
	v_mfma_f32_16x16x32_bf16 v[56:59], v[168:171], v[176:179], v[56:59]
	v_mfma_f32_16x16x32_bf16 v[52:55], v[160:163], v[184:187], v[52:55]
	v_mfma_f32_16x16x32_bf16 v[48:51], v[168:171], v[184:187], v[48:51]
	v_mfma_f32_16x16x32_bf16 v[44:47], v[160:163], v[192:195], v[44:47]
	v_mfma_f32_16x16x32_bf16 v[40:43], v[168:171], v[192:195], v[40:43]
	v_mfma_f32_16x16x32_bf16 v[36:39], v[160:163], v[200:203], v[36:39]
	v_mfma_f32_16x16x32_bf16 v[32:35], v[168:171], v[200:203], v[32:35]
	v_mfma_f32_16x16x32_bf16 v[60:63], v[164:167], v[180:183], v[60:63]
	v_mfma_f32_16x16x32_bf16 v[56:59], v[172:175], v[180:183], v[56:59]
	v_mfma_f32_16x16x32_bf16 v[52:55], v[164:167], v[188:191], v[52:55]
	v_mfma_f32_16x16x32_bf16 v[48:51], v[172:175], v[188:191], v[48:51]
	v_mfma_f32_16x16x32_bf16 v[44:47], v[164:167], v[196:199], v[44:47]
	v_mfma_f32_16x16x32_bf16 v[40:43], v[172:175], v[196:199], v[40:43]
	v_mfma_f32_16x16x32_bf16 v[36:39], v[164:167], v[204:207], v[36:39]
	v_mfma_f32_16x16x32_bf16 v[32:35], v[172:175], v[204:207], v[32:35]
	s_barrier
	s_setprio 0
	s_add_i32 s42, s86, s47
	v_lshl_add_u64 v[208:209], v[208:209], 0, s[26:27]
	s_mov_b32 m0, s42
	ds_read_b128 v[176:179], v231 offset:49152
	ds_read_b128 v[180:183], v252 offset:49152
	ds_read_b128 v[184:187], v231 offset:51200
	ds_read_b128 v[188:191], v252 offset:51200
	ds_read_b128 v[192:195], v231 offset:53248
	ds_read_b128 v[196:199], v252 offset:53248
	ds_read_b128 v[200:203], v231 offset:55296
	ds_read_b128 v[204:207], v252 offset:55296
	global_load_lds_dwordx4 v[208:209], off
	v_lshl_add_u64 v[208:209], v[210:211], 0, s[26:27]
	s_add_i32 m0, s42, 0x2000
	s_add_i32 s42, s87, s47
	global_load_lds_dwordx4 v[208:209], off
	v_lshl_add_u64 v[208:209], v[212:213], 0, s[26:27]
	s_mov_b32 m0, s42
	s_nop 0
	global_load_lds_dwordx4 v[208:209], off
	v_lshl_add_u64 v[208:209], v[214:215], 0, s[26:27]
	s_add_i32 m0, s42, 0x2000
	s_nop 0
	global_load_lds_dwordx4 v[208:209], off
	v_lshl_add_u64 v[208:209], v[216:217], 0, s[26:27]
	s_mov_b32 m0, s57
	s_nop 0
	global_load_lds_dwordx4 v[208:209], off
	v_lshl_add_u64 v[208:209], v[218:219], 0, s[26:27]
	s_mov_b32 m0, s58
	s_nop 0
	global_load_lds_dwordx4 v[208:209], off
	s_waitcnt vmcnt(8)
	s_waitcnt lgkmcnt(0)
	s_setprio 1
	s_barrier
	v_mfma_f32_16x16x32_bf16 v[92:95], v[128:131], v[176:179], v[92:95]
	v_mfma_f32_16x16x32_bf16 v[88:91], v[136:139], v[176:179], v[88:91]
	v_mfma_f32_16x16x32_bf16 v[84:87], v[128:131], v[184:187], v[84:87]
	v_mfma_f32_16x16x32_bf16 v[80:83], v[136:139], v[184:187], v[80:83]
	v_mfma_f32_16x16x32_bf16 v[76:79], v[128:131], v[192:195], v[76:79]
	v_mfma_f32_16x16x32_bf16 v[72:75], v[136:139], v[192:195], v[72:75]
	v_mfma_f32_16x16x32_bf16 v[68:71], v[128:131], v[200:203], v[68:71]
	v_mfma_f32_16x16x32_bf16 v[64:67], v[136:139], v[200:203], v[64:67]
	v_mfma_f32_16x16x32_bf16 v[92:95], v[132:135], v[180:183], v[92:95]
	v_mfma_f32_16x16x32_bf16 v[88:91], v[140:143], v[180:183], v[88:91]
	v_mfma_f32_16x16x32_bf16 v[84:87], v[132:135], v[188:191], v[84:87]
	v_mfma_f32_16x16x32_bf16 v[80:83], v[140:143], v[188:191], v[80:83]
	v_mfma_f32_16x16x32_bf16 v[76:79], v[132:135], v[196:199], v[76:79]
	v_mfma_f32_16x16x32_bf16 v[72:75], v[140:143], v[196:199], v[72:75]
	v_mfma_f32_16x16x32_bf16 v[68:71], v[132:135], v[204:207], v[68:71]
	v_mfma_f32_16x16x32_bf16 v[64:67], v[140:143], v[204:207], v[64:67]
	v_mfma_f32_16x16x32_bf16 v[28:31], v[160:163], v[176:179], v[28:31]
	v_mfma_f32_16x16x32_bf16 v[24:27], v[168:171], v[176:179], v[24:27]
	v_mfma_f32_16x16x32_bf16 v[20:23], v[160:163], v[184:187], v[20:23]
	v_mfma_f32_16x16x32_bf16 v[16:19], v[168:171], v[184:187], v[16:19]
	v_mfma_f32_16x16x32_bf16 v[12:15], v[160:163], v[192:195], v[12:15]
	v_mfma_f32_16x16x32_bf16 v[8:11], v[168:171], v[192:195], v[8:11]
	v_mfma_f32_16x16x32_bf16 v[4:7], v[160:163], v[200:203], v[4:7]
	v_mfma_f32_16x16x32_bf16 v[0:3], v[168:171], v[200:203], v[0:3]
	v_mfma_f32_16x16x32_bf16 v[28:31], v[164:167], v[180:183], v[28:31]
	v_mfma_f32_16x16x32_bf16 v[24:27], v[172:175], v[180:183], v[24:27]
	v_mfma_f32_16x16x32_bf16 v[20:23], v[164:167], v[188:191], v[20:23]
	v_mfma_f32_16x16x32_bf16 v[16:19], v[172:175], v[188:191], v[16:19]
	v_mfma_f32_16x16x32_bf16 v[12:15], v[164:167], v[196:199], v[12:15]
	v_mfma_f32_16x16x32_bf16 v[8:11], v[172:175], v[196:199], v[8:11]
	v_mfma_f32_16x16x32_bf16 v[4:7], v[164:167], v[204:207], v[4:7]
	v_mfma_f32_16x16x32_bf16 v[0:3], v[172:175], v[204:207], v[0:3]
	s_barrier
	s_setprio 0
	s_add_u32 s0, s0, 0x100
	s_addc_u32 s1, s1, 0
	s_add_u32 s44, s44, 0x100
	s_addc_u32 s45, s45, 0
	s_cmp_ge_i32 s85, s59
	s_mov_b32 s42, s85
	s_cbranch_scc0 .LBB0_855

.LBB0_938:
	s_add_u32 s77, s74, 0x17d00000
	s_addc_u32 s78, s75, 0
	s_add_u32 s47, s74, 0x18d00000
	s_addc_u32 s76, s75, 0
	s_add_u32 s20, s74, 0x1fbc0000
	s_addc_u32 s21, s75, 0
	s_andn2_b64 vcc, exec, s[6:7]
	s_cbranch_vccnz .LBB0_999
	v_bfe_i32 v2, v12, 27, 1
	v_lshlrev_b32_e32 v0, 4, v12
	v_lshrrev_b32_e32 v2, 22, v2
	v_add_u32_e32 v2, v0, v2
	v_and_b32_e32 v2, 0xfffffc00, v2
	v_sub_u32_e32 v2, v0, v2
	v_ashrrev_i32_e32 v1, 31, v12
	v_lshrrev_b32_e32 v3, 4, v2
	v_lshrrev_b32_e32 v1, 26, v1
	v_bitop3_b32 v2, v3, v2, 32 bitop3:0x6c
	v_add_u32_e32 v1, v12, v1
	v_ashrrev_i32_e32 v4, 31, v2
	v_ashrrev_i32_e32 v1, 6, v1
	v_lshrrev_b32_e32 v4, 26, v4
	v_lshlrev_b32_e32 v3, 3, v1
	v_add_u32_e32 v4, v2, v4
	v_and_b32_e32 v3, -16, v3
	v_ashrrev_i32_e32 v5, 6, v4
	v_lshlrev_b32_e32 v1, 5, v1
	v_add_u32_e32 v3, v5, v3
	v_and_b32_e32 v13, 32, v1
	v_and_b32_e32 v1, 0xc0, v4
	v_sub_u32_e32 v1, v2, v1
	v_mov_b32_e32 v2, 1
	v_lshlrev_b32_e32 v4, 1, v3
	v_lshrrev_b32_e32 v6, 2, v3
	v_and_b32_e32 v5, 3, v5
	s_mov_b32 s1, 0x7fffffe0
	v_ashrrev_i16_sdwa v1, v2, sext(v1) dst_sel:DWORD dst_unused:UNUSED_PAD src0_sel:DWORD src1_sel:BYTE_0
	v_and_b32_e32 v4, 24, v4
	v_and_b32_e32 v6, 4, v6
	v_and_or_b32 v5, v3, s1, v5
	v_bfe_i32 v14, v1, 0, 16
	v_or3_b32 v4, v5, v6, v4
	v_add_u32_e32 v1, v13, v14
	v_mul_lo_u32 v15, v3, s0
	v_mul_lo_u32 v3, v4, s0
	v_add_u32_e32 v0, 0x2000, v0
	v_lshrrev_b32_e32 v252, 3, v220
	v_bfe_u32 v253, v220, 4, 2
	v_bfe_u32 v254, v220, 6, 1
	v_lshl_or_b32 v253, v254, 2, v253
	v_and_b32_e32 v254, 7, v220
	v_xor_b32_e32 v253, v254, v253
	v_lshlrev_b32_e32 v253, 4, v253
	v_and_b32_e32 v254, 32, v252
	v_bfe_u32 v255, v252, 2, 2
	v_lshl_or_b32 v254, v255, 3, v254
	v_bfe_u32 v255, v252, 4, 1
	v_lshl_or_b32 v254, v255, 2, v254
	v_and_b32_e32 v255, 3, v252
	v_or_b32_e32 v254, v254, v255
	v_mul_u32_u24_e32 v254, 0x1000, v254
	v_add_u32_e32 v254, v254, v253
	v_add_u32_e32 v255, 0x40000, v254
	v_mul_u32_u24_e32 v252, 0x1000, v252
	v_add_u32_e32 v252, v252, v253
	v_add_u32_e32 v253, 0x40000, v252
	v_mov_b32_e32 v128, v252
	v_mov_b32_e32 v130, v254
	v_ashrrev_i32_e32 v1, 31, v0
	v_lshrrev_b32_e32 v1, 22, v1
	v_add_u32_e32 v1, v0, v1
	v_ashrrev_i32_e32 v1, 10, v1
	v_mul_i32_i24_e32 v3, 0x400, v1
	v_sub_u32_e32 v0, v0, v3
	v_lshrrev_b32_e32 v3, 4, v0
	v_bitop3_b32 v0, v3, v0, 32 bitop3:0x6c
	v_ashrrev_i32_e32 v4, 31, v0
	v_lshrrev_b32_e32 v4, 26, v4
	v_lshlrev_b32_e32 v3, 3, v1
	v_add_u32_e32 v4, v0, v4
	v_and_b32_e32 v3, -16, v3
	v_ashrrev_i32_e32 v5, 6, v4
	v_lshlrev_b32_e32 v1, 5, v1
	s_add_u32 s43, s74, 0x6700000
	v_add_u32_e32 v3, v5, v3
	v_and_b32_e32 v16, 32, v1
	v_and_b32_e32 v1, 0xc0, v4
	v_and_b32_e32 v4, 3, v5
	s_addc_u32 s56, s75, 0
	v_and_or_b32 v4, v3, s1, v4
	s_ashr_i32 s1, s0, 31
	s_lshl_b64 s[24:25], s[0:1], 9
	s_ashr_i32 s8, s94, 31
	s_mul_i32 s8, s24, s8
	s_mul_hi_u32 s9, s24, s94
	s_add_i32 s10, s9, s8
	s_lshr_b64 s[8:9], s[0:1], 23
	s_mul_i32 s9, s8, s94
	s_add_i32 s26, s10, s9
	s_ashr_i32 s9, s93, 31
	s_mul_i32 s9, s24, s9
	s_mul_hi_u32 s10, s24, s93
	s_ashr_i32 s6, s38, 6
	s_add_i32 s9, s10, s9
	s_mul_i32 s8, s8, s93
	v_sub_u32_e32 v0, v0, v1
	s_ashr_i32 s7, s38, 8
	s_lshl_b64 s[22:23], s[0:1], 8
	s_lshl_b32 s57, s6, 10
	s_add_i32 s9, s9, s8
	s_mul_i32 s8, s24, s93
	v_ashrrev_i16_sdwa v0, v2, sext(v0) dst_sel:DWORD dst_unused:UNUSED_PAD src0_sel:DWORD src1_sel:BYTE_0
	v_lshlrev_b32_e32 v1, 1, v3
	v_lshrrev_b32_e32 v2, 2, v3
	s_add_u32 s10, s43, s8
	v_and_b32_e32 v1, 24, v1
	v_and_b32_e32 v2, 4, v2
	s_addc_u32 s11, s56, s9
	s_add_i32 s58, s57, 0
	v_bfe_i32 v17, v0, 0, 16
	v_or3_b32 v1, v4, v2, v1
	s_add_i32 m0, s58, 0x10000
	v_add_u32_e32 v0, v16, v17
	v_mul_lo_u32 v1, v1, s0
	global_load_lds_dwordx4 v130, s[10:11]
	s_add_i32 m0, s58, 0x12000
	v_mov_b32_e32 v134, v255
	s_add_u32 s8, s10, s22
	global_load_lds_dwordx4 v134, s[10:11]
	s_addc_u32 s9, s11, s23
	s_add_i32 m0, s58, 0x14000
	s_mul_i32 s27, s24, s94
	global_load_lds_dwordx4 v130, s[8:9]
	s_add_i32 m0, s58, 0x16000
	s_add_u32 s44, s16, s27
	s_addc_u32 s45, s17, s26
	s_add_i32 s59, s58, 0x2000
	v_mul_lo_u32 v18, v3, s0
	global_load_lds_dwordx4 v134, s[8:9]
	s_mov_b32 m0, s58
	s_add_u32 s26, s44, s22
	v_mov_b32_e32 v132, v253
	global_load_lds_dwordx4 v128, s[44:45]
	s_mov_b32 m0, s59
	s_addc_u32 s27, s45, s23
	s_add_i32 s60, s58, 0x4000
	global_load_lds_dwordx4 v132, s[44:45]
	s_mov_b32 m0, s60
	s_add_i32 s61, s58, 0x6000
	global_load_lds_dwordx4 v128, s[26:27]
	s_mov_b32 m0, s61
	v_mov_b32_e32 v131, 0
	global_load_lds_dwordx4 v132, s[26:27]
	v_mov_b32_e32 v135, v131
	v_mov_b32_e32 v129, v131
	v_mov_b32_e32 v133, v131
	s_cmp_eq_u32 s7, 1
	s_mov_b32 s62, 0
	v_lshl_add_u64 v[8:9], s[10:11], 0, v[130:131]
	v_lshl_add_u64 v[4:5], s[10:11], 0, v[134:135]
	v_lshl_add_u64 v[2:3], s[8:9], 0, v[130:131]
	v_lshl_add_u64 v[0:1], s[8:9], 0, v[134:135]
	v_lshl_add_u64 v[6:7], s[44:45], 0, v[128:129]
	s_cselect_b64 s[26:27], -1, 0
	s_cmp_lg_u32 s7, 1
	v_lshl_add_u64 v[10:11], s[44:45], 0, v[132:133]
	s_cbranch_scc1 .LBB0_941
	s_barrier
.LBB0_941:
	s_add_u32 s28, s74, 0x1fb14000
	s_addc_u32 s29, s75, 0
	s_add_u32 s30, s74, 0x1fb15400
	s_mov_b64 s[34:35], 0x80
	s_addc_u32 s31, s75, 0
	s_add_i32 m0, s58, 0x18000
	v_lshl_add_u64 v[8:9], v[8:9], 0, s[34:35]
	s_waitcnt vmcnt(2)
	s_barrier
	global_load_lds_dwordx4 v[8:9], off
	v_lshl_add_u64 v[4:5], v[4:5], 0, s[34:35]
	s_add_i32 m0, s58, 0x1a000
	s_add_i32 s63, s58, 0x8000
	global_load_lds_dwordx4 v[4:5], off
	v_lshl_add_u64 v[4:5], v[6:7], 0, s[34:35]
	s_mov_b32 m0, s63
	s_add_i32 s79, s58, 0xa000
	global_load_lds_dwordx4 v[4:5], off
	v_lshl_add_u64 v[4:5], v[10:11], 0, s[34:35]
	s_mov_b32 m0, s79
	v_lshl_add_u64 v[2:3], v[2:3], 0, s[34:35]
	global_load_lds_dwordx4 v[4:5], off
	s_add_i32 m0, s58, 0x1c000
	v_lshl_add_u64 v[0:1], v[0:1], 0, s[34:35]
	global_load_lds_dwordx4 v[2:3], off
	s_add_i32 m0, s58, 0x1e000
	s_lshr_b32 s1, s1, 26
	global_load_lds_dwordx4 v[0:1], off
	v_bfe_u32 v0, v12, 4, 2
	v_and_b32_e32 v1, 15, v12
	v_lshlrev_b32_e32 v3, 4, v0
	s_add_i32 s1, s0, s1
	v_lshl_or_b32 v163, s7, 6, v1
	v_lshl_or_b32 v1, v1, 6, v3
	v_lshlrev_b32_e32 v3, 2, v12
	s_and_b32 s6, s6, 3
	s_ashr_i32 s80, s1, 6
	s_lshl_b32 s1, s7, 13
	v_and_b32_e32 v3, 32, v3
	v_bitop3_b32 v4, v1, s1, v3 bitop3:0xde
	s_lshl_b32 s1, s6, 12
	s_cmp_gt_i32 s0, 63
	v_lshlrev_b32_e32 v2, 3, v0
	s_cselect_b64 s[36:37], -1, 0
	s_add_i32 s81, s80, -2
	s_cmpk_lt_u32 s38, 0x100
	v_lshl_or_b32 v165, s6, 5, v2
	v_and_b32_e32 v252, 15, v220
	v_bfe_u32 v253, v220, 4, 2
	v_bfe_u32 v254, v252, 1, 2
	v_xor_b32_e32 v253, v253, v254
	v_bfe_u32 v254, v252, 3, 1
	v_lshl_or_b32 v253, v254, 2, v253
	v_lshlrev_b32_e32 v253, 4, v253
	v_lshl_or_b32 v253, v252, 7, v253
	v_lshrrev_b32_e32 v254, 6, v220
	v_lshrrev_b32_e32 v255, 2, v254
	v_lshl_or_b32 v252, v255, 13, v253
	v_and_b32_e32 v254, 3, v254
	v_lshl_or_b32 v253, v254, 12, v253
	v_mov_b32_e32 v164, v253
	s_cselect_b64 s[38:39], -1, 0
	s_cmp_lt_u32 s6, 2
	v_cmp_eq_u32_e64 s[6:7], 0, v0
	v_readlane_b32 s0, v251, 1
	v_lshlrev_b32_e32 v0, 1, v165
	v_mov_b32_e32 v1, v131
	v_readlane_b32 s1, v251, 2
	v_lshl_add_u64 v[136:137], s[50:51], 0, v[0:1]
	v_lshlrev_b32_e32 v0, 2, v165
	s_cselect_b64 s[40:41], -1, 0
	s_ashr_i32 s82, s0, 31
	s_mov_b32 s83, s0
	v_lshl_add_u64 v[0:1], s[74:75], 0, v[0:1]
	s_mov_b64 s[0:1], 0x1fb15000
	v_lshl_add_u64 v[138:139], v[0:1], 0, s[0:1]
	s_mov_b64 s[0:1], 0x1fb16400
	v_lshl_add_u64 v[140:141], v[0:1], 0, s[0:1]
	v_xor_b32_e32 v0, 16, v221
	v_cmp_lt_i32_e32 vcc, v0, v162
	v_mov_b32_e32 v1, v131
	s_waitcnt vmcnt(6)
	s_add_i32 s84, 0, 0x10000
	v_cndmask_b32_e32 v0, v221, v0, vcc
	v_lshlrev_b32_e32 v167, 2, v0
	v_xor_b32_e32 v0, 32, v221
	v_cmp_lt_i32_e32 vcc, v0, v162
	s_add_i32 s85, 0, 0x14000
	v_lshrrev_b32_e32 v166, 1, v165
	v_cndmask_b32_e32 v0, v221, v0, vcc
	v_lshlrev_b32_e32 v168, 2, v0
	v_add_u32_e32 v0, v15, v13
	v_mov_b32_e32 v0, v128
	v_lshl_add_u64 v[142:143], s[22:23], 0, v[0:1]
	v_add_u32_e32 v0, v18, v16
	v_mov_b32_e32 v0, v132
	v_lshl_add_u64 v[144:145], s[22:23], 0, v[0:1]
	v_mov_b64_e32 v[146:147], 0x100
	v_mov_b64_e32 v[148:149], 0xff
	v_add_u32_e32 v169, s84, v164
	v_add_u32_e32 v170, s85, v164
	v_mov_b32_e32 v171, v252
	v_xor_b32_e32 v252, 64, v171
	v_xor_b32_e32 v253, 64, v169
	v_xor_b32_e32 v254, 64, v170
	s_mov_b32 s42, 0x3a000000
	s_mov_b32 s86, 0xf800000
	v_mov_b32_e32 v172, 0x260
	s_mov_b32 s87, 0xf9e0
	s_mov_b32 s88, 0xfbe0
	s_mov_b32 s89, 0xfde0
	s_mov_b32 s90, 0xffe0
	s_barrier
	s_branch .LBB0_944

.LBB0_956:
	ds_read_b128 v[150:153], v169
	ds_read_b128 v[154:157], v253
	ds_read_b128 v[158:161], v169 offset:2048
	ds_read_b128 v[174:177], v253 offset:2048
	ds_read_b128 v[178:181], v170
	ds_read_b128 v[182:185], v254
	ds_read_b128 v[186:189], v170 offset:2048
	ds_read_b128 v[190:193], v254 offset:2048
	s_add_i32 s95, s10, 2
	s_add_u32 s96, s0, 0x80
	s_addc_u32 s11, s1, 0
	s_cmp_eq_u32 s81, s10
	s_cselect_b32 s10, s48, s96
	s_cselect_b32 s11, s49, s11
	s_cselect_b32 s97, s55, s45
	s_cselect_b32 s96, s54, s44
	v_lshl_add_u64 v[218:219], s[0:1], 0, v[142:143]
	s_add_i32 m0, s58, 0xc000
	ds_read_b128 v[194:197], v171
	ds_read_b128 v[198:201], v252
	ds_read_b128 v[202:205], v171 offset:2048
	ds_read_b128 v[206:209], v252 offset:2048
	ds_read_b128 v[210:213], v171 offset:4096
	ds_read_b128 v[214:217], v252 offset:4096
	ds_read_b128 v[222:225], v171 offset:6144
	ds_read_b128 v[226:229], v252 offset:6144
	global_load_lds_dwordx4 v[218:219], off
	v_lshl_add_u64 v[218:219], s[0:1], 0, v[144:145]
	s_add_i32 m0, s58, 0xe000
	s_nop 0
	global_load_lds_dwordx4 v[218:219], off
	s_waitcnt vmcnt(8)
	s_waitcnt lgkmcnt(0)
	s_setprio 1
	s_barrier
	v_mfma_f32_16x16x32_bf16 v[120:123], v[150:153], v[194:197], v[120:123]
	v_mfma_f32_16x16x32_bf16 v[124:127], v[158:161], v[194:197], v[124:127]
	v_mfma_f32_16x16x32_bf16 v[108:111], v[150:153], v[202:205], v[108:111]
	v_mfma_f32_16x16x32_bf16 v[104:107], v[158:161], v[202:205], v[104:107]
	v_mfma_f32_16x16x32_bf16 v[92:95], v[150:153], v[210:213], v[92:95]
	v_mfma_f32_16x16x32_bf16 v[88:91], v[158:161], v[210:213], v[88:91]
	v_mfma_f32_16x16x32_bf16 v[76:79], v[150:153], v[222:225], v[76:79]
	v_mfma_f32_16x16x32_bf16 v[72:75], v[158:161], v[222:225], v[72:75]
	v_mfma_f32_16x16x32_bf16 v[120:123], v[154:157], v[198:201], v[120:123]
	v_mfma_f32_16x16x32_bf16 v[124:127], v[174:177], v[198:201], v[124:127]
	v_mfma_f32_16x16x32_bf16 v[108:111], v[154:157], v[206:209], v[108:111]
	v_mfma_f32_16x16x32_bf16 v[104:107], v[174:177], v[206:209], v[104:107]
	v_mfma_f32_16x16x32_bf16 v[92:95], v[154:157], v[214:217], v[92:95]
	v_mfma_f32_16x16x32_bf16 v[88:91], v[174:177], v[214:217], v[88:91]
	v_mfma_f32_16x16x32_bf16 v[76:79], v[154:157], v[226:229], v[76:79]
	v_mfma_f32_16x16x32_bf16 v[72:75], v[174:177], v[226:229], v[72:75]
	v_mfma_f32_16x16x32_bf16 v[116:119], v[178:181], v[194:197], v[116:119]
	v_mfma_f32_16x16x32_bf16 v[112:115], v[186:189], v[194:197], v[112:115]
	v_mfma_f32_16x16x32_bf16 v[100:103], v[178:181], v[202:205], v[100:103]
	v_mfma_f32_16x16x32_bf16 v[96:99], v[186:189], v[202:205], v[96:99]
	v_mfma_f32_16x16x32_bf16 v[84:87], v[178:181], v[210:213], v[84:87]
	v_mfma_f32_16x16x32_bf16 v[80:83], v[186:189], v[210:213], v[80:83]
	v_mfma_f32_16x16x32_bf16 v[68:71], v[178:181], v[222:225], v[68:71]
	v_mfma_f32_16x16x32_bf16 v[64:67], v[186:189], v[222:225], v[64:67]
	v_mfma_f32_16x16x32_bf16 v[116:119], v[182:185], v[198:201], v[116:119]
	v_mfma_f32_16x16x32_bf16 v[112:115], v[190:193], v[198:201], v[112:115]
	v_mfma_f32_16x16x32_bf16 v[100:103], v[182:185], v[206:209], v[100:103]
	v_mfma_f32_16x16x32_bf16 v[96:99], v[190:193], v[206:209], v[96:99]
	v_mfma_f32_16x16x32_bf16 v[84:87], v[182:185], v[214:217], v[84:87]
	v_mfma_f32_16x16x32_bf16 v[80:83], v[190:193], v[214:217], v[80:83]
	v_mfma_f32_16x16x32_bf16 v[68:71], v[182:185], v[226:229], v[68:71]
	v_mfma_f32_16x16x32_bf16 v[64:67], v[190:193], v[226:229], v[64:67]
	s_barrier
	s_setprio 0
	s_add_i32 vcc_lo, s84, s57
	v_lshl_add_u64 v[218:219], s[96:97], 0, v[130:131]
	s_mov_b32 m0, vcc_lo
	ds_read_b128 v[194:197], v171 offset:16384
	ds_read_b128 v[198:201], v252 offset:16384
	ds_read_b128 v[202:205], v171 offset:18432
	ds_read_b128 v[206:209], v252 offset:18432
	ds_read_b128 v[210:213], v171 offset:20480
	ds_read_b128 v[214:217], v252 offset:20480
	ds_read_b128 v[222:225], v171 offset:22528
	ds_read_b128 v[226:229], v252 offset:22528
	global_load_lds_dwordx4 v[218:219], off
	s_add_i32 m0, vcc_lo, 0x2000
	v_lshl_add_u64 v[230:231], s[96:97], 0, v[134:135]
	s_add_u32 s96, s96, s22
	s_addc_u32 s97, s97, s23
	s_add_i32 vcc_lo, s85, s57
	global_load_lds_dwordx4 v[230:231], off
	v_lshl_add_u64 v[232:233], s[96:97], 0, v[130:131]
	s_mov_b32 m0, vcc_lo
	v_lshl_add_u64 v[234:235], s[96:97], 0, v[134:135]
	global_load_lds_dwordx4 v[232:233], off
	s_add_i32 m0, vcc_lo, 0x2000
	v_lshl_add_u64 v[236:237], s[10:11], 0, v[128:129]
	global_load_lds_dwordx4 v[234:235], off
	s_mov_b32 m0, s58
	v_lshl_add_u64 v[238:239], s[10:11], 0, v[132:133]
	global_load_lds_dwordx4 v[236:237], off
	s_mov_b32 m0, s59
	s_nop 0
	global_load_lds_dwordx4 v[238:239], off
	s_waitcnt vmcnt(8)
	s_waitcnt lgkmcnt(0)
	s_setprio 1
	s_barrier
	v_mfma_f32_16x16x32_bf16 v[60:63], v[150:153], v[194:197], v[60:63]
	v_mfma_f32_16x16x32_bf16 v[56:59], v[158:161], v[194:197], v[56:59]
	v_mfma_f32_16x16x32_bf16 v[44:47], v[150:153], v[202:205], v[44:47]
	v_mfma_f32_16x16x32_bf16 v[40:43], v[158:161], v[202:205], v[40:43]
	v_mfma_f32_16x16x32_bf16 v[28:31], v[150:153], v[210:213], v[28:31]
	v_mfma_f32_16x16x32_bf16 v[24:27], v[158:161], v[210:213], v[24:27]
	v_mfma_f32_16x16x32_bf16 v[12:15], v[150:153], v[222:225], v[12:15]
	v_mfma_f32_16x16x32_bf16 v[8:11], v[158:161], v[222:225], v[8:11]
	v_mfma_f32_16x16x32_bf16 v[60:63], v[154:157], v[198:201], v[60:63]
	v_mfma_f32_16x16x32_bf16 v[56:59], v[174:177], v[198:201], v[56:59]
	v_mfma_f32_16x16x32_bf16 v[44:47], v[154:157], v[206:209], v[44:47]
	v_mfma_f32_16x16x32_bf16 v[40:43], v[174:177], v[206:209], v[40:43]
	v_mfma_f32_16x16x32_bf16 v[28:31], v[154:157], v[214:217], v[28:31]
	v_mfma_f32_16x16x32_bf16 v[24:27], v[174:177], v[214:217], v[24:27]
	v_mfma_f32_16x16x32_bf16 v[12:15], v[154:157], v[226:229], v[12:15]
	v_mfma_f32_16x16x32_bf16 v[8:11], v[174:177], v[226:229], v[8:11]
	v_mfma_f32_16x16x32_bf16 v[52:55], v[178:181], v[194:197], v[52:55]
	v_mfma_f32_16x16x32_bf16 v[48:51], v[186:189], v[194:197], v[48:51]
	v_mfma_f32_16x16x32_bf16 v[36:39], v[178:181], v[202:205], v[36:39]
	v_mfma_f32_16x16x32_bf16 v[32:35], v[186:189], v[202:205], v[32:35]
	v_mfma_f32_16x16x32_bf16 v[20:23], v[178:181], v[210:213], v[20:23]
	v_mfma_f32_16x16x32_bf16 v[16:19], v[186:189], v[210:213], v[16:19]
	v_mfma_f32_16x16x32_bf16 v[4:7], v[178:181], v[222:225], v[4:7]
	v_mfma_f32_16x16x32_bf16 v[0:3], v[186:189], v[222:225], v[0:3]
	v_mfma_f32_16x16x32_bf16 v[52:55], v[182:185], v[198:201], v[52:55]
	v_mfma_f32_16x16x32_bf16 v[48:51], v[190:193], v[198:201], v[48:51]
	v_mfma_f32_16x16x32_bf16 v[36:39], v[182:185], v[206:209], v[36:39]
	v_mfma_f32_16x16x32_bf16 v[32:35], v[190:193], v[206:209], v[32:35]
	v_mfma_f32_16x16x32_bf16 v[20:23], v[182:185], v[214:217], v[20:23]
	v_mfma_f32_16x16x32_bf16 v[16:19], v[190:193], v[214:217], v[16:19]
	v_mfma_f32_16x16x32_bf16 v[4:7], v[182:185], v[226:229], v[4:7]
	v_mfma_f32_16x16x32_bf16 v[0:3], v[190:193], v[226:229], v[0:3]
	s_barrier
	s_setprio 0
	s_add_i32 s96, 0, 0x18000
	v_add_u32_e32 v173, s96, v164
	s_add_i32 s97, 0, 0x1c000
	v_xor_b32_e32 v255, 64, v173
	ds_read_b128 v[150:153], v173
	ds_read_b128 v[154:157], v255
	ds_read_b128 v[158:161], v173 offset:2048
	ds_read_b128 v[174:177], v255 offset:2048
	v_add_u32_e32 v173, s97, v164
	v_xor_b32_e32 v255, 64, v173
	ds_read_b128 v[178:181], v173
	ds_read_b128 v[182:185], v255
	ds_read_b128 v[186:189], v173 offset:2048
	ds_read_b128 v[190:193], v255 offset:2048
	s_add_u32 s10, s10, s22
	s_addc_u32 s11, s11, s23
	s_mov_b32 m0, s60
	v_lshl_add_u64 v[240:241], s[10:11], 0, v[128:129]
	ds_read_b128 v[194:197], v171 offset:32768
	ds_read_b128 v[198:201], v252 offset:32768
	ds_read_b128 v[202:205], v171 offset:34816
	ds_read_b128 v[206:209], v252 offset:34816
	ds_read_b128 v[210:213], v171 offset:36864
	ds_read_b128 v[214:217], v252 offset:36864
	ds_read_b128 v[222:225], v171 offset:38912
	ds_read_b128 v[226:229], v252 offset:38912
	global_load_lds_dwordx4 v[240:241], off
	v_lshl_add_u64 v[240:241], s[10:11], 0, v[132:133]
	s_mov_b32 m0, s61
	s_nop 0
	global_load_lds_dwordx4 v[240:241], off
	s_waitcnt vmcnt(8)
	s_waitcnt lgkmcnt(0)
	s_setprio 1
	s_barrier
	v_mfma_f32_16x16x32_bf16 v[120:123], v[150:153], v[194:197], v[120:123]
	v_mfma_f32_16x16x32_bf16 v[124:127], v[158:161], v[194:197], v[124:127]
	v_mfma_f32_16x16x32_bf16 v[108:111], v[150:153], v[202:205], v[108:111]
	v_mfma_f32_16x16x32_bf16 v[104:107], v[158:161], v[202:205], v[104:107]
	v_mfma_f32_16x16x32_bf16 v[92:95], v[150:153], v[210:213], v[92:95]
	v_mfma_f32_16x16x32_bf16 v[88:91], v[158:161], v[210:213], v[88:91]
	v_mfma_f32_16x16x32_bf16 v[76:79], v[150:153], v[222:225], v[76:79]
	v_mfma_f32_16x16x32_bf16 v[72:75], v[158:161], v[222:225], v[72:75]
	v_mfma_f32_16x16x32_bf16 v[120:123], v[154:157], v[198:201], v[120:123]
	v_mfma_f32_16x16x32_bf16 v[124:127], v[174:177], v[198:201], v[124:127]
	v_mfma_f32_16x16x32_bf16 v[108:111], v[154:157], v[206:209], v[108:111]
	v_mfma_f32_16x16x32_bf16 v[104:107], v[174:177], v[206:209], v[104:107]
	v_mfma_f32_16x16x32_bf16 v[92:95], v[154:157], v[214:217], v[92:95]
	v_mfma_f32_16x16x32_bf16 v[88:91], v[174:177], v[214:217], v[88:91]
	v_mfma_f32_16x16x32_bf16 v[76:79], v[154:157], v[226:229], v[76:79]
	v_mfma_f32_16x16x32_bf16 v[72:75], v[174:177], v[226:229], v[72:75]
	v_mfma_f32_16x16x32_bf16 v[116:119], v[178:181], v[194:197], v[116:119]
	v_mfma_f32_16x16x32_bf16 v[112:115], v[186:189], v[194:197], v[112:115]
	v_mfma_f32_16x16x32_bf16 v[100:103], v[178:181], v[202:205], v[100:103]
	v_mfma_f32_16x16x32_bf16 v[96:99], v[186:189], v[202:205], v[96:99]
	v_mfma_f32_16x16x32_bf16 v[84:87], v[178:181], v[210:213], v[84:87]
	v_mfma_f32_16x16x32_bf16 v[80:83], v[186:189], v[210:213], v[80:83]
	v_mfma_f32_16x16x32_bf16 v[68:71], v[178:181], v[222:225], v[68:71]
	v_mfma_f32_16x16x32_bf16 v[64:67], v[186:189], v[222:225], v[64:67]
	v_mfma_f32_16x16x32_bf16 v[116:119], v[182:185], v[198:201], v[116:119]
	v_mfma_f32_16x16x32_bf16 v[112:115], v[190:193], v[198:201], v[112:115]
	v_mfma_f32_16x16x32_bf16 v[100:103], v[182:185], v[206:209], v[100:103]
	v_mfma_f32_16x16x32_bf16 v[96:99], v[190:193], v[206:209], v[96:99]
	v_mfma_f32_16x16x32_bf16 v[84:87], v[182:185], v[214:217], v[84:87]
	v_mfma_f32_16x16x32_bf16 v[80:83], v[190:193], v[214:217], v[80:83]
	v_mfma_f32_16x16x32_bf16 v[68:71], v[182:185], v[226:229], v[68:71]
	v_mfma_f32_16x16x32_bf16 v[64:67], v[190:193], v[226:229], v[64:67]
	s_barrier
	s_setprio 0
	s_add_i32 s10, s96, s57
	v_lshl_add_u64 v[218:219], v[218:219], 0, s[34:35]
	s_mov_b32 m0, s10
	ds_read_b128 v[194:197], v171 offset:49152
	ds_read_b128 v[198:201], v252 offset:49152
	ds_read_b128 v[202:205], v171 offset:51200
	ds_read_b128 v[206:209], v252 offset:51200
	ds_read_b128 v[210:213], v171 offset:53248
	ds_read_b128 v[214:217], v252 offset:53248
	ds_read_b128 v[222:225], v171 offset:55296
	ds_read_b128 v[226:229], v252 offset:55296
	global_load_lds_dwordx4 v[218:219], off
	v_lshl_add_u64 v[218:219], v[230:231], 0, s[34:35]
	s_add_i32 m0, s10, 0x2000
	s_add_i32 s10, s97, s57
	global_load_lds_dwordx4 v[218:219], off
	v_lshl_add_u64 v[218:219], v[232:233], 0, s[34:35]
	s_mov_b32 m0, s10
	s_nop 0
	global_load_lds_dwordx4 v[218:219], off
	v_lshl_add_u64 v[218:219], v[234:235], 0, s[34:35]
	s_add_i32 m0, s10, 0x2000
	s_nop 0
	global_load_lds_dwordx4 v[218:219], off
	v_lshl_add_u64 v[218:219], v[236:237], 0, s[34:35]
	s_mov_b32 m0, s63
	s_nop 0
	global_load_lds_dwordx4 v[218:219], off
	v_lshl_add_u64 v[218:219], v[238:239], 0, s[34:35]
	s_mov_b32 m0, s79
	s_nop 0
	global_load_lds_dwordx4 v[218:219], off
	s_waitcnt vmcnt(8)
	s_waitcnt lgkmcnt(0)
	s_setprio 1
	s_barrier
	v_mfma_f32_16x16x32_bf16 v[60:63], v[150:153], v[194:197], v[60:63]
	v_mfma_f32_16x16x32_bf16 v[56:59], v[158:161], v[194:197], v[56:59]
	v_mfma_f32_16x16x32_bf16 v[44:47], v[150:153], v[202:205], v[44:47]
	v_mfma_f32_16x16x32_bf16 v[40:43], v[158:161], v[202:205], v[40:43]
	v_mfma_f32_16x16x32_bf16 v[28:31], v[150:153], v[210:213], v[28:31]
	v_mfma_f32_16x16x32_bf16 v[24:27], v[158:161], v[210:213], v[24:27]
	v_mfma_f32_16x16x32_bf16 v[12:15], v[150:153], v[222:225], v[12:15]
	v_mfma_f32_16x16x32_bf16 v[8:11], v[158:161], v[222:225], v[8:11]
	v_mfma_f32_16x16x32_bf16 v[60:63], v[154:157], v[198:201], v[60:63]
	v_mfma_f32_16x16x32_bf16 v[56:59], v[174:177], v[198:201], v[56:59]
	v_mfma_f32_16x16x32_bf16 v[44:47], v[154:157], v[206:209], v[44:47]
	v_mfma_f32_16x16x32_bf16 v[40:43], v[174:177], v[206:209], v[40:43]
	v_mfma_f32_16x16x32_bf16 v[28:31], v[154:157], v[214:217], v[28:31]
	v_mfma_f32_16x16x32_bf16 v[24:27], v[174:177], v[214:217], v[24:27]
	v_mfma_f32_16x16x32_bf16 v[12:15], v[154:157], v[226:229], v[12:15]
	v_mfma_f32_16x16x32_bf16 v[8:11], v[174:177], v[226:229], v[8:11]
	v_mfma_f32_16x16x32_bf16 v[52:55], v[178:181], v[194:197], v[52:55]
	v_mfma_f32_16x16x32_bf16 v[48:51], v[186:189], v[194:197], v[48:51]
	v_mfma_f32_16x16x32_bf16 v[36:39], v[178:181], v[202:205], v[36:39]
	v_mfma_f32_16x16x32_bf16 v[32:35], v[186:189], v[202:205], v[32:35]
	v_mfma_f32_16x16x32_bf16 v[20:23], v[178:181], v[210:213], v[20:23]
	v_mfma_f32_16x16x32_bf16 v[16:19], v[186:189], v[210:213], v[16:19]
	v_mfma_f32_16x16x32_bf16 v[4:7], v[178:181], v[222:225], v[4:7]
	v_mfma_f32_16x16x32_bf16 v[0:3], v[186:189], v[222:225], v[0:3]
	v_mfma_f32_16x16x32_bf16 v[52:55], v[182:185], v[198:201], v[52:55]
	v_mfma_f32_16x16x32_bf16 v[48:51], v[190:193], v[198:201], v[48:51]
	v_mfma_f32_16x16x32_bf16 v[36:39], v[182:185], v[206:209], v[36:39]
	v_mfma_f32_16x16x32_bf16 v[32:35], v[190:193], v[206:209], v[32:35]
	v_mfma_f32_16x16x32_bf16 v[20:23], v[182:185], v[214:217], v[20:23]
	v_mfma_f32_16x16x32_bf16 v[16:19], v[190:193], v[214:217], v[16:19]
	v_mfma_f32_16x16x32_bf16 v[4:7], v[182:185], v[226:229], v[4:7]
	v_mfma_f32_16x16x32_bf16 v[0:3], v[190:193], v[226:229], v[0:3]
	s_barrier
	s_setprio 0
	s_add_u32 s0, s0, 0x100
	s_addc_u32 s1, s1, 0
	s_add_u32 s44, s44, 0x100
	s_addc_u32 s45, s45, 0
	s_cmp_ge_i32 s95, s80
	s_mov_b32 s10, s95
	s_cbranch_scc0 .LBB0_956

.LBB0_1056:
	v_bfe_i32 v2, v12, 27, 1
	v_lshlrev_b32_e32 v0, 4, v12
	v_lshrrev_b32_e32 v2, 22, v2
	v_add_u32_e32 v2, v0, v2
	v_and_b32_e32 v2, 0xfffffc00, v2
	v_sub_u32_e32 v2, v0, v2
	v_ashrrev_i32_e32 v1, 31, v12
	v_lshrrev_b32_e32 v3, 4, v2
	v_lshrrev_b32_e32 v1, 26, v1
	v_bitop3_b32 v2, v3, v2, 32 bitop3:0x6c
	v_add_u32_e32 v1, v12, v1
	v_ashrrev_i32_e32 v4, 31, v2
	v_ashrrev_i32_e32 v1, 6, v1
	v_lshrrev_b32_e32 v4, 26, v4
	v_lshlrev_b32_e32 v3, 3, v1
	v_add_u32_e32 v4, v2, v4
	v_and_b32_e32 v3, -16, v3
	v_ashrrev_i32_e32 v5, 6, v4
	v_lshlrev_b32_e32 v1, 5, v1
	v_add_u32_e32 v3, v5, v3
	v_and_b32_e32 v13, 32, v1
	v_and_b32_e32 v1, 0xc0, v4
	s_ashr_i32 s6, s1, 3
	v_sub_u32_e32 v1, v2, v1
	v_mov_b32_e32 v2, 1
	v_lshlrev_b32_e32 v4, 1, v3
	v_lshrrev_b32_e32 v6, 2, v3
	v_and_b32_e32 v5, 3, v5
	s_mov_b32 s1, 0x7fffffe0
	v_ashrrev_i16_sdwa v1, v2, sext(v1) dst_sel:DWORD dst_unused:UNUSED_PAD src0_sel:DWORD src1_sel:BYTE_0
	v_and_b32_e32 v4, 24, v4
	v_and_b32_e32 v6, 4, v6
	v_and_or_b32 v5, v3, s1, v5
	v_bfe_i32 v14, v1, 0, 16
	v_or3_b32 v4, v5, v6, v4
	v_add_u32_e32 v1, v13, v14
	v_mul_lo_u32 v15, v3, s0
	v_mul_lo_u32 v3, v4, s0
	v_add_u32_e32 v0, 0x2000, v0
	s_add_u32 s9, s74, 0x6c00000
	v_lshrrev_b32_e32 v252, 3, v220
	v_bfe_u32 v253, v220, 4, 2
	v_bfe_u32 v254, v220, 6, 1
	v_lshl_or_b32 v253, v254, 2, v253
	v_and_b32_e32 v254, 7, v220
	v_xor_b32_e32 v253, v254, v253
	v_lshlrev_b32_e32 v253, 4, v253
	v_and_b32_e32 v254, 32, v252
	v_bfe_u32 v255, v252, 2, 2
	v_lshl_or_b32 v254, v255, 3, v254
	v_bfe_u32 v255, v252, 4, 1
	v_lshl_or_b32 v254, v255, 2, v254
	v_and_b32_e32 v255, 3, v252
	v_or_b32_e32 v254, v254, v255
	v_mul_u32_u24_e32 v254, 0x400, v254
	v_add_u32_e32 v254, v254, v253
	v_add_u32_e32 v255, 0x10000, v254
	v_mul_u32_u24_e32 v252, 0x400, v252
	v_add_u32_e32 v252, v252, v253
	v_add_u32_e32 v253, 0x10000, v252
	v_mov_b32_e32 v128, v252
	v_mov_b32_e32 v130, v254
	v_ashrrev_i32_e32 v1, 31, v0
	s_addc_u32 s48, s75, 0
	v_lshrrev_b32_e32 v1, 22, v1
	s_add_i32 s6, s28, s6
	v_add_u32_e32 v1, v0, v1
	s_ashr_i32 s28, s6, 31
	v_ashrrev_i32_e32 v1, 10, v1
	s_lshr_b32 s28, s28, 26
	v_mul_i32_i24_e32 v3, 0x400, v1
	s_add_i32 s28, s6, s28
	v_sub_u32_e32 v0, v0, v3
	s_ashr_i32 s29, s28, 6
	s_andn2_b32 s28, s28, 63
	v_lshrrev_b32_e32 v3, 4, v0
	s_sub_i32 s28, s6, s28
	v_bitop3_b32 v0, v3, v0, 32 bitop3:0x6c
	s_bfe_i32 s6, s28, 0x80000
	v_ashrrev_i32_e32 v4, 31, v0
	s_bfe_u32 s6, s6, 0x2000d
	v_lshrrev_b32_e32 v4, 26, v4
	s_add_i32 s30, s28, s6
	v_lshlrev_b32_e32 v3, 3, v1
	v_add_u32_e32 v4, v0, v4
	s_bfe_i32 s6, s30, 0x80000
	s_and_b32 s30, s30, 0xfc
	v_and_b32_e32 v3, -16, v3
	v_ashrrev_i32_e32 v5, 6, v4
	v_lshlrev_b32_e32 v1, 5, v1
	s_sub_i32 s28, s28, s30
	v_add_u32_e32 v3, v5, v3
	v_and_b32_e32 v16, 32, v1
	v_and_b32_e32 v1, 0xc0, v4
	v_and_b32_e32 v4, 3, v5
	s_lshl_b32 s29, s29, 2
	s_sext_i32_i8 s28, s28
	v_and_or_b32 v4, v3, s1, v4
	s_ashr_i32 s1, s0, 31
	s_add_i32 s87, s29, s28
	s_lshl_b64 s[26:27], s[0:1], 9
	s_ashr_i32 s28, s87, 31
	s_mul_i32 s28, s26, s28
	s_mul_hi_u32 s29, s26, s87
	s_sext_i32_i16 s35, s6
	s_add_i32 s30, s29, s28
	s_lshr_b64 s[28:29], s[0:1], 23
	s_ashr_i32 s7, s36, 6
	s_lshr_b32 s6, s35, 2
	s_mul_i32 s29, s28, s87
	s_add_i32 s37, s30, s29
	s_bfe_i64 s[30:31], s[6:7], 0x100000
	s_ashr_i32 s29, s35, 2
	s_mul_hi_u32 s30, s26, s29
	s_mul_i32 s31, s26, s31
	s_add_i32 s30, s30, s31
	s_mul_i32 s28, s28, s29
	v_sub_u32_e32 v0, v0, v1
	s_ashr_i32 s34, s36, 8
	s_lshl_b64 s[10:11], s[0:1], 8
	s_lshl_b32 s49, s7, 10
	s_add_i32 s30, s30, s28
	s_mul_i32 s28, s26, s29
	v_ashrrev_i16_sdwa v0, v2, sext(v0) dst_sel:DWORD dst_unused:UNUSED_PAD src0_sel:DWORD src1_sel:BYTE_0
	v_lshlrev_b32_e32 v1, 1, v3
	v_lshrrev_b32_e32 v2, 2, v3
	s_add_u32 s42, s9, s28
	v_and_b32_e32 v1, 24, v1
	v_and_b32_e32 v2, 4, v2
	s_addc_u32 s43, s48, s30
	s_add_i32 s54, s49, 0
	v_bfe_i32 v17, v0, 0, 16
	v_or3_b32 v1, v4, v2, v1
	s_add_i32 m0, s54, 0x10000
	v_add_u32_e32 v0, v16, v17
	v_mul_lo_u32 v1, v1, s0
	global_load_lds_dwordx4 v130, s[42:43]
	s_add_i32 m0, s54, 0x12000
	v_mov_b32_e32 v134, v255
	s_add_u32 s28, s42, s10
	global_load_lds_dwordx4 v134, s[42:43]
	s_addc_u32 s29, s43, s11
	s_add_i32 m0, s54, 0x14000
	s_mul_i32 s38, s26, s87
	global_load_lds_dwordx4 v130, s[28:29]
	s_add_i32 m0, s54, 0x16000
	s_add_u32 s44, s77, s38
	s_addc_u32 s45, s78, s37
	s_add_i32 s55, s54, 0x2000
	v_mul_lo_u32 v18, v3, s0
	global_load_lds_dwordx4 v134, s[28:29]
	s_mov_b32 m0, s54
	s_add_u32 s30, s44, s10
	v_mov_b32_e32 v132, v253
	global_load_lds_dwordx4 v128, s[44:45]
	s_mov_b32 m0, s55
	s_addc_u32 s31, s45, s11
	s_add_i32 s56, s54, 0x4000
	global_load_lds_dwordx4 v132, s[44:45]
	s_mov_b32 m0, s56
	s_add_i32 s57, s54, 0x6000
	global_load_lds_dwordx4 v128, s[30:31]
	s_mov_b32 m0, s57
	v_mov_b32_e32 v137, 0
	global_load_lds_dwordx4 v132, s[30:31]
	v_mov_b32_e32 v131, v137
	v_mov_b32_e32 v135, v137
	v_mov_b32_e32 v129, v137
	v_mov_b32_e32 v133, v137
	s_cmp_eq_u32 s34, 1
	s_mov_b32 s58, 0
	v_lshl_add_u64 v[8:9], s[42:43], 0, v[130:131]
	v_lshl_add_u64 v[4:5], s[42:43], 0, v[134:135]
	v_lshl_add_u64 v[2:3], s[28:29], 0, v[130:131]
	v_lshl_add_u64 v[0:1], s[28:29], 0, v[134:135]
	v_lshl_add_u64 v[6:7], s[44:45], 0, v[128:129]
	s_cselect_b64 s[28:29], -1, 0
	s_cmp_lg_u32 s34, 1
	v_lshl_add_u64 v[10:11], s[44:45], 0, v[132:133]
	s_cbranch_scc1 .LBB0_1058
	s_barrier
.LBB0_1058:
	s_mov_b64 s[30:31], 0x80
	s_add_i32 m0, s54, 0x18000
	v_lshl_add_u64 v[8:9], v[8:9], 0, s[30:31]
	s_waitcnt vmcnt(2)
	s_barrier
	global_load_lds_dwordx4 v[8:9], off
	v_lshl_add_u64 v[4:5], v[4:5], 0, s[30:31]
	s_add_i32 m0, s54, 0x1a000
	s_add_i32 s59, s54, 0x8000
	global_load_lds_dwordx4 v[4:5], off
	v_lshl_add_u64 v[4:5], v[6:7], 0, s[30:31]
	s_mov_b32 m0, s59
	s_add_i32 s60, s54, 0xa000
	global_load_lds_dwordx4 v[4:5], off
	v_lshl_add_u64 v[4:5], v[10:11], 0, s[30:31]
	s_mov_b32 m0, s60
	v_lshl_add_u64 v[2:3], v[2:3], 0, s[30:31]
	global_load_lds_dwordx4 v[4:5], off
	s_add_i32 m0, s54, 0x1c000
	v_lshl_add_u64 v[0:1], v[0:1], 0, s[30:31]
	global_load_lds_dwordx4 v[2:3], off
	s_add_i32 m0, s54, 0x1e000
	s_lshr_b32 s1, s1, 26
	global_load_lds_dwordx4 v[0:1], off
	v_lshrrev_b32_e32 v0, 1, v12
	v_and_b32_e32 v0, 24, v0
	v_and_b32_e32 v150, 15, v12
	s_add_i32 s1, s0, s1
	v_lshlrev_b32_e32 v1, 1, v0
	v_lshlrev_b32_e32 v2, 2, v12
	s_ashr_i32 s61, s1, 6
	v_lshl_or_b32 v1, v150, 6, v1
	s_lshl_b32 s1, s34, 13
	v_and_b32_e32 v2, 32, v2
	v_bitop3_b32 v3, v1, s1, v2 bitop3:0xde
	s_lshl_b32 s1, s7, 5
	s_and_b32 s1, s1, 0x60
	s_sext_i32_i8 s86, s6
	s_lshl_b32 s62, s34, 6
	s_lshl_b32 s6, s1, 7
	s_cmp_gt_i32 s0, 63
	v_and_b32_e32 v252, 15, v220
	v_bfe_u32 v253, v220, 4, 2
	v_bfe_u32 v254, v252, 1, 2
	v_xor_b32_e32 v253, v253, v254
	v_bfe_u32 v254, v252, 3, 1
	v_lshl_or_b32 v253, v254, 2, v253
	v_lshlrev_b32_e32 v253, 4, v253
	v_lshl_or_b32 v253, v252, 7, v253
	v_lshrrev_b32_e32 v254, 6, v220
	v_lshrrev_b32_e32 v255, 2, v254
	v_lshl_or_b32 v252, v255, 13, v253
	v_and_b32_e32 v254, 3, v254
	v_lshl_or_b32 v253, v254, 12, v253
	v_mov_b32_e32 v151, v253
	s_cselect_b64 s[34:35], -1, 0
	s_add_i32 s63, s61, -2
	v_add_u32_e32 v1, v15, v13
	s_waitcnt vmcnt(6)
	s_cmpk_lt_u32 s36, 0x100
	v_mov_b32_e32 v136, v128
	v_add_u32_e32 v1, v18, v16
	s_cselect_b64 s[36:37], -1, 0
	v_or_b32_e32 v0, s1, v0
	v_readlane_b32 s0, v251, 1
	v_lshl_add_u64 v[138:139], s[10:11], 0, v[136:137]
	v_mov_b32_e32 v136, v132
	s_add_i32 s81, 0, 0x10000
	s_add_i32 s82, 0, 0x14000
	s_ashr_i32 s79, s0, 31
	s_mov_b32 s80, s0
	v_lshl_add_u64 v[140:141], s[10:11], 0, v[136:137]
	v_mov_b64_e32 v[142:143], 0x400
	v_mov_b64_e32 v[144:145], 0x3ff
	v_add_u32_e32 v152, s81, v151
	v_add_u32_e32 v153, s82, v151
	v_mov_b32_e32 v154, v252
	v_xor_b32_e32 v252, 64, v154
	v_xor_b32_e32 v253, 64, v152
	v_xor_b32_e32 v254, 64, v153
	v_mov_b32_e32 v155, 0x358637bd
	s_mov_b32 s83, 0xf800000
	v_mov_b32_e32 v156, 0x260
	v_lshlrev_b32_e32 v146, 1, v0
	s_barrier
	v_readlane_b32 s1, v251, 2
	s_branch .LBB0_1061

.LBB0_1073:
	ds_read_b128 v[158:161], v152
	ds_read_b128 v[164:167], v253
	ds_read_b128 v[168:171], v152 offset:2048
	ds_read_b128 v[172:175], v253 offset:2048
	ds_read_b128 v[176:179], v153
	ds_read_b128 v[180:183], v254
	ds_read_b128 v[184:187], v153 offset:2048
	ds_read_b128 v[188:191], v254 offset:2048
	s_add_i32 s88, s42, 2
	s_add_u32 s89, s0, 0x80
	s_addc_u32 s43, s1, 0
	s_cmp_eq_u32 s63, s42
	s_cselect_b32 s42, s38, s89
	s_cselect_b32 s43, s39, s43
	s_cselect_b32 s91, s41, s45
	s_cselect_b32 s90, s40, s44
	v_lshl_add_u64 v[148:149], s[0:1], 0, v[138:139]
	s_add_i32 m0, s54, 0xc000
	ds_read_b128 v[192:195], v154
	ds_read_b128 v[196:199], v252
	ds_read_b128 v[200:203], v154 offset:2048
	ds_read_b128 v[204:207], v252 offset:2048
	ds_read_b128 v[208:211], v154 offset:4096
	ds_read_b128 v[212:215], v252 offset:4096
	ds_read_b128 v[216:219], v154 offset:6144
	ds_read_b128 v[222:225], v252 offset:6144
	global_load_lds_dwordx4 v[148:149], off
	v_lshl_add_u64 v[148:149], s[0:1], 0, v[140:141]
	s_add_i32 m0, s54, 0xe000
	s_nop 0
	global_load_lds_dwordx4 v[148:149], off
	s_waitcnt vmcnt(8)
	s_waitcnt lgkmcnt(0)
	s_setprio 1
	s_barrier
	v_mfma_f32_16x16x32_bf16 v[120:123], v[158:161], v[192:195], v[120:123]
	v_mfma_f32_16x16x32_bf16 v[124:127], v[168:171], v[192:195], v[124:127]
	v_mfma_f32_16x16x32_bf16 v[108:111], v[158:161], v[200:203], v[108:111]
	v_mfma_f32_16x16x32_bf16 v[104:107], v[168:171], v[200:203], v[104:107]
	v_mfma_f32_16x16x32_bf16 v[92:95], v[158:161], v[208:211], v[92:95]
	v_mfma_f32_16x16x32_bf16 v[88:91], v[168:171], v[208:211], v[88:91]
	v_mfma_f32_16x16x32_bf16 v[76:79], v[158:161], v[216:219], v[76:79]
	v_mfma_f32_16x16x32_bf16 v[72:75], v[168:171], v[216:219], v[72:75]
	v_mfma_f32_16x16x32_bf16 v[120:123], v[164:167], v[196:199], v[120:123]
	v_mfma_f32_16x16x32_bf16 v[124:127], v[172:175], v[196:199], v[124:127]
	v_mfma_f32_16x16x32_bf16 v[108:111], v[164:167], v[204:207], v[108:111]
	v_mfma_f32_16x16x32_bf16 v[104:107], v[172:175], v[204:207], v[104:107]
	v_mfma_f32_16x16x32_bf16 v[92:95], v[164:167], v[212:215], v[92:95]
	v_mfma_f32_16x16x32_bf16 v[88:91], v[172:175], v[212:215], v[88:91]
	v_mfma_f32_16x16x32_bf16 v[76:79], v[164:167], v[222:225], v[76:79]
	v_mfma_f32_16x16x32_bf16 v[72:75], v[172:175], v[222:225], v[72:75]
	v_mfma_f32_16x16x32_bf16 v[116:119], v[176:179], v[192:195], v[116:119]
	v_mfma_f32_16x16x32_bf16 v[112:115], v[184:187], v[192:195], v[112:115]
	v_mfma_f32_16x16x32_bf16 v[100:103], v[176:179], v[200:203], v[100:103]
	v_mfma_f32_16x16x32_bf16 v[96:99], v[184:187], v[200:203], v[96:99]
	v_mfma_f32_16x16x32_bf16 v[84:87], v[176:179], v[208:211], v[84:87]
	v_mfma_f32_16x16x32_bf16 v[80:83], v[184:187], v[208:211], v[80:83]
	v_mfma_f32_16x16x32_bf16 v[68:71], v[176:179], v[216:219], v[68:71]
	v_mfma_f32_16x16x32_bf16 v[64:67], v[184:187], v[216:219], v[64:67]
	v_mfma_f32_16x16x32_bf16 v[116:119], v[180:183], v[196:199], v[116:119]
	v_mfma_f32_16x16x32_bf16 v[112:115], v[188:191], v[196:199], v[112:115]
	v_mfma_f32_16x16x32_bf16 v[100:103], v[180:183], v[204:207], v[100:103]
	v_mfma_f32_16x16x32_bf16 v[96:99], v[188:191], v[204:207], v[96:99]
	v_mfma_f32_16x16x32_bf16 v[84:87], v[180:183], v[212:215], v[84:87]
	v_mfma_f32_16x16x32_bf16 v[80:83], v[188:191], v[212:215], v[80:83]
	v_mfma_f32_16x16x32_bf16 v[68:71], v[180:183], v[222:225], v[68:71]
	v_mfma_f32_16x16x32_bf16 v[64:67], v[188:191], v[222:225], v[64:67]
	s_barrier
	s_setprio 0
	s_add_i32 s89, s81, s49
	v_lshl_add_u64 v[148:149], s[90:91], 0, v[130:131]
	s_mov_b32 m0, s89
	ds_read_b128 v[192:195], v154 offset:16384
	ds_read_b128 v[196:199], v252 offset:16384
	ds_read_b128 v[200:203], v154 offset:18432
	ds_read_b128 v[204:207], v252 offset:18432
	ds_read_b128 v[208:211], v154 offset:20480
	ds_read_b128 v[212:215], v252 offset:20480
	ds_read_b128 v[216:219], v154 offset:22528
	ds_read_b128 v[222:225], v252 offset:22528
	global_load_lds_dwordx4 v[148:149], off
	s_add_i32 m0, s89, 0x2000
	v_lshl_add_u64 v[226:227], s[90:91], 0, v[134:135]
	s_add_u32 s90, s90, s10
	s_addc_u32 s91, s91, s11
	s_add_i32 s89, s82, s49
	global_load_lds_dwordx4 v[226:227], off
	v_lshl_add_u64 v[228:229], s[90:91], 0, v[130:131]
	s_mov_b32 m0, s89
	v_lshl_add_u64 v[230:231], s[90:91], 0, v[134:135]
	global_load_lds_dwordx4 v[228:229], off
	s_add_i32 m0, s89, 0x2000
	v_lshl_add_u64 v[232:233], s[42:43], 0, v[128:129]
	global_load_lds_dwordx4 v[230:231], off
	s_mov_b32 m0, s54
	v_lshl_add_u64 v[234:235], s[42:43], 0, v[132:133]
	global_load_lds_dwordx4 v[232:233], off
	s_mov_b32 m0, s55
	s_nop 0
	global_load_lds_dwordx4 v[234:235], off
	s_waitcnt vmcnt(8)
	s_waitcnt lgkmcnt(0)
	s_setprio 1
	s_barrier
	v_mfma_f32_16x16x32_bf16 v[60:63], v[158:161], v[192:195], v[60:63]
	v_mfma_f32_16x16x32_bf16 v[56:59], v[168:171], v[192:195], v[56:59]
	v_mfma_f32_16x16x32_bf16 v[44:47], v[158:161], v[200:203], v[44:47]
	v_mfma_f32_16x16x32_bf16 v[40:43], v[168:171], v[200:203], v[40:43]
	v_mfma_f32_16x16x32_bf16 v[28:31], v[158:161], v[208:211], v[28:31]
	v_mfma_f32_16x16x32_bf16 v[24:27], v[168:171], v[208:211], v[24:27]
	v_mfma_f32_16x16x32_bf16 v[12:15], v[158:161], v[216:219], v[12:15]
	v_mfma_f32_16x16x32_bf16 v[8:11], v[168:171], v[216:219], v[8:11]
	v_mfma_f32_16x16x32_bf16 v[60:63], v[164:167], v[196:199], v[60:63]
	v_mfma_f32_16x16x32_bf16 v[56:59], v[172:175], v[196:199], v[56:59]
	v_mfma_f32_16x16x32_bf16 v[44:47], v[164:167], v[204:207], v[44:47]
	v_mfma_f32_16x16x32_bf16 v[40:43], v[172:175], v[204:207], v[40:43]
	v_mfma_f32_16x16x32_bf16 v[28:31], v[164:167], v[212:215], v[28:31]
	v_mfma_f32_16x16x32_bf16 v[24:27], v[172:175], v[212:215], v[24:27]
	v_mfma_f32_16x16x32_bf16 v[12:15], v[164:167], v[222:225], v[12:15]
	v_mfma_f32_16x16x32_bf16 v[8:11], v[172:175], v[222:225], v[8:11]
	v_mfma_f32_16x16x32_bf16 v[52:55], v[176:179], v[192:195], v[52:55]
	v_mfma_f32_16x16x32_bf16 v[48:51], v[184:187], v[192:195], v[48:51]
	v_mfma_f32_16x16x32_bf16 v[36:39], v[176:179], v[200:203], v[36:39]
	v_mfma_f32_16x16x32_bf16 v[32:35], v[184:187], v[200:203], v[32:35]
	v_mfma_f32_16x16x32_bf16 v[20:23], v[176:179], v[208:211], v[20:23]
	v_mfma_f32_16x16x32_bf16 v[16:19], v[184:187], v[208:211], v[16:19]
	v_mfma_f32_16x16x32_bf16 v[4:7], v[176:179], v[216:219], v[4:7]
	v_mfma_f32_16x16x32_bf16 v[0:3], v[184:187], v[216:219], v[0:3]
	v_mfma_f32_16x16x32_bf16 v[52:55], v[180:183], v[196:199], v[52:55]
	v_mfma_f32_16x16x32_bf16 v[48:51], v[188:191], v[196:199], v[48:51]
	v_mfma_f32_16x16x32_bf16 v[36:39], v[180:183], v[204:207], v[36:39]
	v_mfma_f32_16x16x32_bf16 v[32:35], v[188:191], v[204:207], v[32:35]
	v_mfma_f32_16x16x32_bf16 v[20:23], v[180:183], v[212:215], v[20:23]
	v_mfma_f32_16x16x32_bf16 v[16:19], v[188:191], v[212:215], v[16:19]
	v_mfma_f32_16x16x32_bf16 v[4:7], v[180:183], v[222:225], v[4:7]
	v_mfma_f32_16x16x32_bf16 v[0:3], v[188:191], v[222:225], v[0:3]
	s_barrier
	s_setprio 0
	s_add_i32 s89, 0, 0x18000
	v_add_u32_e32 v136, s89, v151
	s_add_i32 s90, 0, 0x1c000
	v_xor_b32_e32 v255, 64, v136
	ds_read_b128 v[158:161], v136
	ds_read_b128 v[164:167], v255
	ds_read_b128 v[168:171], v136 offset:2048
	ds_read_b128 v[172:175], v255 offset:2048
	v_add_u32_e32 v136, s90, v151
	v_xor_b32_e32 v255, 64, v136
	ds_read_b128 v[176:179], v136
	ds_read_b128 v[180:183], v255
	ds_read_b128 v[184:187], v136 offset:2048
	ds_read_b128 v[188:191], v255 offset:2048
	s_add_u32 s42, s42, s10
	s_addc_u32 s43, s43, s11
	s_mov_b32 m0, s56
	v_lshl_add_u64 v[236:237], s[42:43], 0, v[128:129]
	ds_read_b128 v[192:195], v154 offset:32768
	ds_read_b128 v[196:199], v252 offset:32768
	ds_read_b128 v[200:203], v154 offset:34816
	ds_read_b128 v[204:207], v252 offset:34816
	ds_read_b128 v[208:211], v154 offset:36864
	ds_read_b128 v[212:215], v252 offset:36864
	ds_read_b128 v[216:219], v154 offset:38912
	ds_read_b128 v[222:225], v252 offset:38912
	global_load_lds_dwordx4 v[236:237], off
	v_lshl_add_u64 v[236:237], s[42:43], 0, v[132:133]
	s_mov_b32 m0, s57
	s_nop 0
	global_load_lds_dwordx4 v[236:237], off
	s_waitcnt vmcnt(8)
	s_waitcnt lgkmcnt(0)
	s_setprio 1
	s_barrier
	v_mfma_f32_16x16x32_bf16 v[120:123], v[158:161], v[192:195], v[120:123]
	v_mfma_f32_16x16x32_bf16 v[124:127], v[168:171], v[192:195], v[124:127]
	v_mfma_f32_16x16x32_bf16 v[108:111], v[158:161], v[200:203], v[108:111]
	v_mfma_f32_16x16x32_bf16 v[104:107], v[168:171], v[200:203], v[104:107]
	v_mfma_f32_16x16x32_bf16 v[92:95], v[158:161], v[208:211], v[92:95]
	v_mfma_f32_16x16x32_bf16 v[88:91], v[168:171], v[208:211], v[88:91]
	v_mfma_f32_16x16x32_bf16 v[76:79], v[158:161], v[216:219], v[76:79]
	v_mfma_f32_16x16x32_bf16 v[72:75], v[168:171], v[216:219], v[72:75]
	v_mfma_f32_16x16x32_bf16 v[120:123], v[164:167], v[196:199], v[120:123]
	v_mfma_f32_16x16x32_bf16 v[124:127], v[172:175], v[196:199], v[124:127]
	v_mfma_f32_16x16x32_bf16 v[108:111], v[164:167], v[204:207], v[108:111]
	v_mfma_f32_16x16x32_bf16 v[104:107], v[172:175], v[204:207], v[104:107]
	v_mfma_f32_16x16x32_bf16 v[92:95], v[164:167], v[212:215], v[92:95]
	v_mfma_f32_16x16x32_bf16 v[88:91], v[172:175], v[212:215], v[88:91]
	v_mfma_f32_16x16x32_bf16 v[76:79], v[164:167], v[222:225], v[76:79]
	v_mfma_f32_16x16x32_bf16 v[72:75], v[172:175], v[222:225], v[72:75]
	v_mfma_f32_16x16x32_bf16 v[116:119], v[176:179], v[192:195], v[116:119]
	v_mfma_f32_16x16x32_bf16 v[112:115], v[184:187], v[192:195], v[112:115]
	v_mfma_f32_16x16x32_bf16 v[100:103], v[176:179], v[200:203], v[100:103]
	v_mfma_f32_16x16x32_bf16 v[96:99], v[184:187], v[200:203], v[96:99]
	v_mfma_f32_16x16x32_bf16 v[84:87], v[176:179], v[208:211], v[84:87]
	v_mfma_f32_16x16x32_bf16 v[80:83], v[184:187], v[208:211], v[80:83]
	v_mfma_f32_16x16x32_bf16 v[68:71], v[176:179], v[216:219], v[68:71]
	v_mfma_f32_16x16x32_bf16 v[64:67], v[184:187], v[216:219], v[64:67]
	v_mfma_f32_16x16x32_bf16 v[116:119], v[180:183], v[196:199], v[116:119]
	v_mfma_f32_16x16x32_bf16 v[112:115], v[188:191], v[196:199], v[112:115]
	v_mfma_f32_16x16x32_bf16 v[100:103], v[180:183], v[204:207], v[100:103]
	v_mfma_f32_16x16x32_bf16 v[96:99], v[188:191], v[204:207], v[96:99]
	v_mfma_f32_16x16x32_bf16 v[84:87], v[180:183], v[212:215], v[84:87]
	v_mfma_f32_16x16x32_bf16 v[80:83], v[188:191], v[212:215], v[80:83]
	v_mfma_f32_16x16x32_bf16 v[68:71], v[180:183], v[222:225], v[68:71]
	v_mfma_f32_16x16x32_bf16 v[64:67], v[188:191], v[222:225], v[64:67]
	s_barrier
	s_setprio 0
	s_add_i32 s42, s89, s49
	v_lshl_add_u64 v[148:149], v[148:149], 0, s[30:31]
	s_mov_b32 m0, s42
	ds_read_b128 v[192:195], v154 offset:49152
	ds_read_b128 v[196:199], v252 offset:49152
	ds_read_b128 v[200:203], v154 offset:51200
	ds_read_b128 v[204:207], v252 offset:51200
	ds_read_b128 v[208:211], v154 offset:53248
	ds_read_b128 v[212:215], v252 offset:53248
	ds_read_b128 v[216:219], v154 offset:55296
	ds_read_b128 v[222:225], v252 offset:55296
	global_load_lds_dwordx4 v[148:149], off
	v_lshl_add_u64 v[148:149], v[226:227], 0, s[30:31]
	s_add_i32 m0, s42, 0x2000
	s_add_i32 s42, s90, s49
	global_load_lds_dwordx4 v[148:149], off
	v_lshl_add_u64 v[148:149], v[228:229], 0, s[30:31]
	s_mov_b32 m0, s42
	s_nop 0
	global_load_lds_dwordx4 v[148:149], off
	v_lshl_add_u64 v[148:149], v[230:231], 0, s[30:31]
	s_add_i32 m0, s42, 0x2000
	s_nop 0
	global_load_lds_dwordx4 v[148:149], off
	v_lshl_add_u64 v[148:149], v[232:233], 0, s[30:31]
	s_mov_b32 m0, s59
	s_nop 0
	global_load_lds_dwordx4 v[148:149], off
	v_lshl_add_u64 v[148:149], v[234:235], 0, s[30:31]
	s_mov_b32 m0, s60
	s_nop 0
	global_load_lds_dwordx4 v[148:149], off
	s_waitcnt vmcnt(8)
	s_waitcnt lgkmcnt(0)
	s_setprio 1
	s_barrier
	v_mfma_f32_16x16x32_bf16 v[60:63], v[158:161], v[192:195], v[60:63]
	v_mfma_f32_16x16x32_bf16 v[56:59], v[168:171], v[192:195], v[56:59]
	v_mfma_f32_16x16x32_bf16 v[44:47], v[158:161], v[200:203], v[44:47]
	v_mfma_f32_16x16x32_bf16 v[40:43], v[168:171], v[200:203], v[40:43]
	v_mfma_f32_16x16x32_bf16 v[28:31], v[158:161], v[208:211], v[28:31]
	v_mfma_f32_16x16x32_bf16 v[24:27], v[168:171], v[208:211], v[24:27]
	v_mfma_f32_16x16x32_bf16 v[12:15], v[158:161], v[216:219], v[12:15]
	v_mfma_f32_16x16x32_bf16 v[8:11], v[168:171], v[216:219], v[8:11]
	v_mfma_f32_16x16x32_bf16 v[60:63], v[164:167], v[196:199], v[60:63]
	v_mfma_f32_16x16x32_bf16 v[56:59], v[172:175], v[196:199], v[56:59]
	v_mfma_f32_16x16x32_bf16 v[44:47], v[164:167], v[204:207], v[44:47]
	v_mfma_f32_16x16x32_bf16 v[40:43], v[172:175], v[204:207], v[40:43]
	v_mfma_f32_16x16x32_bf16 v[28:31], v[164:167], v[212:215], v[28:31]
	v_mfma_f32_16x16x32_bf16 v[24:27], v[172:175], v[212:215], v[24:27]
	v_mfma_f32_16x16x32_bf16 v[12:15], v[164:167], v[222:225], v[12:15]
	v_mfma_f32_16x16x32_bf16 v[8:11], v[172:175], v[222:225], v[8:11]
	v_mfma_f32_16x16x32_bf16 v[52:55], v[176:179], v[192:195], v[52:55]
	v_mfma_f32_16x16x32_bf16 v[48:51], v[184:187], v[192:195], v[48:51]
	v_mfma_f32_16x16x32_bf16 v[36:39], v[176:179], v[200:203], v[36:39]
	v_mfma_f32_16x16x32_bf16 v[32:35], v[184:187], v[200:203], v[32:35]
	v_mfma_f32_16x16x32_bf16 v[20:23], v[176:179], v[208:211], v[20:23]
	v_mfma_f32_16x16x32_bf16 v[16:19], v[184:187], v[208:211], v[16:19]
	v_mfma_f32_16x16x32_bf16 v[4:7], v[176:179], v[216:219], v[4:7]
	v_mfma_f32_16x16x32_bf16 v[0:3], v[184:187], v[216:219], v[0:3]
	v_mfma_f32_16x16x32_bf16 v[52:55], v[180:183], v[196:199], v[52:55]
	v_mfma_f32_16x16x32_bf16 v[48:51], v[188:191], v[196:199], v[48:51]
	v_mfma_f32_16x16x32_bf16 v[36:39], v[180:183], v[204:207], v[36:39]
	v_mfma_f32_16x16x32_bf16 v[32:35], v[188:191], v[204:207], v[32:35]
	v_mfma_f32_16x16x32_bf16 v[20:23], v[180:183], v[212:215], v[20:23]
	v_mfma_f32_16x16x32_bf16 v[16:19], v[188:191], v[212:215], v[16:19]
	v_mfma_f32_16x16x32_bf16 v[4:7], v[180:183], v[222:225], v[4:7]
	v_mfma_f32_16x16x32_bf16 v[0:3], v[188:191], v[222:225], v[0:3]
	s_barrier
	s_setprio 0
	s_add_u32 s0, s0, 0x100
	s_addc_u32 s1, s1, 0
	s_add_u32 s44, s44, 0x100
	s_addc_u32 s45, s45, 0
	s_cmp_ge_i32 s88, s61
	s_mov_b32 s42, s88
	s_cbranch_scc0 .LBB0_1073

.LBB0_1082:
	s_andn2_b64 vcc, exec, s[0:1]
	s_cbranch_vccnz .LBB0_1135
	v_bfe_i32 v2, v12, 27, 1
	v_lshlrev_b32_e32 v0, 4, v12
	v_lshrrev_b32_e32 v2, 22, v2
	v_add_u32_e32 v2, v0, v2
	v_and_b32_e32 v2, 0xfffffc00, v2
	v_sub_u32_e32 v2, v0, v2
	v_ashrrev_i32_e32 v1, 31, v12
	v_lshrrev_b32_e32 v3, 4, v2
	v_lshrrev_b32_e32 v1, 26, v1
	v_bitop3_b32 v2, v3, v2, 32 bitop3:0x6c
	v_add_u32_e32 v1, v12, v1
	v_ashrrev_i32_e32 v4, 31, v2
	v_ashrrev_i32_e32 v1, 6, v1
	v_lshrrev_b32_e32 v4, 26, v4
	v_lshlrev_b32_e32 v3, 3, v1
	v_add_u32_e32 v4, v2, v4
	v_and_b32_e32 v3, -16, v3
	v_ashrrev_i32_e32 v5, 6, v4
	v_lshlrev_b32_e32 v1, 5, v1
	v_add_u32_e32 v3, v5, v3
	v_and_b32_e32 v13, 32, v1
	v_and_b32_e32 v1, 0xc0, v4
	v_sub_u32_e32 v1, v2, v1
	v_mov_b32_e32 v2, 1
	v_lshlrev_b32_e32 v4, 1, v3
	v_lshrrev_b32_e32 v6, 2, v3
	v_and_b32_e32 v5, 3, v5
	s_mov_b32 s1, 0x7fffffe0
	v_ashrrev_i16_sdwa v1, v2, sext(v1) dst_sel:DWORD dst_unused:UNUSED_PAD src0_sel:DWORD src1_sel:BYTE_0
	v_and_b32_e32 v4, 24, v4
	v_and_b32_e32 v6, 4, v6
	v_and_or_b32 v5, v3, s1, v5
	v_bfe_i32 v14, v1, 0, 16
	v_or3_b32 v4, v5, v6, v4
	v_add_u32_e32 v1, v13, v14
	v_mul_lo_u32 v15, v3, s8
	v_mul_lo_u32 v3, v4, s8
	v_add_u32_e32 v0, 0x2000, v0
	v_lshrrev_b32_e32 v252, 3, v220
	v_bfe_u32 v253, v220, 4, 2
	v_bfe_u32 v254, v220, 6, 1
	v_lshl_or_b32 v253, v254, 2, v253
	v_and_b32_e32 v254, 7, v220
	v_xor_b32_e32 v253, v254, v253
	v_lshlrev_b32_e32 v253, 4, v253
	v_and_b32_e32 v254, 32, v252
	v_bfe_u32 v255, v252, 2, 2
	v_lshl_or_b32 v254, v255, 3, v254
	v_bfe_u32 v255, v252, 4, 1
	v_lshl_or_b32 v254, v255, 2, v254
	v_and_b32_e32 v255, 3, v252
	v_or_b32_e32 v254, v254, v255
	v_mul_u32_u24_e32 v254, 0x400, v254
	v_add_u32_e32 v254, v254, v253
	v_add_u32_e32 v255, 0x10000, v254
	v_mul_u32_u24_e32 v252, 0x400, v252
	v_add_u32_e32 v252, v252, v253
	v_add_u32_e32 v253, 0x10000, v252
	v_mov_b32_e32 v128, v252
	v_mov_b32_e32 v130, v254
	v_ashrrev_i32_e32 v1, 31, v0
	v_lshrrev_b32_e32 v1, 22, v1
	v_add_u32_e32 v1, v0, v1
	v_ashrrev_i32_e32 v1, 10, v1
	s_add_u32 s48, s74, 0x7000000
	v_mul_i32_i24_e32 v3, 0x400, v1
	s_addc_u32 s49, s75, 0
	v_sub_u32_e32 v0, v0, v3
	s_ashr_i32 s9, s8, 31
	v_lshrrev_b32_e32 v3, 4, v0
	s_lshl_b64 s[28:29], s[8:9], 9
	s_ashr_i32 s7, s91, 31
	v_bitop3_b32 v0, v3, v0, 32 bitop3:0x6c
	s_mul_i32 s7, s28, s7
	s_mul_hi_u32 s10, s28, s91
	v_ashrrev_i32_e32 v4, 31, v0
	s_add_i32 s7, s10, s7
	s_lshr_b64 s[10:11], s[8:9], 23
	v_lshrrev_b32_e32 v4, 26, v4
	s_mul_i32 s11, s10, s91
	v_lshlrev_b32_e32 v3, 3, v1
	v_add_u32_e32 v4, v0, v4
	s_add_i32 s7, s7, s11
	s_ashr_i32 s11, s90, 31
	v_and_b32_e32 v3, -16, v3
	v_ashrrev_i32_e32 v5, 6, v4
	v_lshlrev_b32_e32 v1, 5, v1
	s_mul_i32 s11, s28, s11
	s_mul_hi_u32 s30, s28, s90
	s_ashr_i32 s0, s6, 6
	v_add_u32_e32 v3, v5, v3
	v_and_b32_e32 v16, 32, v1
	v_and_b32_e32 v1, 0xc0, v4
	v_and_b32_e32 v4, 3, v5
	s_add_i32 s11, s30, s11
	s_mul_i32 s10, s10, s90
	v_sub_u32_e32 v0, v0, v1
	v_and_or_b32 v4, v3, s1, v4
	s_ashr_i32 s1, s6, 8
	s_lshl_b64 s[26:27], s[8:9], 8
	s_lshl_b32 s54, s0, 10
	s_add_i32 s11, s11, s10
	s_mul_i32 s10, s28, s90
	v_ashrrev_i16_sdwa v0, v2, sext(v0) dst_sel:DWORD dst_unused:UNUSED_PAD src0_sel:DWORD src1_sel:BYTE_0
	v_lshlrev_b32_e32 v1, 1, v3
	v_lshrrev_b32_e32 v2, 2, v3
	s_add_u32 s10, s48, s10
	v_and_b32_e32 v1, 24, v1
	v_and_b32_e32 v2, 4, v2
	s_addc_u32 s11, s49, s11
	s_add_i32 s55, s54, 0
	v_bfe_i32 v17, v0, 0, 16
	v_or3_b32 v1, v4, v2, v1
	s_add_i32 m0, s55, 0x10000
	v_add_u32_e32 v0, v16, v17
	v_mul_lo_u32 v1, v1, s8
	global_load_lds_dwordx4 v130, s[10:11]
	s_add_i32 m0, s55, 0x12000
	v_mov_b32_e32 v134, v255
	s_add_u32 s30, s10, s26
	global_load_lds_dwordx4 v134, s[10:11]
	s_addc_u32 s31, s11, s27
	s_add_i32 m0, s55, 0x14000
	s_mul_i32 s34, s28, s91
	global_load_lds_dwordx4 v130, s[30:31]
	s_add_i32 m0, s55, 0x16000
	s_add_u32 s44, s47, s34
	s_addc_u32 s45, s76, s7
	s_add_i32 s56, s55, 0x2000
	v_mul_lo_u32 v18, v3, s8
	global_load_lds_dwordx4 v134, s[30:31]
	s_mov_b32 m0, s55
	s_add_u32 s34, s44, s26
	v_mov_b32_e32 v132, v253
	global_load_lds_dwordx4 v128, s[44:45]
	s_mov_b32 m0, s56
	s_addc_u32 s35, s45, s27
	s_add_i32 s57, s55, 0x4000
	global_load_lds_dwordx4 v132, s[44:45]
	s_mov_b32 m0, s57
	s_add_i32 s58, s55, 0x6000
	global_load_lds_dwordx4 v128, s[34:35]
	s_mov_b32 m0, s58
	v_mov_b32_e32 v137, 0
	global_load_lds_dwordx4 v132, s[34:35]
	v_mov_b32_e32 v131, v137
	v_mov_b32_e32 v135, v137
	v_mov_b32_e32 v129, v137
	v_mov_b32_e32 v133, v137
	s_cmp_eq_u32 s1, 1
	s_movk_i32 s59, 0xc0
	s_mov_b32 s60, 0
	v_lshl_add_u64 v[8:9], s[10:11], 0, v[130:131]
	v_lshl_add_u64 v[4:5], s[10:11], 0, v[134:135]
	v_lshl_add_u64 v[2:3], s[30:31], 0, v[130:131]
	v_lshl_add_u64 v[0:1], s[30:31], 0, v[134:135]
	v_lshl_add_u64 v[6:7], s[44:45], 0, v[128:129]
	s_cselect_b64 s[30:31], -1, 0
	s_cmp_lg_u32 s1, 1
	v_lshl_add_u64 v[10:11], s[44:45], 0, v[132:133]
	s_cbranch_scc1 .LBB0_1085
	s_barrier
.LBB0_1085:
	s_mov_b64 s[34:35], 0x80
	s_add_i32 m0, s55, 0x18000
	v_lshl_add_u64 v[8:9], v[8:9], 0, s[34:35]
	s_waitcnt vmcnt(2)
	s_barrier
	global_load_lds_dwordx4 v[8:9], off
	v_lshl_add_u64 v[4:5], v[4:5], 0, s[34:35]
	s_add_i32 m0, s55, 0x1a000
	s_add_i32 s61, s55, 0x8000
	global_load_lds_dwordx4 v[4:5], off
	v_lshl_add_u64 v[4:5], v[6:7], 0, s[34:35]
	s_mov_b32 m0, s61
	s_add_i32 s62, s55, 0xa000
	global_load_lds_dwordx4 v[4:5], off
	v_lshl_add_u64 v[4:5], v[10:11], 0, s[34:35]
	s_mov_b32 m0, s62
	v_lshl_add_u64 v[2:3], v[2:3], 0, s[34:35]
	global_load_lds_dwordx4 v[4:5], off
	s_add_i32 m0, s55, 0x1c000
	v_lshl_add_u64 v[0:1], v[0:1], 0, s[34:35]
	global_load_lds_dwordx4 v[2:3], off
	s_add_i32 m0, s55, 0x1e000
	s_lshr_b32 s7, s9, 26
	global_load_lds_dwordx4 v[0:1], off
	v_lshrrev_b32_e32 v1, 1, v12
	v_and_b32_e32 v1, 24, v1
	v_and_b32_e32 v0, 15, v12
	v_lshlrev_b32_e32 v2, 1, v1
	v_lshl_or_b32 v154, s1, 6, v0
	v_lshl_or_b32 v0, v0, 6, v2
	v_lshlrev_b32_e32 v2, 2, v12
	s_lshl_b32 s0, s0, 5
	s_add_i32 s7, s8, s7
	s_lshl_b32 s1, s1, 13
	v_and_b32_e32 v2, 32, v2
	s_and_b32 s0, s0, 0x60
	s_ashr_i32 s63, s7, 6
	v_bitop3_b32 v3, v0, s1, v2 bitop3:0xde
	s_lshl_b32 s1, s0, 7
	s_cmp_gt_i32 s8, 63
	v_and_b32_e32 v252, 15, v220
	v_bfe_u32 v253, v220, 4, 2
	v_bfe_u32 v254, v252, 1, 2
	v_xor_b32_e32 v253, v253, v254
	v_bfe_u32 v254, v252, 3, 1
	v_lshl_or_b32 v253, v254, 2, v253
	v_lshlrev_b32_e32 v253, 4, v253
	v_lshl_or_b32 v253, v252, 7, v253
	v_lshrrev_b32_e32 v254, 6, v220
	v_lshrrev_b32_e32 v255, 2, v254
	v_lshl_or_b32 v252, v255, 13, v253
	v_and_b32_e32 v254, 3, v254
	v_lshl_or_b32 v253, v254, 12, v253
	v_mov_b32_e32 v155, v253
	s_cselect_b64 s[36:37], -1, 0
	s_add_i32 s77, s63, -2
	v_add_u32_e32 v0, v15, v13
	s_waitcnt vmcnt(6)
	s_cmpk_lt_u32 s6, 0x100
	v_mov_b32_e32 v136, v128
	v_add_u32_e32 v0, v18, v16
	s_cselect_b64 s[38:39], -1, 0
	v_readlane_b32 s6, v251, 1
	v_lshl_add_u64 v[138:139], s[26:27], 0, v[136:137]
	v_mov_b32_e32 v136, v132
	s_add_i32 s82, 0, 0x10000
	s_add_i32 s83, 0, 0x14000
	s_ashr_i32 s78, s6, 31
	s_mov_b32 s79, s6
	v_or_b32_e32 v156, s0, v1
	v_lshl_add_u64 v[140:141], s[26:27], 0, v[136:137]
	v_mov_b64_e32 v[142:143], 0x300
	v_mov_b64_e32 v[144:145], 0x2ff
	s_movk_i32 s80, 0x61
	s_mov_b32 s81, 0x2aaaaaab
	v_add_u32_e32 v157, s82, v155
	v_add_u32_e32 v158, s83, v155
	v_mov_b32_e32 v159, v252
	v_xor_b32_e32 v252, 64, v159
	v_xor_b32_e32 v253, 64, v157
	v_xor_b32_e32 v254, 64, v158
	v_mov_b32_e32 v160, 0x358637bd
	s_mov_b32 s84, 0xf800000
	v_mov_b32_e32 v161, 0x260
	s_mov_b32 s85, 0x3dd53b95
	s_movk_i32 s86, 0x7f
	s_movk_i32 s87, 0x1800
	s_barrier
	v_readlane_b32 s7, v251, 2
	s_branch .LBB0_1088

.LBB0_1096:
	ds_read_b128 v[146:149], v157
	ds_read_b128 v[150:153], v253
	ds_read_b128 v[164:167], v157 offset:2048
	ds_read_b128 v[168:171], v253 offset:2048
	ds_read_b128 v[172:175], v158
	ds_read_b128 v[176:179], v254
	ds_read_b128 v[180:183], v158 offset:2048
	ds_read_b128 v[184:187], v254 offset:2048
	s_add_i32 s44, s8, 2
	s_add_u32 s45, s0, 0x80
	s_addc_u32 s9, s1, 0
	s_cmp_eq_u32 s77, s8
	s_cselect_b32 s8, s40, s45
	s_cselect_b32 s9, s41, s9
	s_cselect_b32 s93, s43, s11
	s_cselect_b32 s92, s42, s10
	v_lshl_add_u64 v[222:223], s[0:1], 0, v[138:139]
	s_add_i32 m0, s55, 0xc000
	ds_read_b128 v[188:191], v159
	ds_read_b128 v[192:195], v252
	ds_read_b128 v[196:199], v159 offset:2048
	ds_read_b128 v[200:203], v252 offset:2048
	ds_read_b128 v[204:207], v159 offset:4096
	ds_read_b128 v[208:211], v252 offset:4096
	ds_read_b128 v[212:215], v159 offset:6144
	ds_read_b128 v[216:219], v252 offset:6144
	global_load_lds_dwordx4 v[222:223], off
	v_lshl_add_u64 v[222:223], s[0:1], 0, v[140:141]
	s_add_i32 m0, s55, 0xe000
	s_nop 0
	global_load_lds_dwordx4 v[222:223], off
	s_waitcnt vmcnt(8)
	s_waitcnt lgkmcnt(0)
	s_setprio 1
	s_barrier
	v_mfma_f32_16x16x32_bf16 v[120:123], v[146:149], v[188:191], v[120:123]
	v_mfma_f32_16x16x32_bf16 v[124:127], v[164:167], v[188:191], v[124:127]
	v_mfma_f32_16x16x32_bf16 v[108:111], v[146:149], v[196:199], v[108:111]
	v_mfma_f32_16x16x32_bf16 v[104:107], v[164:167], v[196:199], v[104:107]
	v_mfma_f32_16x16x32_bf16 v[92:95], v[146:149], v[204:207], v[92:95]
	v_mfma_f32_16x16x32_bf16 v[88:91], v[164:167], v[204:207], v[88:91]
	v_mfma_f32_16x16x32_bf16 v[76:79], v[146:149], v[212:215], v[76:79]
	v_mfma_f32_16x16x32_bf16 v[72:75], v[164:167], v[212:215], v[72:75]
	v_mfma_f32_16x16x32_bf16 v[120:123], v[150:153], v[192:195], v[120:123]
	v_mfma_f32_16x16x32_bf16 v[124:127], v[168:171], v[192:195], v[124:127]
	v_mfma_f32_16x16x32_bf16 v[108:111], v[150:153], v[200:203], v[108:111]
	v_mfma_f32_16x16x32_bf16 v[104:107], v[168:171], v[200:203], v[104:107]
	v_mfma_f32_16x16x32_bf16 v[92:95], v[150:153], v[208:211], v[92:95]
	v_mfma_f32_16x16x32_bf16 v[88:91], v[168:171], v[208:211], v[88:91]
	v_mfma_f32_16x16x32_bf16 v[76:79], v[150:153], v[216:219], v[76:79]
	v_mfma_f32_16x16x32_bf16 v[72:75], v[168:171], v[216:219], v[72:75]
	v_mfma_f32_16x16x32_bf16 v[116:119], v[172:175], v[188:191], v[116:119]
	v_mfma_f32_16x16x32_bf16 v[112:115], v[180:183], v[188:191], v[112:115]
	v_mfma_f32_16x16x32_bf16 v[100:103], v[172:175], v[196:199], v[100:103]
	v_mfma_f32_16x16x32_bf16 v[96:99], v[180:183], v[196:199], v[96:99]
	v_mfma_f32_16x16x32_bf16 v[84:87], v[172:175], v[204:207], v[84:87]
	v_mfma_f32_16x16x32_bf16 v[80:83], v[180:183], v[204:207], v[80:83]
	v_mfma_f32_16x16x32_bf16 v[68:71], v[172:175], v[212:215], v[68:71]
	v_mfma_f32_16x16x32_bf16 v[64:67], v[180:183], v[212:215], v[64:67]
	v_mfma_f32_16x16x32_bf16 v[116:119], v[176:179], v[192:195], v[116:119]
	v_mfma_f32_16x16x32_bf16 v[112:115], v[184:187], v[192:195], v[112:115]
	v_mfma_f32_16x16x32_bf16 v[100:103], v[176:179], v[200:203], v[100:103]
	v_mfma_f32_16x16x32_bf16 v[96:99], v[184:187], v[200:203], v[96:99]
	v_mfma_f32_16x16x32_bf16 v[84:87], v[176:179], v[208:211], v[84:87]
	v_mfma_f32_16x16x32_bf16 v[80:83], v[184:187], v[208:211], v[80:83]
	v_mfma_f32_16x16x32_bf16 v[68:71], v[176:179], v[216:219], v[68:71]
	v_mfma_f32_16x16x32_bf16 v[64:67], v[184:187], v[216:219], v[64:67]
	s_barrier
	s_setprio 0
	s_add_i32 s45, s82, s54
	v_lshl_add_u64 v[222:223], s[92:93], 0, v[130:131]
	s_mov_b32 m0, s45
	ds_read_b128 v[188:191], v159 offset:16384
	ds_read_b128 v[192:195], v252 offset:16384
	ds_read_b128 v[196:199], v159 offset:18432
	ds_read_b128 v[200:203], v252 offset:18432
	ds_read_b128 v[204:207], v159 offset:20480
	ds_read_b128 v[208:211], v252 offset:20480
	ds_read_b128 v[212:215], v159 offset:22528
	ds_read_b128 v[216:219], v252 offset:22528
	global_load_lds_dwordx4 v[222:223], off
	s_add_i32 m0, s45, 0x2000
	v_lshl_add_u64 v[224:225], s[92:93], 0, v[134:135]
	s_add_u32 s92, s92, s26
	s_addc_u32 s93, s93, s27
	s_add_i32 s45, s83, s54
	global_load_lds_dwordx4 v[224:225], off
	v_lshl_add_u64 v[226:227], s[92:93], 0, v[130:131]
	s_mov_b32 m0, s45
	v_lshl_add_u64 v[228:229], s[92:93], 0, v[134:135]
	global_load_lds_dwordx4 v[226:227], off
	s_add_i32 m0, s45, 0x2000
	v_lshl_add_u64 v[230:231], s[8:9], 0, v[128:129]
	global_load_lds_dwordx4 v[228:229], off
	s_mov_b32 m0, s55
	v_lshl_add_u64 v[232:233], s[8:9], 0, v[132:133]
	global_load_lds_dwordx4 v[230:231], off
	s_mov_b32 m0, s56
	s_nop 0
	global_load_lds_dwordx4 v[232:233], off
	s_waitcnt vmcnt(8)
	s_waitcnt lgkmcnt(0)
	s_setprio 1
	s_barrier
	v_mfma_f32_16x16x32_bf16 v[60:63], v[146:149], v[188:191], v[60:63]
	v_mfma_f32_16x16x32_bf16 v[56:59], v[164:167], v[188:191], v[56:59]
	v_mfma_f32_16x16x32_bf16 v[44:47], v[146:149], v[196:199], v[44:47]
	v_mfma_f32_16x16x32_bf16 v[40:43], v[164:167], v[196:199], v[40:43]
	v_mfma_f32_16x16x32_bf16 v[28:31], v[146:149], v[204:207], v[28:31]
	v_mfma_f32_16x16x32_bf16 v[24:27], v[164:167], v[204:207], v[24:27]
	v_mfma_f32_16x16x32_bf16 v[12:15], v[146:149], v[212:215], v[12:15]
	v_mfma_f32_16x16x32_bf16 v[8:11], v[164:167], v[212:215], v[8:11]
	v_mfma_f32_16x16x32_bf16 v[60:63], v[150:153], v[192:195], v[60:63]
	v_mfma_f32_16x16x32_bf16 v[56:59], v[168:171], v[192:195], v[56:59]
	v_mfma_f32_16x16x32_bf16 v[44:47], v[150:153], v[200:203], v[44:47]
	v_mfma_f32_16x16x32_bf16 v[40:43], v[168:171], v[200:203], v[40:43]
	v_mfma_f32_16x16x32_bf16 v[28:31], v[150:153], v[208:211], v[28:31]
	v_mfma_f32_16x16x32_bf16 v[24:27], v[168:171], v[208:211], v[24:27]
	v_mfma_f32_16x16x32_bf16 v[12:15], v[150:153], v[216:219], v[12:15]
	v_mfma_f32_16x16x32_bf16 v[8:11], v[168:171], v[216:219], v[8:11]
	v_mfma_f32_16x16x32_bf16 v[52:55], v[172:175], v[188:191], v[52:55]
	v_mfma_f32_16x16x32_bf16 v[48:51], v[180:183], v[188:191], v[48:51]
	v_mfma_f32_16x16x32_bf16 v[36:39], v[172:175], v[196:199], v[36:39]
	v_mfma_f32_16x16x32_bf16 v[32:35], v[180:183], v[196:199], v[32:35]
	v_mfma_f32_16x16x32_bf16 v[20:23], v[172:175], v[204:207], v[20:23]
	v_mfma_f32_16x16x32_bf16 v[16:19], v[180:183], v[204:207], v[16:19]
	v_mfma_f32_16x16x32_bf16 v[4:7], v[172:175], v[212:215], v[4:7]
	v_mfma_f32_16x16x32_bf16 v[0:3], v[180:183], v[212:215], v[0:3]
	v_mfma_f32_16x16x32_bf16 v[52:55], v[176:179], v[192:195], v[52:55]
	v_mfma_f32_16x16x32_bf16 v[48:51], v[184:187], v[192:195], v[48:51]
	v_mfma_f32_16x16x32_bf16 v[36:39], v[176:179], v[200:203], v[36:39]
	v_mfma_f32_16x16x32_bf16 v[32:35], v[184:187], v[200:203], v[32:35]
	v_mfma_f32_16x16x32_bf16 v[20:23], v[176:179], v[208:211], v[20:23]
	v_mfma_f32_16x16x32_bf16 v[16:19], v[184:187], v[208:211], v[16:19]
	v_mfma_f32_16x16x32_bf16 v[4:7], v[176:179], v[216:219], v[4:7]
	v_mfma_f32_16x16x32_bf16 v[0:3], v[184:187], v[216:219], v[0:3]
	s_barrier
	s_setprio 0
	s_add_i32 s45, 0, 0x18000
	v_add_u32_e32 v136, s45, v155
	s_add_i32 s92, 0, 0x1c000
	v_xor_b32_e32 v255, 64, v136
	ds_read_b128 v[146:149], v136
	ds_read_b128 v[150:153], v255
	ds_read_b128 v[164:167], v136 offset:2048
	ds_read_b128 v[168:171], v255 offset:2048
	v_add_u32_e32 v136, s92, v155
	v_xor_b32_e32 v255, 64, v136
	ds_read_b128 v[172:175], v136
	ds_read_b128 v[176:179], v255
	ds_read_b128 v[180:183], v136 offset:2048
	ds_read_b128 v[184:187], v255 offset:2048
	s_add_u32 s8, s8, s26
	s_addc_u32 s9, s9, s27
	s_mov_b32 m0, s57
	v_lshl_add_u64 v[234:235], s[8:9], 0, v[128:129]
	ds_read_b128 v[188:191], v159 offset:32768
	ds_read_b128 v[192:195], v252 offset:32768
	ds_read_b128 v[196:199], v159 offset:34816
	ds_read_b128 v[200:203], v252 offset:34816
	ds_read_b128 v[204:207], v159 offset:36864
	ds_read_b128 v[208:211], v252 offset:36864
	ds_read_b128 v[212:215], v159 offset:38912
	ds_read_b128 v[216:219], v252 offset:38912
	global_load_lds_dwordx4 v[234:235], off
	v_lshl_add_u64 v[234:235], s[8:9], 0, v[132:133]
	s_mov_b32 m0, s58
	s_nop 0
	global_load_lds_dwordx4 v[234:235], off
	s_waitcnt vmcnt(8)
	s_waitcnt lgkmcnt(0)
	s_setprio 1
	s_barrier
	v_mfma_f32_16x16x32_bf16 v[120:123], v[146:149], v[188:191], v[120:123]
	v_mfma_f32_16x16x32_bf16 v[124:127], v[164:167], v[188:191], v[124:127]
	v_mfma_f32_16x16x32_bf16 v[108:111], v[146:149], v[196:199], v[108:111]
	v_mfma_f32_16x16x32_bf16 v[104:107], v[164:167], v[196:199], v[104:107]
	v_mfma_f32_16x16x32_bf16 v[92:95], v[146:149], v[204:207], v[92:95]
	v_mfma_f32_16x16x32_bf16 v[88:91], v[164:167], v[204:207], v[88:91]
	v_mfma_f32_16x16x32_bf16 v[76:79], v[146:149], v[212:215], v[76:79]
	v_mfma_f32_16x16x32_bf16 v[72:75], v[164:167], v[212:215], v[72:75]
	v_mfma_f32_16x16x32_bf16 v[120:123], v[150:153], v[192:195], v[120:123]
	v_mfma_f32_16x16x32_bf16 v[124:127], v[168:171], v[192:195], v[124:127]
	v_mfma_f32_16x16x32_bf16 v[108:111], v[150:153], v[200:203], v[108:111]
	v_mfma_f32_16x16x32_bf16 v[104:107], v[168:171], v[200:203], v[104:107]
	v_mfma_f32_16x16x32_bf16 v[92:95], v[150:153], v[208:211], v[92:95]
	v_mfma_f32_16x16x32_bf16 v[88:91], v[168:171], v[208:211], v[88:91]
	v_mfma_f32_16x16x32_bf16 v[76:79], v[150:153], v[216:219], v[76:79]
	v_mfma_f32_16x16x32_bf16 v[72:75], v[168:171], v[216:219], v[72:75]
	v_mfma_f32_16x16x32_bf16 v[116:119], v[172:175], v[188:191], v[116:119]
	v_mfma_f32_16x16x32_bf16 v[112:115], v[180:183], v[188:191], v[112:115]
	v_mfma_f32_16x16x32_bf16 v[100:103], v[172:175], v[196:199], v[100:103]
	v_mfma_f32_16x16x32_bf16 v[96:99], v[180:183], v[196:199], v[96:99]
	v_mfma_f32_16x16x32_bf16 v[84:87], v[172:175], v[204:207], v[84:87]
	v_mfma_f32_16x16x32_bf16 v[80:83], v[180:183], v[204:207], v[80:83]
	v_mfma_f32_16x16x32_bf16 v[68:71], v[172:175], v[212:215], v[68:71]
	v_mfma_f32_16x16x32_bf16 v[64:67], v[180:183], v[212:215], v[64:67]
	v_mfma_f32_16x16x32_bf16 v[116:119], v[176:179], v[192:195], v[116:119]
	v_mfma_f32_16x16x32_bf16 v[112:115], v[184:187], v[192:195], v[112:115]
	v_mfma_f32_16x16x32_bf16 v[100:103], v[176:179], v[200:203], v[100:103]
	v_mfma_f32_16x16x32_bf16 v[96:99], v[184:187], v[200:203], v[96:99]
	v_mfma_f32_16x16x32_bf16 v[84:87], v[176:179], v[208:211], v[84:87]
	v_mfma_f32_16x16x32_bf16 v[80:83], v[184:187], v[208:211], v[80:83]
	v_mfma_f32_16x16x32_bf16 v[68:71], v[176:179], v[216:219], v[68:71]
	v_mfma_f32_16x16x32_bf16 v[64:67], v[184:187], v[216:219], v[64:67]
	s_barrier
	s_setprio 0
	s_add_i32 s8, s45, s54
	v_lshl_add_u64 v[222:223], v[222:223], 0, s[34:35]
	s_mov_b32 m0, s8
	ds_read_b128 v[188:191], v159 offset:49152
	ds_read_b128 v[192:195], v252 offset:49152
	ds_read_b128 v[196:199], v159 offset:51200
	ds_read_b128 v[200:203], v252 offset:51200
	ds_read_b128 v[204:207], v159 offset:53248
	ds_read_b128 v[208:211], v252 offset:53248
	ds_read_b128 v[212:215], v159 offset:55296
	ds_read_b128 v[216:219], v252 offset:55296
	global_load_lds_dwordx4 v[222:223], off
	v_lshl_add_u64 v[222:223], v[224:225], 0, s[34:35]
	s_add_i32 m0, s8, 0x2000
	s_add_i32 s8, s92, s54
	global_load_lds_dwordx4 v[222:223], off
	v_lshl_add_u64 v[222:223], v[226:227], 0, s[34:35]
	s_mov_b32 m0, s8
	s_nop 0
	global_load_lds_dwordx4 v[222:223], off
	v_lshl_add_u64 v[222:223], v[228:229], 0, s[34:35]
	s_add_i32 m0, s8, 0x2000
	s_nop 0
	global_load_lds_dwordx4 v[222:223], off
	v_lshl_add_u64 v[222:223], v[230:231], 0, s[34:35]
	s_mov_b32 m0, s61
	s_nop 0
	global_load_lds_dwordx4 v[222:223], off
	v_lshl_add_u64 v[222:223], v[232:233], 0, s[34:35]
	s_mov_b32 m0, s62
	s_nop 0
	global_load_lds_dwordx4 v[222:223], off
	s_waitcnt vmcnt(8)
	s_waitcnt lgkmcnt(0)
	s_setprio 1
	s_barrier
	v_mfma_f32_16x16x32_bf16 v[60:63], v[146:149], v[188:191], v[60:63]
	v_mfma_f32_16x16x32_bf16 v[56:59], v[164:167], v[188:191], v[56:59]
	v_mfma_f32_16x16x32_bf16 v[44:47], v[146:149], v[196:199], v[44:47]
	v_mfma_f32_16x16x32_bf16 v[40:43], v[164:167], v[196:199], v[40:43]
	v_mfma_f32_16x16x32_bf16 v[28:31], v[146:149], v[204:207], v[28:31]
	v_mfma_f32_16x16x32_bf16 v[24:27], v[164:167], v[204:207], v[24:27]
	v_mfma_f32_16x16x32_bf16 v[12:15], v[146:149], v[212:215], v[12:15]
	v_mfma_f32_16x16x32_bf16 v[8:11], v[164:167], v[212:215], v[8:11]
	v_mfma_f32_16x16x32_bf16 v[60:63], v[150:153], v[192:195], v[60:63]
	v_mfma_f32_16x16x32_bf16 v[56:59], v[168:171], v[192:195], v[56:59]
	v_mfma_f32_16x16x32_bf16 v[44:47], v[150:153], v[200:203], v[44:47]
	v_mfma_f32_16x16x32_bf16 v[40:43], v[168:171], v[200:203], v[40:43]
	v_mfma_f32_16x16x32_bf16 v[28:31], v[150:153], v[208:211], v[28:31]
	v_mfma_f32_16x16x32_bf16 v[24:27], v[168:171], v[208:211], v[24:27]
	v_mfma_f32_16x16x32_bf16 v[12:15], v[150:153], v[216:219], v[12:15]
	v_mfma_f32_16x16x32_bf16 v[8:11], v[168:171], v[216:219], v[8:11]
	v_mfma_f32_16x16x32_bf16 v[52:55], v[172:175], v[188:191], v[52:55]
	v_mfma_f32_16x16x32_bf16 v[48:51], v[180:183], v[188:191], v[48:51]
	v_mfma_f32_16x16x32_bf16 v[36:39], v[172:175], v[196:199], v[36:39]
	v_mfma_f32_16x16x32_bf16 v[32:35], v[180:183], v[196:199], v[32:35]
	v_mfma_f32_16x16x32_bf16 v[20:23], v[172:175], v[204:207], v[20:23]
	v_mfma_f32_16x16x32_bf16 v[16:19], v[180:183], v[204:207], v[16:19]
	v_mfma_f32_16x16x32_bf16 v[4:7], v[172:175], v[212:215], v[4:7]
	v_mfma_f32_16x16x32_bf16 v[0:3], v[180:183], v[212:215], v[0:3]
	v_mfma_f32_16x16x32_bf16 v[52:55], v[176:179], v[192:195], v[52:55]
	v_mfma_f32_16x16x32_bf16 v[48:51], v[184:187], v[192:195], v[48:51]
	v_mfma_f32_16x16x32_bf16 v[36:39], v[176:179], v[200:203], v[36:39]
	v_mfma_f32_16x16x32_bf16 v[32:35], v[184:187], v[200:203], v[32:35]
	v_mfma_f32_16x16x32_bf16 v[20:23], v[176:179], v[208:211], v[20:23]
	v_mfma_f32_16x16x32_bf16 v[16:19], v[184:187], v[208:211], v[16:19]
	v_mfma_f32_16x16x32_bf16 v[4:7], v[176:179], v[216:219], v[4:7]
	v_mfma_f32_16x16x32_bf16 v[0:3], v[184:187], v[216:219], v[0:3]
	s_barrier
	s_setprio 0
	s_add_u32 s0, s0, 0x100
	s_addc_u32 s1, s1, 0
	s_add_u32 s10, s10, 0x100
	s_addc_u32 s11, s11, 0
	s_cmp_ge_i32 s44, s63
	s_mov_b32 s8, s44
	s_cbranch_scc0 .LBB0_1096

.LBB0_1274:
	s_add_u32 s18, s74, 0x1fb80000
	s_addc_u32 s19, s75, 0
	s_and_b64 vcc, exec, s[4:5]
	s_cbranch_vccnz .LBB0_1315
	v_bfe_i32 v2, v12, 27, 1
	v_lshlrev_b32_e32 v0, 4, v12
	v_lshrrev_b32_e32 v2, 22, v2
	v_add_u32_e32 v2, v0, v2
	v_and_b32_e32 v2, 0xfffffc00, v2
	v_sub_u32_e32 v2, v0, v2
	v_ashrrev_i32_e32 v1, 31, v12
	v_lshrrev_b32_e32 v3, 4, v2
	v_lshrrev_b32_e32 v1, 26, v1
	v_bitop3_b32 v2, v3, v2, 32 bitop3:0x6c
	v_add_u32_e32 v1, v12, v1
	v_ashrrev_i32_e32 v4, 31, v2
	v_ashrrev_i32_e32 v1, 6, v1
	v_lshrrev_b32_e32 v4, 26, v4
	v_lshlrev_b32_e32 v3, 3, v1
	v_add_u32_e32 v4, v2, v4
	v_and_b32_e32 v3, -16, v3
	v_ashrrev_i32_e32 v5, 6, v4
	v_lshlrev_b32_e32 v1, 5, v1
	v_add_u32_e32 v3, v5, v3
	v_and_b32_e32 v13, 32, v1
	v_and_b32_e32 v1, 0xc0, v4
	v_sub_u32_e32 v1, v2, v1
	v_mov_b32_e32 v2, 1
	v_lshlrev_b32_e32 v4, 1, v3
	v_lshrrev_b32_e32 v6, 2, v3
	v_and_b32_e32 v5, 3, v5
	s_mov_b32 s1, 0x7fffffe0
	v_ashrrev_i16_sdwa v1, v2, sext(v1) dst_sel:DWORD dst_unused:UNUSED_PAD src0_sel:DWORD src1_sel:BYTE_0
	v_and_b32_e32 v4, 24, v4
	v_and_b32_e32 v6, 4, v6
	v_and_or_b32 v5, v3, s1, v5
	v_bfe_i32 v14, v1, 0, 16
	v_or3_b32 v4, v5, v6, v4
	v_add_u32_e32 v1, v13, v14
	v_mul_lo_u32 v15, v3, s0
	v_mul_lo_u32 v3, v4, s0
	v_add_u32_e32 v0, 0x2000, v0
	v_lshrrev_b32_e32 v252, 3, v220
	v_bfe_u32 v253, v220, 4, 2
	v_bfe_u32 v254, v220, 6, 1
	v_lshl_or_b32 v253, v254, 2, v253
	v_and_b32_e32 v254, 7, v220
	v_xor_b32_e32 v253, v254, v253
	v_lshlrev_b32_e32 v253, 4, v253
	v_and_b32_e32 v254, 32, v252
	v_bfe_u32 v255, v252, 2, 2
	v_lshl_or_b32 v254, v255, 3, v254
	v_bfe_u32 v255, v252, 4, 1
	v_lshl_or_b32 v254, v255, 2, v254
	v_and_b32_e32 v255, 3, v252
	v_or_b32_e32 v254, v254, v255
	v_mul_u32_u24_e32 v254, 0x1000, v254
	v_add_u32_e32 v254, v254, v253
	v_add_u32_e32 v255, 0x40000, v254
	v_mul_u32_u24_e32 v252, 0x1000, v252
	v_add_u32_e32 v252, v252, v253
	v_add_u32_e32 v253, 0x40000, v252
	v_mov_b32_e32 v144, v252
	v_mov_b32_e32 v146, v254
	v_ashrrev_i32_e32 v1, 31, v0
	v_lshrrev_b32_e32 v1, 22, v1
	v_add_u32_e32 v1, v0, v1
	v_ashrrev_i32_e32 v1, 10, v1
	v_mul_i32_i24_e32 v3, 0x400, v1
	v_sub_u32_e32 v0, v0, v3
	v_lshrrev_b32_e32 v3, 4, v0
	v_bitop3_b32 v0, v3, v0, 32 bitop3:0x6c
	v_ashrrev_i32_e32 v4, 31, v0
	v_lshrrev_b32_e32 v4, 26, v4
	v_lshlrev_b32_e32 v3, 3, v1
	v_add_u32_e32 v4, v0, v4
	v_and_b32_e32 v3, -16, v3
	v_ashrrev_i32_e32 v5, 6, v4
	v_lshlrev_b32_e32 v1, 5, v1
	s_add_u32 s31, s74, 0x7300000
	v_add_u32_e32 v3, v5, v3
	v_and_b32_e32 v16, 32, v1
	v_and_b32_e32 v1, 0xc0, v4
	v_and_b32_e32 v4, 3, v5
	s_addc_u32 s35, s75, 0
	v_and_or_b32 v4, v3, s1, v4
	s_ashr_i32 s1, s0, 31
	s_lshl_b64 s[20:21], s[0:1], 9
	s_ashr_i32 s9, s79, 31
	s_mul_i32 s9, s20, s9
	s_mul_hi_u32 s22, s20, s79
	s_add_i32 s9, s22, s9
	s_lshr_b64 s[22:23], s[0:1], 23
	s_mul_i32 s23, s22, s79
	s_add_i32 s9, s9, s23
	s_ashr_i32 s23, s78, 31
	s_mul_i32 s23, s20, s23
	s_mul_hi_u32 s25, s20, s78
	s_ashr_i32 s7, s8, 6
	s_add_i32 s23, s25, s23
	s_mul_i32 s22, s22, s78
	s_ashr_i32 s6, s8, 8
	v_sub_u32_e32 v0, v0, v1
	s_lshl_b64 s[10:11], s[0:1], 8
	s_lshl_b32 s44, s7, 10
	s_add_i32 s23, s23, s22
	s_mul_i32 s22, s20, s78
	v_ashrrev_i16_sdwa v0, v2, sext(v0) dst_sel:DWORD dst_unused:UNUSED_PAD src0_sel:DWORD src1_sel:BYTE_0
	v_lshlrev_b32_e32 v1, 1, v3
	v_lshrrev_b32_e32 v2, 2, v3
	s_add_u32 s40, s31, s22
	v_and_b32_e32 v1, 24, v1
	v_and_b32_e32 v2, 4, v2
	s_addc_u32 s41, s35, s23
	s_add_i32 s45, s44, 0
	v_bfe_i32 v17, v0, 0, 16
	v_or3_b32 v1, v4, v2, v1
	s_add_i32 m0, s45, 0x10000
	v_add_u32_e32 v0, v16, v17
	v_mul_lo_u32 v1, v1, s0
	global_load_lds_dwordx4 v146, s[40:41]
	s_add_i32 m0, s45, 0x12000
	v_mov_b32_e32 v150, v255
	s_add_u32 s22, s40, s10
	global_load_lds_dwordx4 v150, s[40:41]
	s_addc_u32 s23, s41, s11
	s_add_i32 m0, s45, 0x14000
	s_mul_i32 s24, s20, s79
	global_load_lds_dwordx4 v146, s[22:23]
	s_add_i32 m0, s45, 0x16000
	s_add_u32 s42, s47, s24
	s_addc_u32 s43, s58, s9
	s_add_i32 s48, s45, 0x2000
	v_mul_lo_u32 v18, v3, s0
	global_load_lds_dwordx4 v150, s[22:23]
	s_mov_b32 m0, s45
	s_add_u32 s24, s42, s10
	v_mov_b32_e32 v148, v253
	global_load_lds_dwordx4 v144, s[42:43]
	s_mov_b32 m0, s48
	s_addc_u32 s25, s43, s11
	s_add_i32 s49, s45, 0x4000
	global_load_lds_dwordx4 v148, s[42:43]
	s_mov_b32 m0, s49
	s_add_i32 s52, s45, 0x6000
	global_load_lds_dwordx4 v144, s[24:25]
	s_mov_b32 m0, s52
	v_mov_b32_e32 v147, 0
	global_load_lds_dwordx4 v148, s[24:25]
	v_mov_b32_e32 v151, v147
	v_mov_b32_e32 v145, v147
	v_mov_b32_e32 v149, v147
	s_cmp_eq_u32 s6, 1
	s_mov_b32 s53, 0
	v_lshl_add_u64 v[8:9], s[40:41], 0, v[146:147]
	v_lshl_add_u64 v[4:5], s[40:41], 0, v[150:151]
	v_lshl_add_u64 v[2:3], s[22:23], 0, v[146:147]
	v_lshl_add_u64 v[0:1], s[22:23], 0, v[150:151]
	v_lshl_add_u64 v[6:7], s[42:43], 0, v[144:145]
	s_cselect_b64 s[22:23], -1, 0
	s_cmp_lg_u32 s6, 1
	v_lshl_add_u64 v[10:11], s[42:43], 0, v[148:149]
	s_cbranch_scc1 .LBB0_1277
	s_barrier
.LBB0_1277:
	s_mov_b64 s[24:25], 0x80
	s_add_i32 m0, s45, 0x18000
	v_lshl_add_u64 v[8:9], v[8:9], 0, s[24:25]
	s_waitcnt vmcnt(2)
	s_barrier
	global_load_lds_dwordx4 v[8:9], off
	v_lshl_add_u64 v[4:5], v[4:5], 0, s[24:25]
	s_add_i32 m0, s45, 0x1a000
	s_add_i32 s54, s45, 0x8000
	global_load_lds_dwordx4 v[4:5], off
	v_lshl_add_u64 v[4:5], v[6:7], 0, s[24:25]
	s_mov_b32 m0, s54
	s_add_i32 s55, s45, 0xa000
	global_load_lds_dwordx4 v[4:5], off
	v_lshl_add_u64 v[4:5], v[10:11], 0, s[24:25]
	s_mov_b32 m0, s55
	v_lshl_add_u64 v[2:3], v[2:3], 0, s[24:25]
	global_load_lds_dwordx4 v[4:5], off
	s_add_i32 m0, s45, 0x1c000
	v_lshl_add_u64 v[0:1], v[0:1], 0, s[24:25]
	global_load_lds_dwordx4 v[2:3], off
	s_add_i32 m0, s45, 0x1e000
	s_lshr_b32 s1, s1, 26
	global_load_lds_dwordx4 v[0:1], off
	v_bfe_u32 v0, v12, 4, 2
	v_and_b32_e32 v1, 15, v12
	v_lshlrev_b32_e32 v2, 4, v0
	s_add_i32 s1, s0, s1
	v_lshl_or_b32 v223, s6, 6, v1
	v_lshl_or_b32 v1, v1, 6, v2
	v_lshlrev_b32_e32 v2, 2, v12
	s_ashr_i32 s56, s1, 6
	s_lshl_b32 s1, s6, 13
	v_and_b32_e32 v2, 32, v2
	v_bitop3_b32 v3, v1, s1, v2 bitop3:0xde
	s_lshl_b32 s1, s7, 5
	s_and_b32 s1, s1, 0x60
	s_lshl_b32 s6, s1, 7
	v_and_b32_e32 v252, 15, v220
	v_bfe_u32 v253, v220, 4, 2
	v_bfe_u32 v254, v252, 1, 2
	v_xor_b32_e32 v253, v253, v254
	v_bfe_u32 v254, v252, 3, 1
	v_lshl_or_b32 v253, v254, 2, v253
	v_lshlrev_b32_e32 v253, 4, v253
	v_lshl_or_b32 v253, v252, 7, v253
	v_lshrrev_b32_e32 v254, 6, v220
	v_lshrrev_b32_e32 v255, 2, v254
	v_lshl_or_b32 v252, v255, 13, v253
	v_and_b32_e32 v254, 3, v254
	v_lshl_or_b32 v253, v254, 12, v253
	v_mov_b32_e32 v224, v253
	s_cmp_gt_i32 s0, 63
	v_cmp_eq_u32_e64 s[6:7], 0, v0
	v_lshl_or_b32 v225, v0, 3, s1
	v_add_u32_e32 v0, v15, v13
	s_cselect_b64 s[26:27], -1, 0
	s_add_i32 s57, s56, -2
	v_mov_b32_e32 v0, v144
	v_mov_b32_e32 v1, v147
	s_waitcnt vmcnt(6)
	s_cmpk_lt_u32 s8, 0x100
	v_lshl_add_u64 v[152:153], s[10:11], 0, v[0:1]
	v_add_u32_e32 v0, v18, v16
	s_cselect_b64 s[28:29], -1, 0
	v_readlane_b32 s8, v251, 1
	v_mov_b32_e32 v0, v148
	s_add_i32 s61, 0, 0x10000
	s_add_i32 s62, 0, 0x14000
	s_ashr_i32 s59, s8, 31
	s_mov_b32 s60, s8
	v_lshl_add_u64 v[154:155], s[10:11], 0, v[0:1]
	s_waitcnt vmcnt(0)
	v_mov_b64_e32 v[156:157], 0x200
	v_mov_b64_e32 v[158:159], 0x1ff
	v_add_u32_e32 v226, s61, v224
	v_add_u32_e32 v227, s62, v224
	v_mov_b32_e32 v228, v252
	v_xor_b32_e32 v252, 64, v228
	v_xor_b32_e32 v253, 64, v226
	v_xor_b32_e32 v254, 64, v227
	s_mov_b32 s30, 0x3a000000
	s_mov_b32 s63, 0xf800000
	v_mov_b32_e32 v229, 0x260
	s_mov_b32 s34, 0x3fb504f3
	s_barrier
	v_readlane_b32 s9, v251, 2
	s_branch .LBB0_1280

.LBB0_1292:
	ds_read_b128 v[128:131], v226
	ds_read_b128 v[132:135], v253
	ds_read_b128 v[136:139], v226 offset:2048
	ds_read_b128 v[140:143], v253 offset:2048
	ds_read_b128 v[160:163], v227
	ds_read_b128 v[164:167], v254
	ds_read_b128 v[168:171], v227 offset:2048
	ds_read_b128 v[172:175], v254 offset:2048
	s_add_i32 s80, s40, 2
	s_add_u32 s81, s0, 0x80
	s_addc_u32 s41, s1, 0
	s_cmp_eq_u32 s57, s40
	s_cselect_b32 s40, s36, s81
	s_cselect_b32 s41, s37, s41
	s_cselect_b32 s83, s39, s43
	s_cselect_b32 s82, s38, s42
	v_lshl_add_u64 v[208:209], s[0:1], 0, v[152:153]
	s_add_i32 m0, s45, 0xc000
	ds_read_b128 v[176:179], v228
	ds_read_b128 v[180:183], v252
	ds_read_b128 v[184:187], v228 offset:2048
	ds_read_b128 v[188:191], v252 offset:2048
	ds_read_b128 v[192:195], v228 offset:4096
	ds_read_b128 v[196:199], v252 offset:4096
	ds_read_b128 v[200:203], v228 offset:6144
	ds_read_b128 v[204:207], v252 offset:6144
	global_load_lds_dwordx4 v[208:209], off
	v_lshl_add_u64 v[208:209], s[0:1], 0, v[154:155]
	s_add_i32 m0, s45, 0xe000
	s_nop 0
	global_load_lds_dwordx4 v[208:209], off
	s_waitcnt vmcnt(8)
	s_waitcnt lgkmcnt(0)
	s_setprio 1
	s_barrier
	v_mfma_f32_16x16x32_bf16 v[124:127], v[128:131], v[176:179], v[124:127]
	v_mfma_f32_16x16x32_bf16 v[120:123], v[136:139], v[176:179], v[120:123]
	v_mfma_f32_16x16x32_bf16 v[116:119], v[128:131], v[184:187], v[116:119]
	v_mfma_f32_16x16x32_bf16 v[112:115], v[136:139], v[184:187], v[112:115]
	v_mfma_f32_16x16x32_bf16 v[108:111], v[128:131], v[192:195], v[108:111]
	v_mfma_f32_16x16x32_bf16 v[104:107], v[136:139], v[192:195], v[104:107]
	v_mfma_f32_16x16x32_bf16 v[100:103], v[128:131], v[200:203], v[100:103]
	v_mfma_f32_16x16x32_bf16 v[96:99], v[136:139], v[200:203], v[96:99]
	v_mfma_f32_16x16x32_bf16 v[124:127], v[132:135], v[180:183], v[124:127]
	v_mfma_f32_16x16x32_bf16 v[120:123], v[140:143], v[180:183], v[120:123]
	v_mfma_f32_16x16x32_bf16 v[116:119], v[132:135], v[188:191], v[116:119]
	v_mfma_f32_16x16x32_bf16 v[112:115], v[140:143], v[188:191], v[112:115]
	v_mfma_f32_16x16x32_bf16 v[108:111], v[132:135], v[196:199], v[108:111]
	v_mfma_f32_16x16x32_bf16 v[104:107], v[140:143], v[196:199], v[104:107]
	v_mfma_f32_16x16x32_bf16 v[100:103], v[132:135], v[204:207], v[100:103]
	v_mfma_f32_16x16x32_bf16 v[96:99], v[140:143], v[204:207], v[96:99]
	v_mfma_f32_16x16x32_bf16 v[60:63], v[160:163], v[176:179], v[60:63]
	v_mfma_f32_16x16x32_bf16 v[56:59], v[168:171], v[176:179], v[56:59]
	v_mfma_f32_16x16x32_bf16 v[52:55], v[160:163], v[184:187], v[52:55]
	v_mfma_f32_16x16x32_bf16 v[48:51], v[168:171], v[184:187], v[48:51]
	v_mfma_f32_16x16x32_bf16 v[44:47], v[160:163], v[192:195], v[44:47]
	v_mfma_f32_16x16x32_bf16 v[40:43], v[168:171], v[192:195], v[40:43]
	v_mfma_f32_16x16x32_bf16 v[36:39], v[160:163], v[200:203], v[36:39]
	v_mfma_f32_16x16x32_bf16 v[32:35], v[168:171], v[200:203], v[32:35]
	v_mfma_f32_16x16x32_bf16 v[60:63], v[164:167], v[180:183], v[60:63]
	v_mfma_f32_16x16x32_bf16 v[56:59], v[172:175], v[180:183], v[56:59]
	v_mfma_f32_16x16x32_bf16 v[52:55], v[164:167], v[188:191], v[52:55]
	v_mfma_f32_16x16x32_bf16 v[48:51], v[172:175], v[188:191], v[48:51]
	v_mfma_f32_16x16x32_bf16 v[44:47], v[164:167], v[196:199], v[44:47]
	v_mfma_f32_16x16x32_bf16 v[40:43], v[172:175], v[196:199], v[40:43]
	v_mfma_f32_16x16x32_bf16 v[36:39], v[164:167], v[204:207], v[36:39]
	v_mfma_f32_16x16x32_bf16 v[32:35], v[172:175], v[204:207], v[32:35]
	s_barrier
	s_setprio 0
	s_add_i32 s81, s61, s44
	v_lshl_add_u64 v[208:209], s[82:83], 0, v[146:147]
	s_mov_b32 m0, s81
	ds_read_b128 v[176:179], v228 offset:16384
	ds_read_b128 v[180:183], v252 offset:16384
	ds_read_b128 v[184:187], v228 offset:18432
	ds_read_b128 v[188:191], v252 offset:18432
	ds_read_b128 v[192:195], v228 offset:20480
	ds_read_b128 v[196:199], v252 offset:20480
	ds_read_b128 v[200:203], v228 offset:22528
	ds_read_b128 v[204:207], v252 offset:22528
	global_load_lds_dwordx4 v[208:209], off
	s_add_i32 m0, s81, 0x2000
	v_lshl_add_u64 v[210:211], s[82:83], 0, v[150:151]
	s_add_u32 s82, s82, s10
	s_addc_u32 s83, s83, s11
	s_add_i32 s81, s62, s44
	global_load_lds_dwordx4 v[210:211], off
	v_lshl_add_u64 v[212:213], s[82:83], 0, v[146:147]
	s_mov_b32 m0, s81
	v_lshl_add_u64 v[214:215], s[82:83], 0, v[150:151]
	global_load_lds_dwordx4 v[212:213], off
	s_add_i32 m0, s81, 0x2000
	v_lshl_add_u64 v[216:217], s[40:41], 0, v[144:145]
	global_load_lds_dwordx4 v[214:215], off
	s_mov_b32 m0, s45
	v_lshl_add_u64 v[218:219], s[40:41], 0, v[148:149]
	global_load_lds_dwordx4 v[216:217], off
	s_mov_b32 m0, s48
	s_nop 0
	global_load_lds_dwordx4 v[218:219], off
	s_waitcnt vmcnt(8)
	s_waitcnt lgkmcnt(0)
	s_setprio 1
	s_barrier
	v_mfma_f32_16x16x32_bf16 v[92:95], v[128:131], v[176:179], v[92:95]
	v_mfma_f32_16x16x32_bf16 v[88:91], v[136:139], v[176:179], v[88:91]
	v_mfma_f32_16x16x32_bf16 v[84:87], v[128:131], v[184:187], v[84:87]
	v_mfma_f32_16x16x32_bf16 v[80:83], v[136:139], v[184:187], v[80:83]
	v_mfma_f32_16x16x32_bf16 v[76:79], v[128:131], v[192:195], v[76:79]
	v_mfma_f32_16x16x32_bf16 v[72:75], v[136:139], v[192:195], v[72:75]
	v_mfma_f32_16x16x32_bf16 v[68:71], v[128:131], v[200:203], v[68:71]
	v_mfma_f32_16x16x32_bf16 v[64:67], v[136:139], v[200:203], v[64:67]
	v_mfma_f32_16x16x32_bf16 v[92:95], v[132:135], v[180:183], v[92:95]
	v_mfma_f32_16x16x32_bf16 v[88:91], v[140:143], v[180:183], v[88:91]
	v_mfma_f32_16x16x32_bf16 v[84:87], v[132:135], v[188:191], v[84:87]
	v_mfma_f32_16x16x32_bf16 v[80:83], v[140:143], v[188:191], v[80:83]
	v_mfma_f32_16x16x32_bf16 v[76:79], v[132:135], v[196:199], v[76:79]
	v_mfma_f32_16x16x32_bf16 v[72:75], v[140:143], v[196:199], v[72:75]
	v_mfma_f32_16x16x32_bf16 v[68:71], v[132:135], v[204:207], v[68:71]
	v_mfma_f32_16x16x32_bf16 v[64:67], v[140:143], v[204:207], v[64:67]
	v_mfma_f32_16x16x32_bf16 v[28:31], v[160:163], v[176:179], v[28:31]
	v_mfma_f32_16x16x32_bf16 v[24:27], v[168:171], v[176:179], v[24:27]
	v_mfma_f32_16x16x32_bf16 v[20:23], v[160:163], v[184:187], v[20:23]
	v_mfma_f32_16x16x32_bf16 v[16:19], v[168:171], v[184:187], v[16:19]
	v_mfma_f32_16x16x32_bf16 v[12:15], v[160:163], v[192:195], v[12:15]
	v_mfma_f32_16x16x32_bf16 v[8:11], v[168:171], v[192:195], v[8:11]
	v_mfma_f32_16x16x32_bf16 v[4:7], v[160:163], v[200:203], v[4:7]
	v_mfma_f32_16x16x32_bf16 v[0:3], v[168:171], v[200:203], v[0:3]
	v_mfma_f32_16x16x32_bf16 v[28:31], v[164:167], v[180:183], v[28:31]
	v_mfma_f32_16x16x32_bf16 v[24:27], v[172:175], v[180:183], v[24:27]
	v_mfma_f32_16x16x32_bf16 v[20:23], v[164:167], v[188:191], v[20:23]
	v_mfma_f32_16x16x32_bf16 v[16:19], v[172:175], v[188:191], v[16:19]
	v_mfma_f32_16x16x32_bf16 v[12:15], v[164:167], v[196:199], v[12:15]
	v_mfma_f32_16x16x32_bf16 v[8:11], v[172:175], v[196:199], v[8:11]
	v_mfma_f32_16x16x32_bf16 v[4:7], v[164:167], v[204:207], v[4:7]
	v_mfma_f32_16x16x32_bf16 v[0:3], v[172:175], v[204:207], v[0:3]
	s_barrier
	s_setprio 0
	s_add_i32 s81, 0, 0x18000
	s_add_i32 s82, 0, 0x1c000
	v_add_u32_e32 v140, s81, v224
	v_add_u32_e32 v172, s82, v224
	v_xor_b32_e32 v255, 64, v140
	ds_read_b128 v[128:131], v140
	ds_read_b128 v[132:135], v255
	ds_read_b128 v[136:139], v140 offset:2048
	ds_read_b128 v[140:143], v255 offset:2048
	v_xor_b32_e32 v255, 64, v172
	ds_read_b128 v[160:163], v172
	ds_read_b128 v[164:167], v255
	ds_read_b128 v[168:171], v172 offset:2048
	ds_read_b128 v[172:175], v255 offset:2048
	s_add_u32 s40, s40, s10
	s_addc_u32 s41, s41, s11
	s_mov_b32 m0, s49
	v_lshl_add_u64 v[230:231], s[40:41], 0, v[144:145]
	ds_read_b128 v[176:179], v228 offset:32768
	ds_read_b128 v[180:183], v252 offset:32768
	ds_read_b128 v[184:187], v228 offset:34816
	ds_read_b128 v[188:191], v252 offset:34816
	ds_read_b128 v[192:195], v228 offset:36864
	ds_read_b128 v[196:199], v252 offset:36864
	ds_read_b128 v[200:203], v228 offset:38912
	ds_read_b128 v[204:207], v252 offset:38912
	global_load_lds_dwordx4 v[230:231], off
	v_lshl_add_u64 v[230:231], s[40:41], 0, v[148:149]
	s_mov_b32 m0, s52
	s_nop 0
	global_load_lds_dwordx4 v[230:231], off
	s_waitcnt vmcnt(8)
	s_waitcnt lgkmcnt(0)
	s_setprio 1
	s_barrier
	v_mfma_f32_16x16x32_bf16 v[124:127], v[128:131], v[176:179], v[124:127]
	v_mfma_f32_16x16x32_bf16 v[120:123], v[136:139], v[176:179], v[120:123]
	v_mfma_f32_16x16x32_bf16 v[116:119], v[128:131], v[184:187], v[116:119]
	v_mfma_f32_16x16x32_bf16 v[112:115], v[136:139], v[184:187], v[112:115]
	v_mfma_f32_16x16x32_bf16 v[108:111], v[128:131], v[192:195], v[108:111]
	v_mfma_f32_16x16x32_bf16 v[104:107], v[136:139], v[192:195], v[104:107]
	v_mfma_f32_16x16x32_bf16 v[100:103], v[128:131], v[200:203], v[100:103]
	v_mfma_f32_16x16x32_bf16 v[96:99], v[136:139], v[200:203], v[96:99]
	v_mfma_f32_16x16x32_bf16 v[124:127], v[132:135], v[180:183], v[124:127]
	v_mfma_f32_16x16x32_bf16 v[120:123], v[140:143], v[180:183], v[120:123]
	v_mfma_f32_16x16x32_bf16 v[116:119], v[132:135], v[188:191], v[116:119]
	v_mfma_f32_16x16x32_bf16 v[112:115], v[140:143], v[188:191], v[112:115]
	v_mfma_f32_16x16x32_bf16 v[108:111], v[132:135], v[196:199], v[108:111]
	v_mfma_f32_16x16x32_bf16 v[104:107], v[140:143], v[196:199], v[104:107]
	v_mfma_f32_16x16x32_bf16 v[100:103], v[132:135], v[204:207], v[100:103]
	v_mfma_f32_16x16x32_bf16 v[96:99], v[140:143], v[204:207], v[96:99]
	v_mfma_f32_16x16x32_bf16 v[60:63], v[160:163], v[176:179], v[60:63]
	v_mfma_f32_16x16x32_bf16 v[56:59], v[168:171], v[176:179], v[56:59]
	v_mfma_f32_16x16x32_bf16 v[52:55], v[160:163], v[184:187], v[52:55]
	v_mfma_f32_16x16x32_bf16 v[48:51], v[168:171], v[184:187], v[48:51]
	v_mfma_f32_16x16x32_bf16 v[44:47], v[160:163], v[192:195], v[44:47]
	v_mfma_f32_16x16x32_bf16 v[40:43], v[168:171], v[192:195], v[40:43]
	v_mfma_f32_16x16x32_bf16 v[36:39], v[160:163], v[200:203], v[36:39]
	v_mfma_f32_16x16x32_bf16 v[32:35], v[168:171], v[200:203], v[32:35]
	v_mfma_f32_16x16x32_bf16 v[60:63], v[164:167], v[180:183], v[60:63]
	v_mfma_f32_16x16x32_bf16 v[56:59], v[172:175], v[180:183], v[56:59]
	v_mfma_f32_16x16x32_bf16 v[52:55], v[164:167], v[188:191], v[52:55]
	v_mfma_f32_16x16x32_bf16 v[48:51], v[172:175], v[188:191], v[48:51]
	v_mfma_f32_16x16x32_bf16 v[44:47], v[164:167], v[196:199], v[44:47]
	v_mfma_f32_16x16x32_bf16 v[40:43], v[172:175], v[196:199], v[40:43]
	v_mfma_f32_16x16x32_bf16 v[36:39], v[164:167], v[204:207], v[36:39]
	v_mfma_f32_16x16x32_bf16 v[32:35], v[172:175], v[204:207], v[32:35]
	s_barrier
	s_setprio 0
	s_add_i32 s40, s81, s44
	v_lshl_add_u64 v[208:209], v[208:209], 0, s[24:25]
	s_mov_b32 m0, s40
	ds_read_b128 v[176:179], v228 offset:49152
	ds_read_b128 v[180:183], v252 offset:49152
	ds_read_b128 v[184:187], v228 offset:51200
	ds_read_b128 v[188:191], v252 offset:51200
	ds_read_b128 v[192:195], v228 offset:53248
	ds_read_b128 v[196:199], v252 offset:53248
	ds_read_b128 v[200:203], v228 offset:55296
	ds_read_b128 v[204:207], v252 offset:55296
	global_load_lds_dwordx4 v[208:209], off
	v_lshl_add_u64 v[208:209], v[210:211], 0, s[24:25]
	s_add_i32 m0, s40, 0x2000
	s_add_i32 s40, s82, s44
	global_load_lds_dwordx4 v[208:209], off
	v_lshl_add_u64 v[208:209], v[212:213], 0, s[24:25]
	s_mov_b32 m0, s40
	s_nop 0
	global_load_lds_dwordx4 v[208:209], off
	v_lshl_add_u64 v[208:209], v[214:215], 0, s[24:25]
	s_add_i32 m0, s40, 0x2000
	s_nop 0
	global_load_lds_dwordx4 v[208:209], off
	v_lshl_add_u64 v[208:209], v[216:217], 0, s[24:25]
	s_mov_b32 m0, s54
	s_nop 0
	global_load_lds_dwordx4 v[208:209], off
	v_lshl_add_u64 v[208:209], v[218:219], 0, s[24:25]
	s_mov_b32 m0, s55
	s_nop 0
	global_load_lds_dwordx4 v[208:209], off
	s_waitcnt vmcnt(8)
	s_waitcnt lgkmcnt(0)
	s_setprio 1
	s_barrier
	v_mfma_f32_16x16x32_bf16 v[92:95], v[128:131], v[176:179], v[92:95]
	v_mfma_f32_16x16x32_bf16 v[88:91], v[136:139], v[176:179], v[88:91]
	v_mfma_f32_16x16x32_bf16 v[84:87], v[128:131], v[184:187], v[84:87]
	v_mfma_f32_16x16x32_bf16 v[80:83], v[136:139], v[184:187], v[80:83]
	v_mfma_f32_16x16x32_bf16 v[76:79], v[128:131], v[192:195], v[76:79]
	v_mfma_f32_16x16x32_bf16 v[72:75], v[136:139], v[192:195], v[72:75]
	v_mfma_f32_16x16x32_bf16 v[68:71], v[128:131], v[200:203], v[68:71]
	v_mfma_f32_16x16x32_bf16 v[64:67], v[136:139], v[200:203], v[64:67]
	v_mfma_f32_16x16x32_bf16 v[92:95], v[132:135], v[180:183], v[92:95]
	v_mfma_f32_16x16x32_bf16 v[88:91], v[140:143], v[180:183], v[88:91]
	v_mfma_f32_16x16x32_bf16 v[84:87], v[132:135], v[188:191], v[84:87]
	v_mfma_f32_16x16x32_bf16 v[80:83], v[140:143], v[188:191], v[80:83]
	v_mfma_f32_16x16x32_bf16 v[76:79], v[132:135], v[196:199], v[76:79]
	v_mfma_f32_16x16x32_bf16 v[72:75], v[140:143], v[196:199], v[72:75]
	v_mfma_f32_16x16x32_bf16 v[68:71], v[132:135], v[204:207], v[68:71]
	v_mfma_f32_16x16x32_bf16 v[64:67], v[140:143], v[204:207], v[64:67]
	v_mfma_f32_16x16x32_bf16 v[28:31], v[160:163], v[176:179], v[28:31]
	v_mfma_f32_16x16x32_bf16 v[24:27], v[168:171], v[176:179], v[24:27]
	v_mfma_f32_16x16x32_bf16 v[20:23], v[160:163], v[184:187], v[20:23]
	v_mfma_f32_16x16x32_bf16 v[16:19], v[168:171], v[184:187], v[16:19]
	v_mfma_f32_16x16x32_bf16 v[12:15], v[160:163], v[192:195], v[12:15]
	v_mfma_f32_16x16x32_bf16 v[8:11], v[168:171], v[192:195], v[8:11]
	v_mfma_f32_16x16x32_bf16 v[4:7], v[160:163], v[200:203], v[4:7]
	v_mfma_f32_16x16x32_bf16 v[0:3], v[168:171], v[200:203], v[0:3]
	v_mfma_f32_16x16x32_bf16 v[28:31], v[164:167], v[180:183], v[28:31]
	v_mfma_f32_16x16x32_bf16 v[24:27], v[172:175], v[180:183], v[24:27]
	v_mfma_f32_16x16x32_bf16 v[20:23], v[164:167], v[188:191], v[20:23]
	v_mfma_f32_16x16x32_bf16 v[16:19], v[172:175], v[188:191], v[16:19]
	v_mfma_f32_16x16x32_bf16 v[12:15], v[164:167], v[196:199], v[12:15]
	v_mfma_f32_16x16x32_bf16 v[8:11], v[172:175], v[196:199], v[8:11]
	v_mfma_f32_16x16x32_bf16 v[4:7], v[164:167], v[204:207], v[4:7]
	v_mfma_f32_16x16x32_bf16 v[0:3], v[172:175], v[204:207], v[0:3]
	s_barrier
	s_setprio 0
	s_add_u32 s0, s0, 0x100
	s_addc_u32 s1, s1, 0
	s_add_u32 s42, s42, 0x100
	s_addc_u32 s43, s43, 0
	s_cmp_ge_i32 s80, s56
	s_mov_b32 s40, s80
	s_cbranch_scc0 .LBB0_1292

.LBB0_1372:
	v_bfe_i32 v2, v12, 27, 1
	v_lshlrev_b32_e32 v0, 4, v12
	v_lshrrev_b32_e32 v2, 22, v2
	v_add_u32_e32 v2, v0, v2
	v_and_b32_e32 v2, 0xfffffc00, v2
	v_sub_u32_e32 v2, v0, v2
	v_ashrrev_i32_e32 v1, 31, v12
	v_lshrrev_b32_e32 v3, 4, v2
	v_lshrrev_b32_e32 v1, 26, v1
	v_bitop3_b32 v2, v3, v2, 32 bitop3:0x6c
	v_add_u32_e32 v1, v12, v1
	v_ashrrev_i32_e32 v4, 31, v2
	v_ashrrev_i32_e32 v1, 6, v1
	v_lshrrev_b32_e32 v4, 26, v4
	v_lshlrev_b32_e32 v3, 3, v1
	v_add_u32_e32 v4, v2, v4
	v_and_b32_e32 v3, -16, v3
	v_ashrrev_i32_e32 v5, 6, v4
	v_lshlrev_b32_e32 v1, 5, v1
	v_add_u32_e32 v3, v5, v3
	v_and_b32_e32 v13, 32, v1
	v_and_b32_e32 v1, 0xc0, v4
	s_ashr_i32 s6, s1, 3
	v_sub_u32_e32 v1, v2, v1
	v_mov_b32_e32 v2, 1
	v_lshlrev_b32_e32 v4, 1, v3
	v_lshrrev_b32_e32 v6, 2, v3
	v_and_b32_e32 v5, 3, v5
	s_mov_b32 s1, 0x7fffffe0
	v_ashrrev_i16_sdwa v1, v2, sext(v1) dst_sel:DWORD dst_unused:UNUSED_PAD src0_sel:DWORD src1_sel:BYTE_0
	v_and_b32_e32 v4, 24, v4
	v_and_b32_e32 v6, 4, v6
	v_and_or_b32 v5, v3, s1, v5
	v_bfe_i32 v14, v1, 0, 16
	v_or3_b32 v4, v5, v6, v4
	v_add_u32_e32 v1, v13, v14
	v_mul_lo_u32 v15, v3, s0
	v_mul_lo_u32 v3, v4, s0
	v_add_u32_e32 v0, 0x2000, v0
	s_add_u32 s35, s74, 0x7b00000
	v_lshrrev_b32_e32 v252, 3, v220
	v_bfe_u32 v253, v220, 4, 2
	v_bfe_u32 v254, v220, 6, 1
	v_lshl_or_b32 v253, v254, 2, v253
	v_and_b32_e32 v254, 7, v220
	v_xor_b32_e32 v253, v254, v253
	v_lshlrev_b32_e32 v253, 4, v253
	v_and_b32_e32 v254, 32, v252
	v_bfe_u32 v255, v252, 2, 2
	v_lshl_or_b32 v254, v255, 3, v254
	v_bfe_u32 v255, v252, 4, 1
	v_lshl_or_b32 v254, v255, 2, v254
	v_and_b32_e32 v255, 3, v252
	v_or_b32_e32 v254, v254, v255
	v_mul_u32_u24_e32 v254, 0x1000, v254
	v_add_u32_e32 v254, v254, v253
	v_add_u32_e32 v255, 0x40000, v254
	v_mul_u32_u24_e32 v252, 0x1000, v252
	v_add_u32_e32 v252, v252, v253
	v_add_u32_e32 v253, 0x40000, v252
	v_mov_b32_e32 v144, v252
	v_mov_b32_e32 v146, v254
	v_ashrrev_i32_e32 v1, 31, v0
	s_addc_u32 s40, s75, 0
	v_lshrrev_b32_e32 v1, 22, v1
	s_add_i32 s6, s8, s6
	v_add_u32_e32 v1, v0, v1
	s_ashr_i32 s8, s6, 31
	v_ashrrev_i32_e32 v1, 10, v1
	s_lshr_b32 s8, s8, 25
	v_mul_i32_i24_e32 v3, 0x400, v1
	s_add_i32 s8, s6, s8
	v_sub_u32_e32 v0, v0, v3
	s_ashr_i32 s9, s8, 7
	s_and_b32 s8, s8, 0xffffff80
	v_lshrrev_b32_e32 v3, 4, v0
	s_sub_i32 s8, s6, s8
	v_bitop3_b32 v0, v3, v0, 32 bitop3:0x6c
	s_bfe_i32 s6, s8, 0x80000
	v_ashrrev_i32_e32 v4, 31, v0
	s_bfe_u32 s6, s6, 0x2000d
	v_lshrrev_b32_e32 v4, 26, v4
	s_add_i32 s10, s8, s6
	v_lshlrev_b32_e32 v3, 3, v1
	v_add_u32_e32 v4, v0, v4
	s_bfe_i32 s6, s10, 0x80000
	s_and_b32 s10, s10, 0xfc
	v_and_b32_e32 v3, -16, v3
	v_ashrrev_i32_e32 v5, 6, v4
	v_lshlrev_b32_e32 v1, 5, v1
	s_sub_i32 s8, s8, s10
	v_add_u32_e32 v3, v5, v3
	v_and_b32_e32 v16, 32, v1
	v_and_b32_e32 v1, 0xc0, v4
	v_and_b32_e32 v4, 3, v5
	s_lshl_b32 s9, s9, 2
	s_sext_i32_i8 s8, s8
	v_and_or_b32 v4, v3, s1, v4
	s_ashr_i32 s1, s0, 31
	s_add_i32 s62, s9, s8
	s_lshl_b64 s[14:15], s[0:1], 9
	s_ashr_i32 s8, s62, 31
	s_mul_i32 s8, s14, s8
	s_mul_hi_u32 s9, s14, s62
	s_sext_i32_i16 s20, s6
	s_add_i32 s10, s9, s8
	s_lshr_b64 s[8:9], s[0:1], 23
	s_ashr_i32 s7, s30, 6
	s_lshr_b32 s6, s20, 2
	s_mul_i32 s9, s8, s62
	s_add_i32 s22, s10, s9
	s_bfe_i64 s[10:11], s[6:7], 0x100000
	s_ashr_i32 s9, s20, 2
	s_mul_hi_u32 s10, s14, s9
	s_mul_i32 s11, s14, s11
	s_add_i32 s10, s10, s11
	s_mul_i32 s8, s8, s9
	v_sub_u32_e32 v0, v0, v1
	s_ashr_i32 s28, s30, 8
	s_lshl_b64 s[12:13], s[0:1], 8
	s_lshl_b32 s41, s7, 10
	s_add_i32 s10, s10, s8
	s_mul_i32 s8, s14, s9
	v_ashrrev_i16_sdwa v0, v2, sext(v0) dst_sel:DWORD dst_unused:UNUSED_PAD src0_sel:DWORD src1_sel:BYTE_0
	v_lshlrev_b32_e32 v1, 1, v3
	v_lshrrev_b32_e32 v2, 2, v3
	s_add_u32 s8, s35, s8
	v_and_b32_e32 v1, 24, v1
	v_and_b32_e32 v2, 4, v2
	s_addc_u32 s9, s40, s10
	s_add_i32 s42, s41, 0
	v_bfe_i32 v17, v0, 0, 16
	v_or3_b32 v1, v4, v2, v1
	s_add_i32 m0, s42, 0x10000
	v_add_u32_e32 v0, v16, v17
	v_mul_lo_u32 v1, v1, s0
	global_load_lds_dwordx4 v146, s[8:9]
	s_add_i32 m0, s42, 0x12000
	v_mov_b32_e32 v150, v255
	s_add_u32 s20, s8, s12
	global_load_lds_dwordx4 v150, s[8:9]
	s_addc_u32 s21, s9, s13
	s_add_i32 m0, s42, 0x14000
	s_mul_i32 s23, s14, s62
	global_load_lds_dwordx4 v146, s[20:21]
	s_add_i32 m0, s42, 0x16000
	s_add_u32 s10, s16, s23
	s_addc_u32 s11, s17, s22
	s_add_i32 s43, s42, 0x2000
	v_mul_lo_u32 v18, v3, s0
	global_load_lds_dwordx4 v150, s[20:21]
	s_mov_b32 m0, s42
	s_add_u32 s22, s10, s12
	v_mov_b32_e32 v148, v253
	global_load_lds_dwordx4 v144, s[10:11]
	s_mov_b32 m0, s43
	s_addc_u32 s23, s11, s13
	s_add_i32 s44, s42, 0x4000
	global_load_lds_dwordx4 v148, s[10:11]
	s_mov_b32 m0, s44
	s_add_i32 s45, s42, 0x6000
	global_load_lds_dwordx4 v144, s[22:23]
	s_mov_b32 m0, s45
	v_mov_b32_e32 v147, 0
	global_load_lds_dwordx4 v148, s[22:23]
	v_mov_b32_e32 v151, v147
	v_mov_b32_e32 v145, v147
	v_mov_b32_e32 v149, v147
	s_cmp_eq_u32 s28, 1
	s_mov_b32 s47, 0
	v_lshl_add_u64 v[8:9], s[8:9], 0, v[146:147]
	v_lshl_add_u64 v[4:5], s[8:9], 0, v[150:151]
	v_lshl_add_u64 v[2:3], s[20:21], 0, v[146:147]
	v_lshl_add_u64 v[0:1], s[20:21], 0, v[150:151]
	v_lshl_add_u64 v[6:7], s[10:11], 0, v[144:145]
	s_cselect_b64 s[20:21], -1, 0
	s_cmp_lg_u32 s28, 1
	v_lshl_add_u64 v[10:11], s[10:11], 0, v[148:149]
	s_cbranch_scc1 .LBB0_1374
	s_barrier
.LBB0_1374:
	s_add_u32 s22, s74, 0x1fb16800
	s_addc_u32 s23, s75, 0
	s_add_u32 s24, s74, 0x1fb1e800
	s_mov_b64 s[26:27], 0x80
	s_addc_u32 s25, s75, 0
	s_add_i32 m0, s42, 0x18000
	v_lshl_add_u64 v[8:9], v[8:9], 0, s[26:27]
	s_waitcnt vmcnt(2)
	s_barrier
	global_load_lds_dwordx4 v[8:9], off
	v_lshl_add_u64 v[4:5], v[4:5], 0, s[26:27]
	s_add_i32 m0, s42, 0x1a000
	s_add_i32 s48, s42, 0x8000
	global_load_lds_dwordx4 v[4:5], off
	v_lshl_add_u64 v[4:5], v[6:7], 0, s[26:27]
	s_mov_b32 m0, s48
	s_add_i32 s49, s42, 0xa000
	global_load_lds_dwordx4 v[4:5], off
	v_lshl_add_u64 v[4:5], v[10:11], 0, s[26:27]
	s_mov_b32 m0, s49
	v_lshl_add_u64 v[2:3], v[2:3], 0, s[26:27]
	global_load_lds_dwordx4 v[4:5], off
	s_add_i32 m0, s42, 0x1c000
	v_lshl_add_u64 v[0:1], v[0:1], 0, s[26:27]
	global_load_lds_dwordx4 v[2:3], off
	s_add_i32 m0, s42, 0x1e000
	s_lshr_b32 s1, s1, 26
	global_load_lds_dwordx4 v[0:1], off
	v_lshrrev_b32_e32 v1, 1, v12
	v_and_b32_e32 v1, 24, v1
	v_and_b32_e32 v0, 15, v12
	v_lshlrev_b32_e32 v2, 1, v1
	s_add_i32 s1, s0, s1
	v_lshl_or_b32 v175, s28, 6, v0
	v_lshl_or_b32 v0, v0, 6, v2
	v_lshlrev_b32_e32 v2, 2, v12
	s_ashr_i32 s52, s1, 6
	s_lshl_b32 s1, s28, 13
	v_and_b32_e32 v2, 32, v2
	v_bitop3_b32 v3, v0, s1, v2 bitop3:0xde
	s_lshl_b32 s1, s7, 5
	s_and_b32 s1, s1, 0x60
	s_sext_i32_i8 s61, s6
	s_lshl_b32 s6, s1, 7
	v_and_b32_e32 v252, 15, v220
	v_bfe_u32 v253, v220, 4, 2
	v_bfe_u32 v254, v252, 1, 2
	v_xor_b32_e32 v253, v253, v254
	v_bfe_u32 v254, v252, 3, 1
	v_lshl_or_b32 v253, v254, 2, v253
	v_lshlrev_b32_e32 v253, 4, v253
	v_lshl_or_b32 v253, v252, 7, v253
	v_lshrrev_b32_e32 v254, 6, v220
	v_lshrrev_b32_e32 v255, 2, v254
	v_lshl_or_b32 v252, v255, 13, v253
	v_and_b32_e32 v254, 3, v254
	v_lshl_or_b32 v253, v254, 12, v253
	v_mov_b32_e32 v177, v253
	s_cmp_gt_i32 s0, 63
	v_add_u32_e32 v0, v15, v13
	s_cselect_b64 s[28:29], -1, 0
	s_add_i32 s53, s52, -2
	v_or_b32_e32 v181, s1, v1
	v_mov_b32_e32 v0, v144
	v_mov_b32_e32 v1, v147
	s_waitcnt vmcnt(6)
	s_cmpk_lt_u32 s30, 0x100
	v_lshl_add_u64 v[152:153], s[12:13], 0, v[0:1]
	v_add_u32_e32 v0, v18, v16
	s_cselect_b64 s[30:31], -1, 0
	v_readlane_b32 s6, v251, 1
	v_mov_b32_e32 v0, v148
	s_add_i32 s56, 0, 0x10000
	s_add_i32 s57, 0, 0x14000
	s_ashr_i32 s54, s6, 31
	s_mov_b32 s55, s6
	v_lshl_add_u64 v[154:155], s[12:13], 0, v[0:1]
	s_waitcnt vmcnt(0)
	v_mov_b64_e32 v[156:157], 0x800
	v_mov_b64_e32 v[158:159], 0x7ff
	v_add_u32_e32 v183, s56, v177
	v_add_u32_e32 v185, s57, v177
	v_mov_b32_e32 v187, v252
	v_xor_b32_e32 v252, 64, v187
	v_xor_b32_e32 v253, 64, v183
	v_xor_b32_e32 v254, 64, v185
	s_mov_b32 s34, 0x3a000000
	s_mov_b32 s58, 0xf800000
	v_mov_b32_e32 v189, 0x260
	s_barrier
	v_readlane_b32 s7, v251, 2
	s_branch .LBB0_1377

.LBB0_1389:
	ds_read_b128 v[128:131], v183
	ds_read_b128 v[132:135], v253
	ds_read_b128 v[136:139], v183 offset:2048
	ds_read_b128 v[140:143], v253 offset:2048
	ds_read_b128 v[160:163], v185
	ds_read_b128 v[164:167], v254
	ds_read_b128 v[168:171], v185 offset:2048
	ds_read_b128 v[190:193], v254 offset:2048
	s_add_i32 s63, s8, 2
	s_add_u32 s76, s0, 0x80
	s_addc_u32 s9, s1, 0
	s_cmp_eq_u32 s53, s8
	s_cselect_b32 s8, s36, s76
	s_cselect_b32 s9, s37, s9
	s_cselect_b32 s77, s39, s11
	s_cselect_b32 s76, s38, s10
	v_lshl_add_u64 v[172:173], s[0:1], 0, v[152:153]
	s_add_i32 m0, s42, 0xc000
	ds_read_b128 v[194:197], v187
	ds_read_b128 v[198:201], v252
	ds_read_b128 v[202:205], v187 offset:2048
	ds_read_b128 v[206:209], v252 offset:2048
	ds_read_b128 v[210:213], v187 offset:4096
	ds_read_b128 v[214:217], v252 offset:4096
	ds_read_b128 v[224:227], v187 offset:6144
	ds_read_b128 v[228:231], v252 offset:6144
	global_load_lds_dwordx4 v[172:173], off
	v_lshl_add_u64 v[172:173], s[0:1], 0, v[154:155]
	s_add_i32 m0, s42, 0xe000
	s_nop 0
	global_load_lds_dwordx4 v[172:173], off
	s_waitcnt vmcnt(8)
	s_waitcnt lgkmcnt(0)
	s_setprio 1
	s_barrier
	v_mfma_f32_16x16x32_bf16 v[124:127], v[128:131], v[194:197], v[124:127]
	v_mfma_f32_16x16x32_bf16 v[120:123], v[136:139], v[194:197], v[120:123]
	v_mfma_f32_16x16x32_bf16 v[116:119], v[128:131], v[202:205], v[116:119]
	v_mfma_f32_16x16x32_bf16 v[112:115], v[136:139], v[202:205], v[112:115]
	v_mfma_f32_16x16x32_bf16 v[108:111], v[128:131], v[210:213], v[108:111]
	v_mfma_f32_16x16x32_bf16 v[104:107], v[136:139], v[210:213], v[104:107]
	v_mfma_f32_16x16x32_bf16 v[100:103], v[128:131], v[224:227], v[100:103]
	v_mfma_f32_16x16x32_bf16 v[96:99], v[136:139], v[224:227], v[96:99]
	v_mfma_f32_16x16x32_bf16 v[124:127], v[132:135], v[198:201], v[124:127]
	v_mfma_f32_16x16x32_bf16 v[120:123], v[140:143], v[198:201], v[120:123]
	v_mfma_f32_16x16x32_bf16 v[116:119], v[132:135], v[206:209], v[116:119]
	v_mfma_f32_16x16x32_bf16 v[112:115], v[140:143], v[206:209], v[112:115]
	v_mfma_f32_16x16x32_bf16 v[108:111], v[132:135], v[214:217], v[108:111]
	v_mfma_f32_16x16x32_bf16 v[104:107], v[140:143], v[214:217], v[104:107]
	v_mfma_f32_16x16x32_bf16 v[100:103], v[132:135], v[228:231], v[100:103]
	v_mfma_f32_16x16x32_bf16 v[96:99], v[140:143], v[228:231], v[96:99]
	v_mfma_f32_16x16x32_bf16 v[60:63], v[160:163], v[194:197], v[60:63]
	v_mfma_f32_16x16x32_bf16 v[56:59], v[168:171], v[194:197], v[56:59]
	v_mfma_f32_16x16x32_bf16 v[52:55], v[160:163], v[202:205], v[52:55]
	v_mfma_f32_16x16x32_bf16 v[48:51], v[168:171], v[202:205], v[48:51]
	v_mfma_f32_16x16x32_bf16 v[44:47], v[160:163], v[210:213], v[44:47]
	v_mfma_f32_16x16x32_bf16 v[40:43], v[168:171], v[210:213], v[40:43]
	v_mfma_f32_16x16x32_bf16 v[36:39], v[160:163], v[224:227], v[36:39]
	v_mfma_f32_16x16x32_bf16 v[32:35], v[168:171], v[224:227], v[32:35]
	v_mfma_f32_16x16x32_bf16 v[60:63], v[164:167], v[198:201], v[60:63]
	v_mfma_f32_16x16x32_bf16 v[56:59], v[190:193], v[198:201], v[56:59]
	v_mfma_f32_16x16x32_bf16 v[52:55], v[164:167], v[206:209], v[52:55]
	v_mfma_f32_16x16x32_bf16 v[48:51], v[190:193], v[206:209], v[48:51]
	v_mfma_f32_16x16x32_bf16 v[44:47], v[164:167], v[214:217], v[44:47]
	v_mfma_f32_16x16x32_bf16 v[40:43], v[190:193], v[214:217], v[40:43]
	v_mfma_f32_16x16x32_bf16 v[36:39], v[164:167], v[228:231], v[36:39]
	v_mfma_f32_16x16x32_bf16 v[32:35], v[190:193], v[228:231], v[32:35]
	s_barrier
	s_setprio 0
	s_add_i32 s78, s56, s41
	v_lshl_add_u64 v[172:173], s[76:77], 0, v[146:147]
	s_mov_b32 m0, s78
	ds_read_b128 v[194:197], v187 offset:16384
	ds_read_b128 v[198:201], v252 offset:16384
	ds_read_b128 v[202:205], v187 offset:18432
	ds_read_b128 v[206:209], v252 offset:18432
	ds_read_b128 v[210:213], v187 offset:20480
	ds_read_b128 v[214:217], v252 offset:20480
	ds_read_b128 v[224:227], v187 offset:22528
	ds_read_b128 v[228:231], v252 offset:22528
	global_load_lds_dwordx4 v[172:173], off
	s_add_i32 m0, s78, 0x2000
	v_lshl_add_u64 v[178:179], s[76:77], 0, v[150:151]
	s_add_u32 s76, s76, s12
	s_addc_u32 s77, s77, s13
	s_add_i32 s78, s57, s41
	global_load_lds_dwordx4 v[178:179], off
	v_lshl_add_u64 v[218:219], s[76:77], 0, v[146:147]
	s_mov_b32 m0, s78
	v_lshl_add_u64 v[232:233], s[76:77], 0, v[150:151]
	global_load_lds_dwordx4 v[218:219], off
	s_add_i32 m0, s78, 0x2000
	v_lshl_add_u64 v[234:235], s[8:9], 0, v[144:145]
	global_load_lds_dwordx4 v[232:233], off
	s_mov_b32 m0, s42
	v_lshl_add_u64 v[236:237], s[8:9], 0, v[148:149]
	global_load_lds_dwordx4 v[234:235], off
	s_mov_b32 m0, s43
	s_nop 0
	global_load_lds_dwordx4 v[236:237], off
	s_waitcnt vmcnt(8)
	s_waitcnt lgkmcnt(0)
	s_setprio 1
	s_barrier
	v_mfma_f32_16x16x32_bf16 v[92:95], v[128:131], v[194:197], v[92:95]
	v_mfma_f32_16x16x32_bf16 v[88:91], v[136:139], v[194:197], v[88:91]
	v_mfma_f32_16x16x32_bf16 v[84:87], v[128:131], v[202:205], v[84:87]
	v_mfma_f32_16x16x32_bf16 v[80:83], v[136:139], v[202:205], v[80:83]
	v_mfma_f32_16x16x32_bf16 v[76:79], v[128:131], v[210:213], v[76:79]
	v_mfma_f32_16x16x32_bf16 v[72:75], v[136:139], v[210:213], v[72:75]
	v_mfma_f32_16x16x32_bf16 v[68:71], v[128:131], v[224:227], v[68:71]
	v_mfma_f32_16x16x32_bf16 v[64:67], v[136:139], v[224:227], v[64:67]
	v_mfma_f32_16x16x32_bf16 v[92:95], v[132:135], v[198:201], v[92:95]
	v_mfma_f32_16x16x32_bf16 v[88:91], v[140:143], v[198:201], v[88:91]
	v_mfma_f32_16x16x32_bf16 v[84:87], v[132:135], v[206:209], v[84:87]
	v_mfma_f32_16x16x32_bf16 v[80:83], v[140:143], v[206:209], v[80:83]
	v_mfma_f32_16x16x32_bf16 v[76:79], v[132:135], v[214:217], v[76:79]
	v_mfma_f32_16x16x32_bf16 v[72:75], v[140:143], v[214:217], v[72:75]
	v_mfma_f32_16x16x32_bf16 v[68:71], v[132:135], v[228:231], v[68:71]
	v_mfma_f32_16x16x32_bf16 v[64:67], v[140:143], v[228:231], v[64:67]
	v_mfma_f32_16x16x32_bf16 v[28:31], v[160:163], v[194:197], v[28:31]
	v_mfma_f32_16x16x32_bf16 v[24:27], v[168:171], v[194:197], v[24:27]
	v_mfma_f32_16x16x32_bf16 v[20:23], v[160:163], v[202:205], v[20:23]
	v_mfma_f32_16x16x32_bf16 v[16:19], v[168:171], v[202:205], v[16:19]
	v_mfma_f32_16x16x32_bf16 v[12:15], v[160:163], v[210:213], v[12:15]
	v_mfma_f32_16x16x32_bf16 v[8:11], v[168:171], v[210:213], v[8:11]
	v_mfma_f32_16x16x32_bf16 v[4:7], v[160:163], v[224:227], v[4:7]
	v_mfma_f32_16x16x32_bf16 v[0:3], v[168:171], v[224:227], v[0:3]
	v_mfma_f32_16x16x32_bf16 v[28:31], v[164:167], v[198:201], v[28:31]
	v_mfma_f32_16x16x32_bf16 v[24:27], v[190:193], v[198:201], v[24:27]
	v_mfma_f32_16x16x32_bf16 v[20:23], v[164:167], v[206:209], v[20:23]
	v_mfma_f32_16x16x32_bf16 v[16:19], v[190:193], v[206:209], v[16:19]
	v_mfma_f32_16x16x32_bf16 v[12:15], v[164:167], v[214:217], v[12:15]
	v_mfma_f32_16x16x32_bf16 v[8:11], v[190:193], v[214:217], v[8:11]
	v_mfma_f32_16x16x32_bf16 v[4:7], v[164:167], v[228:231], v[4:7]
	v_mfma_f32_16x16x32_bf16 v[0:3], v[190:193], v[228:231], v[0:3]
	s_barrier
	s_setprio 0
	s_add_i32 s76, 0, 0x18000
	s_add_i32 s77, 0, 0x1c000
	v_add_u32_e32 v140, s76, v177
	v_add_u32_e32 v174, s77, v177
	v_xor_b32_e32 v255, 64, v140
	ds_read_b128 v[128:131], v140
	ds_read_b128 v[132:135], v255
	ds_read_b128 v[136:139], v140 offset:2048
	ds_read_b128 v[140:143], v255 offset:2048
	v_xor_b32_e32 v255, 64, v174
	ds_read_b128 v[160:163], v174
	ds_read_b128 v[164:167], v255
	ds_read_b128 v[168:171], v174 offset:2048
	ds_read_b128 v[190:193], v255 offset:2048
	s_add_u32 s8, s8, s12
	s_addc_u32 s9, s9, s13
	s_mov_b32 m0, s44
	v_lshl_add_u64 v[238:239], s[8:9], 0, v[144:145]
	ds_read_b128 v[194:197], v187 offset:32768
	ds_read_b128 v[198:201], v252 offset:32768
	ds_read_b128 v[202:205], v187 offset:34816
	ds_read_b128 v[206:209], v252 offset:34816
	ds_read_b128 v[210:213], v187 offset:36864
	ds_read_b128 v[214:217], v252 offset:36864
	ds_read_b128 v[224:227], v187 offset:38912
	ds_read_b128 v[228:231], v252 offset:38912
	global_load_lds_dwordx4 v[238:239], off
	v_lshl_add_u64 v[238:239], s[8:9], 0, v[148:149]
	s_mov_b32 m0, s45
	s_nop 0
	global_load_lds_dwordx4 v[238:239], off
	s_waitcnt vmcnt(8)
	s_waitcnt lgkmcnt(0)
	s_setprio 1
	s_barrier
	v_mfma_f32_16x16x32_bf16 v[124:127], v[128:131], v[194:197], v[124:127]
	v_mfma_f32_16x16x32_bf16 v[120:123], v[136:139], v[194:197], v[120:123]
	v_mfma_f32_16x16x32_bf16 v[116:119], v[128:131], v[202:205], v[116:119]
	v_mfma_f32_16x16x32_bf16 v[112:115], v[136:139], v[202:205], v[112:115]
	v_mfma_f32_16x16x32_bf16 v[108:111], v[128:131], v[210:213], v[108:111]
	v_mfma_f32_16x16x32_bf16 v[104:107], v[136:139], v[210:213], v[104:107]
	v_mfma_f32_16x16x32_bf16 v[100:103], v[128:131], v[224:227], v[100:103]
	v_mfma_f32_16x16x32_bf16 v[96:99], v[136:139], v[224:227], v[96:99]
	v_mfma_f32_16x16x32_bf16 v[124:127], v[132:135], v[198:201], v[124:127]
	v_mfma_f32_16x16x32_bf16 v[120:123], v[140:143], v[198:201], v[120:123]
	v_mfma_f32_16x16x32_bf16 v[116:119], v[132:135], v[206:209], v[116:119]
	v_mfma_f32_16x16x32_bf16 v[112:115], v[140:143], v[206:209], v[112:115]
	v_mfma_f32_16x16x32_bf16 v[108:111], v[132:135], v[214:217], v[108:111]
	v_mfma_f32_16x16x32_bf16 v[104:107], v[140:143], v[214:217], v[104:107]
	v_mfma_f32_16x16x32_bf16 v[100:103], v[132:135], v[228:231], v[100:103]
	v_mfma_f32_16x16x32_bf16 v[96:99], v[140:143], v[228:231], v[96:99]
	v_mfma_f32_16x16x32_bf16 v[60:63], v[160:163], v[194:197], v[60:63]
	v_mfma_f32_16x16x32_bf16 v[56:59], v[168:171], v[194:197], v[56:59]
	v_mfma_f32_16x16x32_bf16 v[52:55], v[160:163], v[202:205], v[52:55]
	v_mfma_f32_16x16x32_bf16 v[48:51], v[168:171], v[202:205], v[48:51]
	v_mfma_f32_16x16x32_bf16 v[44:47], v[160:163], v[210:213], v[44:47]
	v_mfma_f32_16x16x32_bf16 v[40:43], v[168:171], v[210:213], v[40:43]
	v_mfma_f32_16x16x32_bf16 v[36:39], v[160:163], v[224:227], v[36:39]
	v_mfma_f32_16x16x32_bf16 v[32:35], v[168:171], v[224:227], v[32:35]
	v_mfma_f32_16x16x32_bf16 v[60:63], v[164:167], v[198:201], v[60:63]
	v_mfma_f32_16x16x32_bf16 v[56:59], v[190:193], v[198:201], v[56:59]
	v_mfma_f32_16x16x32_bf16 v[52:55], v[164:167], v[206:209], v[52:55]
	v_mfma_f32_16x16x32_bf16 v[48:51], v[190:193], v[206:209], v[48:51]
	v_mfma_f32_16x16x32_bf16 v[44:47], v[164:167], v[214:217], v[44:47]
	v_mfma_f32_16x16x32_bf16 v[40:43], v[190:193], v[214:217], v[40:43]
	v_mfma_f32_16x16x32_bf16 v[36:39], v[164:167], v[228:231], v[36:39]
	v_mfma_f32_16x16x32_bf16 v[32:35], v[190:193], v[228:231], v[32:35]
	s_barrier
	s_setprio 0
	s_add_i32 s8, s76, s41
	v_lshl_add_u64 v[172:173], v[172:173], 0, s[26:27]
	s_mov_b32 m0, s8
	ds_read_b128 v[194:197], v187 offset:49152
	ds_read_b128 v[198:201], v252 offset:49152
	ds_read_b128 v[202:205], v187 offset:51200
	ds_read_b128 v[206:209], v252 offset:51200
	ds_read_b128 v[210:213], v187 offset:53248
	ds_read_b128 v[214:217], v252 offset:53248
	ds_read_b128 v[224:227], v187 offset:55296
	ds_read_b128 v[228:231], v252 offset:55296
	global_load_lds_dwordx4 v[172:173], off
	v_lshl_add_u64 v[172:173], v[178:179], 0, s[26:27]
	s_add_i32 m0, s8, 0x2000
	s_add_i32 s8, s77, s41
	global_load_lds_dwordx4 v[172:173], off
	v_lshl_add_u64 v[172:173], v[218:219], 0, s[26:27]
	s_mov_b32 m0, s8
	s_nop 0
	global_load_lds_dwordx4 v[172:173], off
	v_lshl_add_u64 v[172:173], v[232:233], 0, s[26:27]
	s_add_i32 m0, s8, 0x2000
	s_nop 0
	global_load_lds_dwordx4 v[172:173], off
	v_lshl_add_u64 v[172:173], v[234:235], 0, s[26:27]
	s_mov_b32 m0, s48
	s_nop 0
	global_load_lds_dwordx4 v[172:173], off
	v_lshl_add_u64 v[172:173], v[236:237], 0, s[26:27]
	s_mov_b32 m0, s49
	s_nop 0
	global_load_lds_dwordx4 v[172:173], off
	s_waitcnt vmcnt(8)
	s_waitcnt lgkmcnt(0)
	s_setprio 1
	s_barrier
	v_mfma_f32_16x16x32_bf16 v[92:95], v[128:131], v[194:197], v[92:95]
	v_mfma_f32_16x16x32_bf16 v[88:91], v[136:139], v[194:197], v[88:91]
	v_mfma_f32_16x16x32_bf16 v[84:87], v[128:131], v[202:205], v[84:87]
	v_mfma_f32_16x16x32_bf16 v[80:83], v[136:139], v[202:205], v[80:83]
	v_mfma_f32_16x16x32_bf16 v[76:79], v[128:131], v[210:213], v[76:79]
	v_mfma_f32_16x16x32_bf16 v[72:75], v[136:139], v[210:213], v[72:75]
	v_mfma_f32_16x16x32_bf16 v[68:71], v[128:131], v[224:227], v[68:71]
	v_mfma_f32_16x16x32_bf16 v[64:67], v[136:139], v[224:227], v[64:67]
	v_mfma_f32_16x16x32_bf16 v[92:95], v[132:135], v[198:201], v[92:95]
	v_mfma_f32_16x16x32_bf16 v[88:91], v[140:143], v[198:201], v[88:91]
	v_mfma_f32_16x16x32_bf16 v[84:87], v[132:135], v[206:209], v[84:87]
	v_mfma_f32_16x16x32_bf16 v[80:83], v[140:143], v[206:209], v[80:83]
	v_mfma_f32_16x16x32_bf16 v[76:79], v[132:135], v[214:217], v[76:79]
	v_mfma_f32_16x16x32_bf16 v[72:75], v[140:143], v[214:217], v[72:75]
	v_mfma_f32_16x16x32_bf16 v[68:71], v[132:135], v[228:231], v[68:71]
	v_mfma_f32_16x16x32_bf16 v[64:67], v[140:143], v[228:231], v[64:67]
	v_mfma_f32_16x16x32_bf16 v[28:31], v[160:163], v[194:197], v[28:31]
	v_mfma_f32_16x16x32_bf16 v[24:27], v[168:171], v[194:197], v[24:27]
	v_mfma_f32_16x16x32_bf16 v[20:23], v[160:163], v[202:205], v[20:23]
	v_mfma_f32_16x16x32_bf16 v[16:19], v[168:171], v[202:205], v[16:19]
	v_mfma_f32_16x16x32_bf16 v[12:15], v[160:163], v[210:213], v[12:15]
	v_mfma_f32_16x16x32_bf16 v[8:11], v[168:171], v[210:213], v[8:11]
	v_mfma_f32_16x16x32_bf16 v[4:7], v[160:163], v[224:227], v[4:7]
	v_mfma_f32_16x16x32_bf16 v[0:3], v[168:171], v[224:227], v[0:3]
	v_mfma_f32_16x16x32_bf16 v[28:31], v[164:167], v[198:201], v[28:31]
	v_mfma_f32_16x16x32_bf16 v[24:27], v[190:193], v[198:201], v[24:27]
	v_mfma_f32_16x16x32_bf16 v[20:23], v[164:167], v[206:209], v[20:23]
	v_mfma_f32_16x16x32_bf16 v[16:19], v[190:193], v[206:209], v[16:19]
	v_mfma_f32_16x16x32_bf16 v[12:15], v[164:167], v[214:217], v[12:15]
	v_mfma_f32_16x16x32_bf16 v[8:11], v[190:193], v[214:217], v[8:11]
	v_mfma_f32_16x16x32_bf16 v[4:7], v[164:167], v[228:231], v[4:7]
	v_mfma_f32_16x16x32_bf16 v[0:3], v[190:193], v[228:231], v[0:3]
	s_barrier
	s_setprio 0
	s_add_u32 s0, s0, 0x100
	s_addc_u32 s1, s1, 0
	s_add_u32 s10, s10, 0x100
	s_addc_u32 s11, s11, 0
	s_cmp_ge_i32 s63, s52
	s_mov_b32 s8, s63
	s_cbranch_scc0 .LBB0_1389

.LBB0_1454:
	s_and_b64 vcc, exec, s[4:5]
	s_cbranch_vccnz .LBB0_1495
	v_bfe_i32 v2, v12, 27, 1
	v_lshlrev_b32_e32 v0, 4, v12
	v_lshrrev_b32_e32 v2, 22, v2
	v_add_u32_e32 v2, v0, v2
	v_and_b32_e32 v2, 0xfffffc00, v2
	v_sub_u32_e32 v2, v0, v2
	v_ashrrev_i32_e32 v1, 31, v12
	v_lshrrev_b32_e32 v3, 4, v2
	v_lshrrev_b32_e32 v1, 26, v1
	v_bitop3_b32 v2, v3, v2, 32 bitop3:0x6c
	v_add_u32_e32 v1, v12, v1
	v_ashrrev_i32_e32 v4, 31, v2
	v_ashrrev_i32_e32 v1, 6, v1
	v_lshrrev_b32_e32 v4, 26, v4
	v_lshlrev_b32_e32 v3, 3, v1
	v_add_u32_e32 v4, v2, v4
	v_and_b32_e32 v3, -16, v3
	v_ashrrev_i32_e32 v5, 6, v4
	v_lshlrev_b32_e32 v1, 5, v1
	v_add_u32_e32 v3, v5, v3
	v_and_b32_e32 v13, 32, v1
	v_and_b32_e32 v1, 0xc0, v4
	v_sub_u32_e32 v1, v2, v1
	v_mov_b32_e32 v2, 1
	v_lshlrev_b32_e32 v4, 1, v3
	v_lshrrev_b32_e32 v6, 2, v3
	v_and_b32_e32 v5, 3, v5
	s_mov_b32 s1, 0x7fffffe0
	v_ashrrev_i16_sdwa v1, v2, sext(v1) dst_sel:DWORD dst_unused:UNUSED_PAD src0_sel:DWORD src1_sel:BYTE_0
	v_and_b32_e32 v4, 24, v4
	v_and_b32_e32 v6, 4, v6
	v_and_or_b32 v5, v3, s1, v5
	v_bfe_i32 v14, v1, 0, 16
	v_or3_b32 v4, v5, v6, v4
	v_add_u32_e32 v1, v13, v14
	v_mul_lo_u32 v15, v3, s0
	v_mul_lo_u32 v3, v4, s0
	v_add_u32_e32 v0, 0x2000, v0
	v_lshrrev_b32_e32 v252, 3, v220
	v_bfe_u32 v253, v220, 4, 2
	v_bfe_u32 v254, v220, 6, 1
	v_lshl_or_b32 v253, v254, 2, v253
	v_and_b32_e32 v254, 7, v220
	v_xor_b32_e32 v253, v254, v253
	v_lshlrev_b32_e32 v253, 4, v253
	v_and_b32_e32 v254, 32, v252
	v_bfe_u32 v255, v252, 2, 2
	v_lshl_or_b32 v254, v255, 3, v254
	v_bfe_u32 v255, v252, 4, 1
	v_lshl_or_b32 v254, v255, 2, v254
	v_and_b32_e32 v255, 3, v252
	v_or_b32_e32 v254, v254, v255
	v_mul_u32_u24_e32 v254, 0x4000, v254
	v_add_u32_e32 v254, v254, v253
	v_add_u32_e32 v255, 0x100000, v254
	v_mul_u32_u24_e32 v252, 0x4000, v252
	v_add_u32_e32 v252, v252, v253
	v_add_u32_e32 v253, 0x100000, v252
	v_mov_b32_e32 v144, v252
	v_mov_b32_e32 v146, v254
	v_ashrrev_i32_e32 v1, 31, v0
	v_lshrrev_b32_e32 v1, 22, v1
	v_add_u32_e32 v1, v0, v1
	v_ashrrev_i32_e32 v1, 10, v1
	v_mul_i32_i24_e32 v3, 0x400, v1
	v_sub_u32_e32 v0, v0, v3
	v_lshrrev_b32_e32 v3, 4, v0
	v_bitop3_b32 v0, v3, v0, 32 bitop3:0x6c
	v_ashrrev_i32_e32 v4, 31, v0
	v_lshrrev_b32_e32 v4, 26, v4
	v_lshlrev_b32_e32 v3, 3, v1
	v_add_u32_e32 v4, v0, v4
	v_and_b32_e32 v3, -16, v3
	v_ashrrev_i32_e32 v5, 6, v4
	v_lshlrev_b32_e32 v1, 5, v1
	s_add_u32 s31, s74, 0x9b00000
	v_add_u32_e32 v3, v5, v3
	v_and_b32_e32 v16, 32, v1
	v_and_b32_e32 v1, 0xc0, v4
	v_and_b32_e32 v4, 3, v5
	s_addc_u32 s35, s75, 0
	v_and_or_b32 v4, v3, s1, v4
	s_ashr_i32 s1, s0, 31
	s_lshl_b64 s[10:11], s[0:1], 9
	s_ashr_i32 s6, s77, 31
	s_mul_i32 s6, s10, s6
	s_mul_hi_u32 s7, s10, s77
	s_add_i32 s12, s7, s6
	s_lshr_b64 s[6:7], s[0:1], 23
	s_mul_i32 s7, s6, s77
	s_add_i32 s12, s12, s7
	s_ashr_i32 s7, s76, 31
	s_mul_i32 s7, s10, s7
	s_mul_hi_u32 s14, s10, s76
	s_ashr_i32 s5, s28, 6
	s_add_i32 s7, s14, s7
	s_mul_i32 s6, s6, s76
	s_ashr_i32 s4, s28, 8
	v_sub_u32_e32 v0, v0, v1
	s_lshl_b64 s[8:9], s[0:1], 8
	s_lshl_b32 s44, s5, 10
	s_add_i32 s7, s7, s6
	s_mul_i32 s6, s10, s76
	v_ashrrev_i16_sdwa v0, v2, sext(v0) dst_sel:DWORD dst_unused:UNUSED_PAD src0_sel:DWORD src1_sel:BYTE_0
	v_lshlrev_b32_e32 v1, 1, v3
	v_lshrrev_b32_e32 v2, 2, v3
	s_add_u32 s40, s31, s6
	v_and_b32_e32 v1, 24, v1
	v_and_b32_e32 v2, 4, v2
	s_addc_u32 s41, s35, s7
	s_add_i32 s45, s44, 0
	v_bfe_i32 v17, v0, 0, 16
	v_or3_b32 v1, v4, v2, v1
	s_add_i32 m0, s45, 0x10000
	v_add_u32_e32 v0, v16, v17
	v_mul_lo_u32 v1, v1, s0
	global_load_lds_dwordx4 v146, s[40:41]
	s_add_i32 m0, s45, 0x12000
	v_mov_b32_e32 v150, v255
	s_add_u32 s6, s40, s8
	global_load_lds_dwordx4 v150, s[40:41]
	s_addc_u32 s7, s41, s9
	s_add_i32 m0, s45, 0x14000
	s_mul_i32 s13, s10, s77
	global_load_lds_dwordx4 v146, s[6:7]
	s_add_i32 m0, s45, 0x16000
	s_add_u32 s42, s50, s13
	s_addc_u32 s43, s51, s12
	s_add_i32 s47, s45, 0x2000
	v_mul_lo_u32 v18, v3, s0
	global_load_lds_dwordx4 v150, s[6:7]
	s_mov_b32 m0, s45
	s_add_u32 s12, s42, s8
	v_mov_b32_e32 v148, v253
	global_load_lds_dwordx4 v144, s[42:43]
	s_mov_b32 m0, s47
	s_addc_u32 s13, s43, s9
	s_add_i32 s48, s45, 0x4000
	global_load_lds_dwordx4 v148, s[42:43]
	s_mov_b32 m0, s48
	s_add_i32 s49, s45, 0x6000
	global_load_lds_dwordx4 v144, s[12:13]
	s_mov_b32 m0, s49
	v_mov_b32_e32 v147, 0
	global_load_lds_dwordx4 v148, s[12:13]
	v_mov_b32_e32 v151, v147
	v_mov_b32_e32 v145, v147
	v_mov_b32_e32 v149, v147
	s_cmp_eq_u32 s4, 1
	s_mov_b32 s52, 0
	v_lshl_add_u64 v[8:9], s[40:41], 0, v[146:147]
	v_lshl_add_u64 v[4:5], s[40:41], 0, v[150:151]
	v_lshl_add_u64 v[2:3], s[6:7], 0, v[146:147]
	v_lshl_add_u64 v[0:1], s[6:7], 0, v[150:151]
	v_lshl_add_u64 v[6:7], s[42:43], 0, v[144:145]
	s_cselect_b64 s[12:13], -1, 0
	s_cmp_lg_u32 s4, 1
	v_lshl_add_u64 v[10:11], s[42:43], 0, v[148:149]
	s_cbranch_scc1 .LBB0_1457
	s_barrier
.LBB0_1457:
	s_add_u32 s14, s64, 0x2000
	s_addc_u32 s15, s65, 0
	s_add_u32 s20, s66, 0x2000
	s_addc_u32 s21, s67, 0
	s_add_u32 s22, s74, 0x1fba0000
	s_mov_b64 s[24:25], 0x80
	s_addc_u32 s23, s75, 0
	s_add_i32 m0, s45, 0x18000
	v_lshl_add_u64 v[8:9], v[8:9], 0, s[24:25]
	s_waitcnt vmcnt(2)
	s_barrier
	global_load_lds_dwordx4 v[8:9], off
	v_lshl_add_u64 v[4:5], v[4:5], 0, s[24:25]
	s_add_i32 m0, s45, 0x1a000
	s_add_i32 s53, s45, 0x8000
	global_load_lds_dwordx4 v[4:5], off
	v_lshl_add_u64 v[4:5], v[6:7], 0, s[24:25]
	s_mov_b32 m0, s53
	s_add_i32 s54, s45, 0xa000
	global_load_lds_dwordx4 v[4:5], off
	v_lshl_add_u64 v[4:5], v[10:11], 0, s[24:25]
	s_mov_b32 m0, s54
	v_lshl_add_u64 v[2:3], v[2:3], 0, s[24:25]
	global_load_lds_dwordx4 v[4:5], off
	s_add_i32 m0, s45, 0x1c000
	v_lshl_add_u64 v[0:1], v[0:1], 0, s[24:25]
	global_load_lds_dwordx4 v[2:3], off
	s_add_i32 m0, s45, 0x1e000
	s_lshr_b32 s1, s1, 26
	global_load_lds_dwordx4 v[0:1], off
	v_bfe_u32 v0, v12, 4, 2
	v_and_b32_e32 v1, 15, v12
	v_lshlrev_b32_e32 v2, 4, v0
	s_add_i32 s1, s0, s1
	v_lshl_or_b32 v218, s4, 6, v1
	v_lshl_or_b32 v1, v1, 6, v2
	v_lshlrev_b32_e32 v2, 2, v12
	s_ashr_i32 s55, s1, 6
	s_lshl_b32 s1, s4, 13
	v_and_b32_e32 v2, 32, v2
	v_bitop3_b32 v3, v1, s1, v2 bitop3:0xde
	s_lshl_b32 s1, s5, 5
	s_and_b32 s1, s1, 0x60
	s_lshl_b32 s4, s1, 7
	v_and_b32_e32 v252, 15, v220
	v_bfe_u32 v253, v220, 4, 2
	v_bfe_u32 v254, v252, 1, 2
	v_xor_b32_e32 v253, v253, v254
	v_bfe_u32 v254, v252, 3, 1
	v_lshl_or_b32 v253, v254, 2, v253
	v_lshlrev_b32_e32 v253, 4, v253
	v_lshl_or_b32 v253, v252, 7, v253
	v_lshrrev_b32_e32 v254, 6, v220
	v_lshrrev_b32_e32 v255, 2, v254
	v_lshl_or_b32 v252, v255, 13, v253
	v_and_b32_e32 v254, 3, v254
	v_lshl_or_b32 v253, v254, 12, v253
	v_mov_b32_e32 v219, v253
	s_cmp_gt_i32 s0, 63
	v_cmp_eq_u32_e64 s[4:5], 0, v0
	v_lshl_or_b32 v223, v0, 3, s1
	v_add_u32_e32 v0, v15, v13
	s_cselect_b64 s[26:27], -1, 0
	s_add_i32 s56, s55, -2
	v_mov_b32_e32 v0, v144
	v_mov_b32_e32 v1, v147
	s_waitcnt vmcnt(6)
	s_cmpk_lt_u32 s28, 0x100
	v_lshl_add_u64 v[152:153], s[8:9], 0, v[0:1]
	v_add_u32_e32 v0, v18, v16
	s_cselect_b64 s[28:29], -1, 0
	v_readlane_b32 s6, v251, 1
	v_mov_b32_e32 v0, v148
	s_add_i32 s59, 0, 0x10000
	s_add_i32 s60, 0, 0x14000
	s_ashr_i32 s57, s6, 31
	s_mov_b32 s58, s6
	v_lshl_add_u64 v[154:155], s[8:9], 0, v[0:1]
	s_waitcnt vmcnt(0)
	v_mov_b64_e32 v[156:157], 0x200
	v_mov_b64_e32 v[158:159], 0x1ff
	v_add_u32_e32 v224, s59, v219
	v_add_u32_e32 v225, s60, v219
	v_mov_b32_e32 v226, v252
	v_xor_b32_e32 v252, 64, v226
	v_xor_b32_e32 v253, 64, v224
	v_xor_b32_e32 v254, 64, v225
	s_mov_b32 s30, 0x3a000000
	s_mov_b32 s61, 0xf800000
	v_mov_b32_e32 v227, 0x260
	s_mov_b32 s34, 0x3fb504f3
	s_barrier
	v_readlane_b32 s7, v251, 2
	s_branch .LBB0_1460

.LBB0_1472:
	ds_read_b128 v[128:131], v224
	ds_read_b128 v[132:135], v253
	ds_read_b128 v[136:139], v224 offset:2048
	ds_read_b128 v[140:143], v253 offset:2048
	ds_read_b128 v[160:163], v225
	ds_read_b128 v[164:167], v254
	ds_read_b128 v[168:171], v225 offset:2048
	ds_read_b128 v[172:175], v254 offset:2048
	s_add_i32 s64, s40, 2
	s_add_u32 s65, s0, 0x80
	s_addc_u32 s41, s1, 0
	s_cmp_eq_u32 s56, s40
	s_cselect_b32 s40, s36, s65
	s_cselect_b32 s41, s37, s41
	s_cselect_b32 s67, s39, s43
	s_cselect_b32 s66, s38, s42
	v_lshl_add_u64 v[208:209], s[0:1], 0, v[152:153]
	s_add_i32 m0, s45, 0xc000
	ds_read_b128 v[176:179], v226
	ds_read_b128 v[180:183], v252
	ds_read_b128 v[184:187], v226 offset:2048
	ds_read_b128 v[188:191], v252 offset:2048
	ds_read_b128 v[192:195], v226 offset:4096
	ds_read_b128 v[196:199], v252 offset:4096
	ds_read_b128 v[200:203], v226 offset:6144
	ds_read_b128 v[204:207], v252 offset:6144
	global_load_lds_dwordx4 v[208:209], off
	v_lshl_add_u64 v[208:209], s[0:1], 0, v[154:155]
	s_add_i32 m0, s45, 0xe000
	s_nop 0
	global_load_lds_dwordx4 v[208:209], off
	s_waitcnt vmcnt(8)
	s_waitcnt lgkmcnt(0)
	s_setprio 1
	s_barrier
	v_mfma_f32_16x16x32_bf16 v[124:127], v[128:131], v[176:179], v[124:127]
	v_mfma_f32_16x16x32_bf16 v[120:123], v[136:139], v[176:179], v[120:123]
	v_mfma_f32_16x16x32_bf16 v[116:119], v[128:131], v[184:187], v[116:119]
	v_mfma_f32_16x16x32_bf16 v[112:115], v[136:139], v[184:187], v[112:115]
	v_mfma_f32_16x16x32_bf16 v[108:111], v[128:131], v[192:195], v[108:111]
	v_mfma_f32_16x16x32_bf16 v[104:107], v[136:139], v[192:195], v[104:107]
	v_mfma_f32_16x16x32_bf16 v[100:103], v[128:131], v[200:203], v[100:103]
	v_mfma_f32_16x16x32_bf16 v[96:99], v[136:139], v[200:203], v[96:99]
	v_mfma_f32_16x16x32_bf16 v[124:127], v[132:135], v[180:183], v[124:127]
	v_mfma_f32_16x16x32_bf16 v[120:123], v[140:143], v[180:183], v[120:123]
	v_mfma_f32_16x16x32_bf16 v[116:119], v[132:135], v[188:191], v[116:119]
	v_mfma_f32_16x16x32_bf16 v[112:115], v[140:143], v[188:191], v[112:115]
	v_mfma_f32_16x16x32_bf16 v[108:111], v[132:135], v[196:199], v[108:111]
	v_mfma_f32_16x16x32_bf16 v[104:107], v[140:143], v[196:199], v[104:107]
	v_mfma_f32_16x16x32_bf16 v[100:103], v[132:135], v[204:207], v[100:103]
	v_mfma_f32_16x16x32_bf16 v[96:99], v[140:143], v[204:207], v[96:99]
	v_mfma_f32_16x16x32_bf16 v[60:63], v[160:163], v[176:179], v[60:63]
	v_mfma_f32_16x16x32_bf16 v[56:59], v[168:171], v[176:179], v[56:59]
	v_mfma_f32_16x16x32_bf16 v[52:55], v[160:163], v[184:187], v[52:55]
	v_mfma_f32_16x16x32_bf16 v[48:51], v[168:171], v[184:187], v[48:51]
	v_mfma_f32_16x16x32_bf16 v[44:47], v[160:163], v[192:195], v[44:47]
	v_mfma_f32_16x16x32_bf16 v[40:43], v[168:171], v[192:195], v[40:43]
	v_mfma_f32_16x16x32_bf16 v[36:39], v[160:163], v[200:203], v[36:39]
	v_mfma_f32_16x16x32_bf16 v[32:35], v[168:171], v[200:203], v[32:35]
	v_mfma_f32_16x16x32_bf16 v[60:63], v[164:167], v[180:183], v[60:63]
	v_mfma_f32_16x16x32_bf16 v[56:59], v[172:175], v[180:183], v[56:59]
	v_mfma_f32_16x16x32_bf16 v[52:55], v[164:167], v[188:191], v[52:55]
	v_mfma_f32_16x16x32_bf16 v[48:51], v[172:175], v[188:191], v[48:51]
	v_mfma_f32_16x16x32_bf16 v[44:47], v[164:167], v[196:199], v[44:47]
	v_mfma_f32_16x16x32_bf16 v[40:43], v[172:175], v[196:199], v[40:43]
	v_mfma_f32_16x16x32_bf16 v[36:39], v[164:167], v[204:207], v[36:39]
	v_mfma_f32_16x16x32_bf16 v[32:35], v[172:175], v[204:207], v[32:35]
	s_barrier
	s_setprio 0
	s_add_i32 s65, s59, s44
	v_lshl_add_u64 v[208:209], s[66:67], 0, v[146:147]
	s_mov_b32 m0, s65
	ds_read_b128 v[176:179], v226 offset:16384
	ds_read_b128 v[180:183], v252 offset:16384
	ds_read_b128 v[184:187], v226 offset:18432
	ds_read_b128 v[188:191], v252 offset:18432
	ds_read_b128 v[192:195], v226 offset:20480
	ds_read_b128 v[196:199], v252 offset:20480
	ds_read_b128 v[200:203], v226 offset:22528
	ds_read_b128 v[204:207], v252 offset:22528
	global_load_lds_dwordx4 v[208:209], off
	s_add_i32 m0, s65, 0x2000
	v_lshl_add_u64 v[210:211], s[66:67], 0, v[150:151]
	s_add_u32 s66, s66, s8
	s_addc_u32 s67, s67, s9
	s_add_i32 s65, s60, s44
	global_load_lds_dwordx4 v[210:211], off
	v_lshl_add_u64 v[212:213], s[66:67], 0, v[146:147]
	s_mov_b32 m0, s65
	v_lshl_add_u64 v[214:215], s[66:67], 0, v[150:151]
	global_load_lds_dwordx4 v[212:213], off
	s_add_i32 m0, s65, 0x2000
	v_lshl_add_u64 v[216:217], s[40:41], 0, v[144:145]
	global_load_lds_dwordx4 v[214:215], off
	s_mov_b32 m0, s45
	v_lshl_add_u64 v[228:229], s[40:41], 0, v[148:149]
	global_load_lds_dwordx4 v[216:217], off
	s_mov_b32 m0, s47
	s_nop 0
	global_load_lds_dwordx4 v[228:229], off
	s_waitcnt vmcnt(8)
	s_waitcnt lgkmcnt(0)
	s_setprio 1
	s_barrier
	v_mfma_f32_16x16x32_bf16 v[92:95], v[128:131], v[176:179], v[92:95]
	v_mfma_f32_16x16x32_bf16 v[88:91], v[136:139], v[176:179], v[88:91]
	v_mfma_f32_16x16x32_bf16 v[84:87], v[128:131], v[184:187], v[84:87]
	v_mfma_f32_16x16x32_bf16 v[80:83], v[136:139], v[184:187], v[80:83]
	v_mfma_f32_16x16x32_bf16 v[76:79], v[128:131], v[192:195], v[76:79]
	v_mfma_f32_16x16x32_bf16 v[72:75], v[136:139], v[192:195], v[72:75]
	v_mfma_f32_16x16x32_bf16 v[68:71], v[128:131], v[200:203], v[68:71]
	v_mfma_f32_16x16x32_bf16 v[64:67], v[136:139], v[200:203], v[64:67]
	v_mfma_f32_16x16x32_bf16 v[92:95], v[132:135], v[180:183], v[92:95]
	v_mfma_f32_16x16x32_bf16 v[88:91], v[140:143], v[180:183], v[88:91]
	v_mfma_f32_16x16x32_bf16 v[84:87], v[132:135], v[188:191], v[84:87]
	v_mfma_f32_16x16x32_bf16 v[80:83], v[140:143], v[188:191], v[80:83]
	v_mfma_f32_16x16x32_bf16 v[76:79], v[132:135], v[196:199], v[76:79]
	v_mfma_f32_16x16x32_bf16 v[72:75], v[140:143], v[196:199], v[72:75]
	v_mfma_f32_16x16x32_bf16 v[68:71], v[132:135], v[204:207], v[68:71]
	v_mfma_f32_16x16x32_bf16 v[64:67], v[140:143], v[204:207], v[64:67]
	v_mfma_f32_16x16x32_bf16 v[28:31], v[160:163], v[176:179], v[28:31]
	v_mfma_f32_16x16x32_bf16 v[24:27], v[168:171], v[176:179], v[24:27]
	v_mfma_f32_16x16x32_bf16 v[20:23], v[160:163], v[184:187], v[20:23]
	v_mfma_f32_16x16x32_bf16 v[16:19], v[168:171], v[184:187], v[16:19]
	v_mfma_f32_16x16x32_bf16 v[12:15], v[160:163], v[192:195], v[12:15]
	v_mfma_f32_16x16x32_bf16 v[8:11], v[168:171], v[192:195], v[8:11]
	v_mfma_f32_16x16x32_bf16 v[4:7], v[160:163], v[200:203], v[4:7]
	v_mfma_f32_16x16x32_bf16 v[0:3], v[168:171], v[200:203], v[0:3]
	v_mfma_f32_16x16x32_bf16 v[28:31], v[164:167], v[180:183], v[28:31]
	v_mfma_f32_16x16x32_bf16 v[24:27], v[172:175], v[180:183], v[24:27]
	v_mfma_f32_16x16x32_bf16 v[20:23], v[164:167], v[188:191], v[20:23]
	v_mfma_f32_16x16x32_bf16 v[16:19], v[172:175], v[188:191], v[16:19]
	v_mfma_f32_16x16x32_bf16 v[12:15], v[164:167], v[196:199], v[12:15]
	v_mfma_f32_16x16x32_bf16 v[8:11], v[172:175], v[196:199], v[8:11]
	v_mfma_f32_16x16x32_bf16 v[4:7], v[164:167], v[204:207], v[4:7]
	v_mfma_f32_16x16x32_bf16 v[0:3], v[172:175], v[204:207], v[0:3]
	s_barrier
	s_setprio 0
	s_add_i32 s65, 0, 0x18000
	s_add_i32 s66, 0, 0x1c000
	v_add_u32_e32 v140, s65, v219
	v_add_u32_e32 v172, s66, v219
	v_xor_b32_e32 v255, 64, v140
	ds_read_b128 v[128:131], v140
	ds_read_b128 v[132:135], v255
	ds_read_b128 v[136:139], v140 offset:2048
	ds_read_b128 v[140:143], v255 offset:2048
	v_xor_b32_e32 v255, 64, v172
	ds_read_b128 v[160:163], v172
	ds_read_b128 v[164:167], v255
	ds_read_b128 v[168:171], v172 offset:2048
	ds_read_b128 v[172:175], v255 offset:2048
	s_add_u32 s40, s40, s8
	s_addc_u32 s41, s41, s9
	s_mov_b32 m0, s48
	v_lshl_add_u64 v[230:231], s[40:41], 0, v[144:145]
	ds_read_b128 v[176:179], v226 offset:32768
	ds_read_b128 v[180:183], v252 offset:32768
	ds_read_b128 v[184:187], v226 offset:34816
	ds_read_b128 v[188:191], v252 offset:34816
	ds_read_b128 v[192:195], v226 offset:36864
	ds_read_b128 v[196:199], v252 offset:36864
	ds_read_b128 v[200:203], v226 offset:38912
	ds_read_b128 v[204:207], v252 offset:38912
	global_load_lds_dwordx4 v[230:231], off
	v_lshl_add_u64 v[230:231], s[40:41], 0, v[148:149]
	s_mov_b32 m0, s49
	s_nop 0
	global_load_lds_dwordx4 v[230:231], off
	s_waitcnt vmcnt(8)
	s_waitcnt lgkmcnt(0)
	s_setprio 1
	s_barrier
	v_mfma_f32_16x16x32_bf16 v[124:127], v[128:131], v[176:179], v[124:127]
	v_mfma_f32_16x16x32_bf16 v[120:123], v[136:139], v[176:179], v[120:123]
	v_mfma_f32_16x16x32_bf16 v[116:119], v[128:131], v[184:187], v[116:119]
	v_mfma_f32_16x16x32_bf16 v[112:115], v[136:139], v[184:187], v[112:115]
	v_mfma_f32_16x16x32_bf16 v[108:111], v[128:131], v[192:195], v[108:111]
	v_mfma_f32_16x16x32_bf16 v[104:107], v[136:139], v[192:195], v[104:107]
	v_mfma_f32_16x16x32_bf16 v[100:103], v[128:131], v[200:203], v[100:103]
	v_mfma_f32_16x16x32_bf16 v[96:99], v[136:139], v[200:203], v[96:99]
	v_mfma_f32_16x16x32_bf16 v[124:127], v[132:135], v[180:183], v[124:127]
	v_mfma_f32_16x16x32_bf16 v[120:123], v[140:143], v[180:183], v[120:123]
	v_mfma_f32_16x16x32_bf16 v[116:119], v[132:135], v[188:191], v[116:119]
	v_mfma_f32_16x16x32_bf16 v[112:115], v[140:143], v[188:191], v[112:115]
	v_mfma_f32_16x16x32_bf16 v[108:111], v[132:135], v[196:199], v[108:111]
	v_mfma_f32_16x16x32_bf16 v[104:107], v[140:143], v[196:199], v[104:107]
	v_mfma_f32_16x16x32_bf16 v[100:103], v[132:135], v[204:207], v[100:103]
	v_mfma_f32_16x16x32_bf16 v[96:99], v[140:143], v[204:207], v[96:99]
	v_mfma_f32_16x16x32_bf16 v[60:63], v[160:163], v[176:179], v[60:63]
	v_mfma_f32_16x16x32_bf16 v[56:59], v[168:171], v[176:179], v[56:59]
	v_mfma_f32_16x16x32_bf16 v[52:55], v[160:163], v[184:187], v[52:55]
	v_mfma_f32_16x16x32_bf16 v[48:51], v[168:171], v[184:187], v[48:51]
	v_mfma_f32_16x16x32_bf16 v[44:47], v[160:163], v[192:195], v[44:47]
	v_mfma_f32_16x16x32_bf16 v[40:43], v[168:171], v[192:195], v[40:43]
	v_mfma_f32_16x16x32_bf16 v[36:39], v[160:163], v[200:203], v[36:39]
	v_mfma_f32_16x16x32_bf16 v[32:35], v[168:171], v[200:203], v[32:35]
	v_mfma_f32_16x16x32_bf16 v[60:63], v[164:167], v[180:183], v[60:63]
	v_mfma_f32_16x16x32_bf16 v[56:59], v[172:175], v[180:183], v[56:59]
	v_mfma_f32_16x16x32_bf16 v[52:55], v[164:167], v[188:191], v[52:55]
	v_mfma_f32_16x16x32_bf16 v[48:51], v[172:175], v[188:191], v[48:51]
	v_mfma_f32_16x16x32_bf16 v[44:47], v[164:167], v[196:199], v[44:47]
	v_mfma_f32_16x16x32_bf16 v[40:43], v[172:175], v[196:199], v[40:43]
	v_mfma_f32_16x16x32_bf16 v[36:39], v[164:167], v[204:207], v[36:39]
	v_mfma_f32_16x16x32_bf16 v[32:35], v[172:175], v[204:207], v[32:35]
	s_barrier
	s_setprio 0
	s_add_i32 s40, s65, s44
	v_lshl_add_u64 v[208:209], v[208:209], 0, s[24:25]
	s_mov_b32 m0, s40
	ds_read_b128 v[176:179], v226 offset:49152
	ds_read_b128 v[180:183], v252 offset:49152
	ds_read_b128 v[184:187], v226 offset:51200
	ds_read_b128 v[188:191], v252 offset:51200
	ds_read_b128 v[192:195], v226 offset:53248
	ds_read_b128 v[196:199], v252 offset:53248
	ds_read_b128 v[200:203], v226 offset:55296
	ds_read_b128 v[204:207], v252 offset:55296
	global_load_lds_dwordx4 v[208:209], off
	v_lshl_add_u64 v[208:209], v[210:211], 0, s[24:25]
	s_add_i32 m0, s40, 0x2000
	s_add_i32 s40, s66, s44
	global_load_lds_dwordx4 v[208:209], off
	v_lshl_add_u64 v[208:209], v[212:213], 0, s[24:25]
	s_mov_b32 m0, s40
	s_nop 0
	global_load_lds_dwordx4 v[208:209], off
	v_lshl_add_u64 v[208:209], v[214:215], 0, s[24:25]
	s_add_i32 m0, s40, 0x2000
	s_nop 0
	global_load_lds_dwordx4 v[208:209], off
	v_lshl_add_u64 v[208:209], v[216:217], 0, s[24:25]
	s_mov_b32 m0, s53
	s_nop 0
	global_load_lds_dwordx4 v[208:209], off
	v_lshl_add_u64 v[208:209], v[228:229], 0, s[24:25]
	s_mov_b32 m0, s54
	s_nop 0
	global_load_lds_dwordx4 v[208:209], off
	s_waitcnt vmcnt(8)
	s_waitcnt lgkmcnt(0)
	s_setprio 1
	s_barrier
	v_mfma_f32_16x16x32_bf16 v[92:95], v[128:131], v[176:179], v[92:95]
	v_mfma_f32_16x16x32_bf16 v[88:91], v[136:139], v[176:179], v[88:91]
	v_mfma_f32_16x16x32_bf16 v[84:87], v[128:131], v[184:187], v[84:87]
	v_mfma_f32_16x16x32_bf16 v[80:83], v[136:139], v[184:187], v[80:83]
	v_mfma_f32_16x16x32_bf16 v[76:79], v[128:131], v[192:195], v[76:79]
	v_mfma_f32_16x16x32_bf16 v[72:75], v[136:139], v[192:195], v[72:75]
	v_mfma_f32_16x16x32_bf16 v[68:71], v[128:131], v[200:203], v[68:71]
	v_mfma_f32_16x16x32_bf16 v[64:67], v[136:139], v[200:203], v[64:67]
	v_mfma_f32_16x16x32_bf16 v[92:95], v[132:135], v[180:183], v[92:95]
	v_mfma_f32_16x16x32_bf16 v[88:91], v[140:143], v[180:183], v[88:91]
	v_mfma_f32_16x16x32_bf16 v[84:87], v[132:135], v[188:191], v[84:87]
	v_mfma_f32_16x16x32_bf16 v[80:83], v[140:143], v[188:191], v[80:83]
	v_mfma_f32_16x16x32_bf16 v[76:79], v[132:135], v[196:199], v[76:79]
	v_mfma_f32_16x16x32_bf16 v[72:75], v[140:143], v[196:199], v[72:75]
	v_mfma_f32_16x16x32_bf16 v[68:71], v[132:135], v[204:207], v[68:71]
	v_mfma_f32_16x16x32_bf16 v[64:67], v[140:143], v[204:207], v[64:67]
	v_mfma_f32_16x16x32_bf16 v[28:31], v[160:163], v[176:179], v[28:31]
	v_mfma_f32_16x16x32_bf16 v[24:27], v[168:171], v[176:179], v[24:27]
	v_mfma_f32_16x16x32_bf16 v[20:23], v[160:163], v[184:187], v[20:23]
	v_mfma_f32_16x16x32_bf16 v[16:19], v[168:171], v[184:187], v[16:19]
	v_mfma_f32_16x16x32_bf16 v[12:15], v[160:163], v[192:195], v[12:15]
	v_mfma_f32_16x16x32_bf16 v[8:11], v[168:171], v[192:195], v[8:11]
	v_mfma_f32_16x16x32_bf16 v[4:7], v[160:163], v[200:203], v[4:7]
	v_mfma_f32_16x16x32_bf16 v[0:3], v[168:171], v[200:203], v[0:3]
	v_mfma_f32_16x16x32_bf16 v[28:31], v[164:167], v[180:183], v[28:31]
	v_mfma_f32_16x16x32_bf16 v[24:27], v[172:175], v[180:183], v[24:27]
	v_mfma_f32_16x16x32_bf16 v[20:23], v[164:167], v[188:191], v[20:23]
	v_mfma_f32_16x16x32_bf16 v[16:19], v[172:175], v[188:191], v[16:19]
	v_mfma_f32_16x16x32_bf16 v[12:15], v[164:167], v[196:199], v[12:15]
	v_mfma_f32_16x16x32_bf16 v[8:11], v[172:175], v[196:199], v[8:11]
	v_mfma_f32_16x16x32_bf16 v[4:7], v[164:167], v[204:207], v[4:7]
	v_mfma_f32_16x16x32_bf16 v[0:3], v[172:175], v[204:207], v[0:3]
	s_barrier
	s_setprio 0
	s_add_u32 s0, s0, 0x100
	s_addc_u32 s1, s1, 0
	s_add_u32 s42, s42, 0x100
	s_addc_u32 s43, s43, 0
	s_cmp_ge_i32 s64, s55
	s_mov_b32 s40, s64
	s_cbranch_scc0 .LBB0_1472
